# v29 with the staging write/load pairs placed later in the k-iteration (0.10..0.92 of the MFMA slots)
# speedup vs baseline: 1.0027x; 1.0027x over previous
; DI f32x4 mfma16(bf16x8 a, bf16x8 b, f32x4 c) { return __builtin_amdgcn_mfma_f32_16x16x32_bf16(a, b, c, 0, 0, 0); }
; template <int MI, int NJ, bool SWAP, class AP, class BP>
; DI void gemm_main(f32x4 (&acc)[MI][NJ], const AP& ap, int a_kstep, const BP& bp, int b_kstep, int nk, bf16_t* smem) {
;     ...
;   auto gload = [&](int kt) {
;     const bf16_t* ab = ap.base + (size_t)kt * a_kstep; const bf16_t* bb = bp.base + (size_t)kt * b_kstep;
; #pragma unroll
;     for (int i = 0; i < CA; ++i) ra[i] = *(const u32x4*)(ab + pa[i]);
; #pragma unroll
;     for (int i = 0; i < CB; ++i) rb[i] = *(const u32x4*)(bb + pb[i]);
;   };
;   auto sstore = [&](int buf) {
;     bf16_t* As = smem + buf * L::STAGE; bf16_t* Bs = As + L::A_ELEMS;
; #pragma unroll
;     for (int i = 0; i < CA; ++i) { const int c = tid + NTHR * i; *(u32x4*)(As + (c >> 3) * LDT + (c & 7) * 8) = oka[i] ? ra[i] : (u32x4){0u, 0u, 0u, 0u}; }
; #pragma unroll
;     for (int i = 0; i < CB; ++i) { const int c = tid + NTHR * i; *(u32x4*)(Bs + (c >> 3) * LDT + (c & 7) * 8) = rb[i]; }
;     ...
;   for (int kt = 0; kt < nk; ++kt) {
;     const int buf = kt & 1;
;     sstore(buf ^ 1);
;     gload(kt + 2 < nk ? kt + 2 : nk - 1);
;     __builtin_amdgcn_sched_barrier(0);
;     const bf16_t* As = smem + buf * L::STAGE + (wm * 16 * MI + l15) * LDT + quad * 8;
;     const bf16_t* Bs = smem + buf * L::STAGE + L::A_ELEMS + (wn * 16 * NJ + l15) * LDT + quad * 8;
; #pragma unroll
;     for (int ks = 0; ks < 2; ++ks) {
;       if (MI * NJ >= 32 && ks == 1) asm volatile("" ::: "memory");
;       bf16x8 b[NJ];
; #pragma unroll
;       for (int j = 0; j < NJ; ++j) b[j] = *(const bf16x8*)(Bs + j * 16 * LDT + ks * 32);
; #pragma unroll
;       for (int i = 0; i < MI; ++i) {
;         const bf16x8 a = *(const bf16x8*)(As + i * 16 * LDT + ks * 32);
; #pragma unroll
;         for (int j = 0; j < NJ; ++j) acc[i][j] = SWAP ? mfma16(b[j], a, acc[i][j]) : mfma16(a, b[j], acc[i][j]);
;       }
;     }
.Lgm0_main:
	ds_read_b128 v[242:245], v176 offset:4608
	s_waitcnt lgkmcnt(4)
	v_mfma_f32_16x16x32_bf16 v[124:127], v[178:181], v[212:215], v[124:127]
	s_waitcnt lgkmcnt(3)
	v_mfma_f32_16x16x32_bf16 v[120:123], v[200:203], v[212:215], v[120:123]
	s_waitcnt lgkmcnt(2)
	v_mfma_f32_16x16x32_bf16 v[116:119], v[204:207], v[212:215], v[116:119]
	s_waitcnt lgkmcnt(1)
	v_mfma_f32_16x16x32_bf16 v[112:115], v[208:211], v[212:215], v[112:115]
	ds_read_b128 v[246:249], v176 offset:6912
	v_mfma_f32_16x16x32_bf16 v[108:111], v[178:181], v[216:219], v[108:111]
	v_mfma_f32_16x16x32_bf16 v[104:107], v[200:203], v[216:219], v[104:107]
	s_and_b32 s5, s4, 1
	s_min_u32 s6, s4, 13
	s_xor_b32 s7, s5, 1
	s_mul_i32 s7, s7, 0x12000
	v_add3_u32 v250, s7, v171, v169
	s_waitcnt vmcnt(7)
	ds_write_b128 v250, v[128:131]
	v_mfma_f32_16x16x32_bf16 v[100:103], v[204:207], v[216:219], v[100:103]
	v_mfma_f32_16x16x32_bf16 v[96:99], v[208:211], v[216:219], v[96:99]
	s_lshl_b32 s33, s6, 7
	s_add_u32 s6, s0, s33
	v_add3_u32 v251, s7, v173, v169
	v_add3_u32 v252, s7, v174, v169
	v_add3_u32 v253, s7, v175, v169
	s_addc_u32 s7, s1, 0
	v_lshl_add_u64 v[128:129], s[6:7], 0, v[160:161]
	s_nop 0
	global_load_dwordx4 v[128:131], v[128:129], off offset:256
	ds_read_b128 v[212:215], v176 offset:9216
	s_waitcnt lgkmcnt(3)
	v_mfma_f32_16x16x32_bf16 v[92:95], v[178:181], v[242:245], v[92:95]
	v_mfma_f32_16x16x32_bf16 v[88:91], v[200:203], v[242:245], v[88:91]
	v_mfma_f32_16x16x32_bf16 v[84:87], v[204:207], v[242:245], v[84:87]
	v_mfma_f32_16x16x32_bf16 v[80:83], v[208:211], v[242:245], v[80:83]
	s_waitcnt vmcnt(7)
	ds_write_b128 v251, v[132:135]
	ds_read_b128 v[216:219], v176 offset:11520
	s_waitcnt lgkmcnt(4)
	v_mfma_f32_16x16x32_bf16 v[76:79], v[178:181], v[246:249], v[76:79]
	v_mfma_f32_16x16x32_bf16 v[72:75], v[200:203], v[246:249], v[72:75]
	v_lshl_add_u64 v[132:133], s[6:7], 0, v[162:163]
	s_nop 0
	global_load_dwordx4 v[132:135], v[132:133], off offset:256
	v_mfma_f32_16x16x32_bf16 v[68:71], v[204:207], v[246:249], v[68:71]
	v_mfma_f32_16x16x32_bf16 v[64:67], v[208:211], v[246:249], v[64:67]
	ds_read_b128 v[242:245], v176 offset:13824
	s_waitcnt lgkmcnt(3)
	v_mfma_f32_16x16x32_bf16 v[60:63], v[178:181], v[212:215], v[60:63]
	v_mfma_f32_16x16x32_bf16 v[56:59], v[200:203], v[212:215], v[56:59]
	v_mfma_f32_16x16x32_bf16 v[52:55], v[204:207], v[212:215], v[52:55]
	s_waitcnt vmcnt(7)
	ds_write_b128 v252, v[136:139]
	v_mfma_f32_16x16x32_bf16 v[48:51], v[208:211], v[212:215], v[48:51]
	ds_read_b128 v[246:249], v176 offset:16128
	s_waitcnt lgkmcnt(3)
	v_mfma_f32_16x16x32_bf16 v[44:47], v[178:181], v[216:219], v[44:47]
	v_lshl_add_u64 v[136:137], s[6:7], 0, v[164:165]
	s_nop 0
	global_load_dwordx4 v[136:139], v[136:137], off offset:256
	v_mfma_f32_16x16x32_bf16 v[40:43], v[200:203], v[216:219], v[40:43]
	v_mfma_f32_16x16x32_bf16 v[36:39], v[204:207], v[216:219], v[36:39]
	v_mfma_f32_16x16x32_bf16 v[32:35], v[208:211], v[216:219], v[32:35]
	ds_read_b128 v[212:215], v176 offset:64
	s_waitcnt lgkmcnt(3)
	v_mfma_f32_16x16x32_bf16 v[28:31], v[178:181], v[242:245], v[28:31]
	s_waitcnt vmcnt(7)
	ds_write_b128 v253, v[140:143]
	v_mfma_f32_16x16x32_bf16 v[24:27], v[200:203], v[242:245], v[24:27]
	v_mfma_f32_16x16x32_bf16 v[20:23], v[204:207], v[242:245], v[20:23]
	v_lshl_add_u64 v[140:141], s[6:7], 0, v[166:167]
	s_nop 0
	global_load_dwordx4 v[140:143], v[140:141], off offset:256
	v_mfma_f32_16x16x32_bf16 v[16:19], v[208:211], v[242:245], v[16:19]
	ds_read_b128 v[216:219], v176 offset:2368
	s_waitcnt lgkmcnt(3)
	v_mfma_f32_16x16x32_bf16 v[12:15], v[178:181], v[246:249], v[12:15]
	ds_read_b128 v[178:181], v182 offset:36928
	v_mfma_f32_16x16x32_bf16 v[8:11], v[200:203], v[246:249], v[8:11]
	ds_read_b128 v[200:203], v182 offset:39232
	v_mfma_f32_16x16x32_bf16 v[0:3], v[204:207], v[246:249], v[0:3]
	ds_read_b128 v[204:207], v182 offset:41536
	v_mfma_f32_16x16x32_bf16 v[4:7], v[208:211], v[246:249], v[4:7]
	ds_read_b128 v[208:211], v182 offset:43840
	s_waitcnt vmcnt(7)
	ds_write_b128 v250, v[144:147] offset:36864
	ds_read_b128 v[242:245], v176 offset:4672
	s_waitcnt lgkmcnt(5)
	v_mfma_f32_16x16x32_bf16 v[124:127], v[178:181], v[212:215], v[124:127]
	s_waitcnt lgkmcnt(4)
	v_mfma_f32_16x16x32_bf16 v[120:123], v[200:203], v[212:215], v[120:123]
	s_add_u32 s6, s2, s33
	s_addc_u32 s7, s3, 0
	v_lshl_add_u64 v[144:145], s[6:7], 0, v[160:161]
	s_nop 0
	global_load_dwordx4 v[144:147], v[144:145], off offset:256
	s_waitcnt lgkmcnt(3)
	v_mfma_f32_16x16x32_bf16 v[116:119], v[204:207], v[212:215], v[116:119]
	s_waitcnt lgkmcnt(2)
	v_mfma_f32_16x16x32_bf16 v[112:115], v[208:211], v[212:215], v[112:115]
	ds_read_b128 v[246:249], v176 offset:6976
	v_mfma_f32_16x16x32_bf16 v[108:111], v[178:181], v[216:219], v[108:111]
	v_mfma_f32_16x16x32_bf16 v[104:107], v[200:203], v[216:219], v[104:107]
	s_waitcnt vmcnt(7)
	ds_write_b128 v251, v[148:151] offset:36864
	v_mfma_f32_16x16x32_bf16 v[100:103], v[204:207], v[216:219], v[100:103]
	v_mfma_f32_16x16x32_bf16 v[96:99], v[208:211], v[216:219], v[96:99]
	v_lshl_add_u64 v[148:149], s[6:7], 0, v[162:163]
	s_nop 0
	global_load_dwordx4 v[148:151], v[148:149], off offset:256
	ds_read_b128 v[212:215], v176 offset:9280
	s_waitcnt lgkmcnt(3)
	v_mfma_f32_16x16x32_bf16 v[92:95], v[178:181], v[242:245], v[92:95]
	v_mfma_f32_16x16x32_bf16 v[88:91], v[200:203], v[242:245], v[88:91]
	v_mfma_f32_16x16x32_bf16 v[84:87], v[204:207], v[242:245], v[84:87]
	v_mfma_f32_16x16x32_bf16 v[80:83], v[208:211], v[242:245], v[80:83]
	ds_read_b128 v[216:219], v176 offset:11584
	s_waitcnt lgkmcnt(3)
	v_mfma_f32_16x16x32_bf16 v[76:79], v[178:181], v[246:249], v[76:79]
	s_waitcnt vmcnt(7)
	ds_write_b128 v252, v[152:155] offset:36864
	v_mfma_f32_16x16x32_bf16 v[72:75], v[200:203], v[246:249], v[72:75]
	v_mfma_f32_16x16x32_bf16 v[68:71], v[204:207], v[246:249], v[68:71]
	v_lshl_add_u64 v[152:153], s[6:7], 0, v[164:165]
	s_nop 0
	global_load_dwordx4 v[152:155], v[152:153], off offset:256
	v_mfma_f32_16x16x32_bf16 v[64:67], v[208:211], v[246:249], v[64:67]
	ds_read_b128 v[242:245], v176 offset:13888
	s_waitcnt lgkmcnt(3)
	v_mfma_f32_16x16x32_bf16 v[60:63], v[178:181], v[212:215], v[60:63]
	v_mfma_f32_16x16x32_bf16 v[56:59], v[200:203], v[212:215], v[56:59]
	v_mfma_f32_16x16x32_bf16 v[52:55], v[204:207], v[212:215], v[52:55]
	v_mfma_f32_16x16x32_bf16 v[48:51], v[208:211], v[212:215], v[48:51]
	s_waitcnt vmcnt(7)
	ds_write_b128 v253, v[156:159] offset:36864
	ds_read_b128 v[246:249], v176 offset:16192
	s_waitcnt lgkmcnt(4)
	v_mfma_f32_16x16x32_bf16 v[44:47], v[178:181], v[216:219], v[44:47]
	v_mfma_f32_16x16x32_bf16 v[40:43], v[200:203], v[216:219], v[40:43]
	v_lshl_add_u64 v[156:157], s[6:7], 0, v[166:167]
	s_nop 0
	global_load_dwordx4 v[156:159], v[156:157], off offset:256
	v_mfma_f32_16x16x32_bf16 v[36:39], v[204:207], v[216:219], v[36:39]
	v_mfma_f32_16x16x32_bf16 v[32:35], v[208:211], v[216:219], v[32:35]
	s_add_i32 s4, s4, 1
	s_and_b32 s98, s4, 1
	s_mul_i32 s98, s98, 0x12000
	v_add3_u32 v182, s98, v168, v172
	v_add3_u32 v176, s98, v170, v172
	s_cmp_lg_u32 s4, 16
	s_waitcnt lgkmcnt(0)
	s_barrier
; DI f32x4 mfma16(bf16x8 a, bf16x8 b, f32x4 c) { return __builtin_amdgcn_mfma_f32_16x16x32_bf16(a, b, c, 0, 0, 0); }
; template <int MI, int NJ, bool SWAP, class AP, class BP>
; DI void gemm_main(f32x4 (&acc)[MI][NJ], const AP& ap, int a_kstep, const BP& bp, int b_kstep, int nk, bf16_t* smem) {
;     ...
;   for (int kt = 0; kt < nk; ++kt) {
;     const int buf = kt & 1;
;     sstore(buf ^ 1);
;     gload(kt + 2 < nk ? kt + 2 : nk - 1);
;     __builtin_amdgcn_sched_barrier(0);
;     const bf16_t* As = smem + buf * L::STAGE + (wm * 16 * MI + l15) * LDT + quad * 8;
;     const bf16_t* Bs = smem + buf * L::STAGE + L::A_ELEMS + (wn * 16 * NJ + l15) * LDT + quad * 8;
; #pragma unroll
;     for (int ks = 0; ks < 2; ++ks) {
;       if (MI * NJ >= 32 && ks == 1) asm volatile("" ::: "memory");
;       bf16x8 b[NJ];
; #pragma unroll
;       for (int j = 0; j < NJ; ++j) b[j] = *(const bf16x8*)(Bs + j * 16 * LDT + ks * 32);
; #pragma unroll
;       for (int i = 0; i < MI; ++i) {
;         const bf16x8 a = *(const bf16x8*)(As + i * 16 * LDT + ks * 32);
; #pragma unroll
;         for (int j = 0; j < NJ; ++j) acc[i][j] = SWAP ? mfma16(b[j], a, acc[i][j]) : mfma16(a, b[j], acc[i][j]);
;       }
;     }
;     __syncthreads();
;   }
	s_cbranch_scc0 .Lgm0_exit
	ds_read_b128 v[212:215], v176
	ds_read_b128 v[216:219], v176 offset:2304
	v_mfma_f32_16x16x32_bf16 v[28:31], v[178:181], v[242:245], v[28:31]
	v_mfma_f32_16x16x32_bf16 v[12:15], v[178:181], v[246:249], v[12:15]
	ds_read_b128 v[178:181], v182 offset:36864
	v_mfma_f32_16x16x32_bf16 v[24:27], v[200:203], v[242:245], v[24:27]
	v_mfma_f32_16x16x32_bf16 v[8:11], v[200:203], v[246:249], v[8:11]
	ds_read_b128 v[200:203], v182 offset:39168
	v_mfma_f32_16x16x32_bf16 v[20:23], v[204:207], v[242:245], v[20:23]
	v_mfma_f32_16x16x32_bf16 v[0:3], v[204:207], v[246:249], v[0:3]
	ds_read_b128 v[204:207], v182 offset:41472
	v_mfma_f32_16x16x32_bf16 v[16:19], v[208:211], v[242:245], v[16:19]
	v_mfma_f32_16x16x32_bf16 v[4:7], v[208:211], v[246:249], v[4:7]
	ds_read_b128 v[208:211], v182 offset:43776
	s_branch .Lgm0_main

; DI f32x4 mfma16(bf16x8 a, bf16x8 b, f32x4 c) { return __builtin_amdgcn_mfma_f32_16x16x32_bf16(a, b, c, 0, 0, 0); }
; template <int MI, int NJ, bool SWAP, class AP, class BP>
; DI void gemm_main(f32x4 (&acc)[MI][NJ], const AP& ap, int a_kstep, const BP& bp, int b_kstep, int nk, bf16_t* smem) {
;     ...
;   auto gload = [&](int kt) {
;     const bf16_t* ab = ap.base + (size_t)kt * a_kstep; const bf16_t* bb = bp.base + (size_t)kt * b_kstep;
; #pragma unroll
;     for (int i = 0; i < CA; ++i) ra[i] = *(const u32x4*)(ab + pa[i]);
; #pragma unroll
;     for (int i = 0; i < CB; ++i) rb[i] = *(const u32x4*)(bb + pb[i]);
;   };
;   auto sstore = [&](int buf) {
;     bf16_t* As = smem + buf * L::STAGE; bf16_t* Bs = As + L::A_ELEMS;
; #pragma unroll
;     for (int i = 0; i < CA; ++i) { const int c = tid + NTHR * i; *(u32x4*)(As + (c >> 3) * LDT + (c & 7) * 8) = oka[i] ? ra[i] : (u32x4){0u, 0u, 0u, 0u}; }
; #pragma unroll
;     for (int i = 0; i < CB; ++i) { const int c = tid + NTHR * i; *(u32x4*)(Bs + (c >> 3) * LDT + (c & 7) * 8) = rb[i]; }
;     ...
;   for (int kt = 0; kt < nk; ++kt) {
;     const int buf = kt & 1;
;     sstore(buf ^ 1);
;     gload(kt + 2 < nk ? kt + 2 : nk - 1);
;     __builtin_amdgcn_sched_barrier(0);
;     const bf16_t* As = smem + buf * L::STAGE + (wm * 16 * MI + l15) * LDT + quad * 8;
;     const bf16_t* Bs = smem + buf * L::STAGE + L::A_ELEMS + (wn * 16 * NJ + l15) * LDT + quad * 8;
; #pragma unroll
;     for (int ks = 0; ks < 2; ++ks) {
;       if (MI * NJ >= 32 && ks == 1) asm volatile("" ::: "memory");
;       bf16x8 b[NJ];
; #pragma unroll
;       for (int j = 0; j < NJ; ++j) b[j] = *(const bf16x8*)(Bs + j * 16 * LDT + ks * 32);
; #pragma unroll
;       for (int i = 0; i < MI; ++i) {
;         const bf16x8 a = *(const bf16x8*)(As + i * 16 * LDT + ks * 32);
; #pragma unroll
;         for (int j = 0; j < NJ; ++j) acc[i][j] = SWAP ? mfma16(b[j], a, acc[i][j]) : mfma16(a, b[j], acc[i][j]);
;       }
;     }
.Lgm1_main:
	ds_read_b128 v[242:245], v176 offset:4608
	s_waitcnt lgkmcnt(4)
	v_mfma_f32_16x16x32_bf16 v[124:127], v[212:215], v[178:181], v[124:127]
	s_waitcnt lgkmcnt(3)
	v_mfma_f32_16x16x32_bf16 v[120:123], v[212:215], v[200:203], v[120:123]
	s_waitcnt lgkmcnt(2)
	v_mfma_f32_16x16x32_bf16 v[116:119], v[212:215], v[204:207], v[116:119]
	s_waitcnt lgkmcnt(1)
	v_mfma_f32_16x16x32_bf16 v[112:115], v[212:215], v[208:211], v[112:115]
	ds_read_b128 v[246:249], v176 offset:6912
	v_mfma_f32_16x16x32_bf16 v[108:111], v[216:219], v[178:181], v[108:111]
	v_mfma_f32_16x16x32_bf16 v[104:107], v[216:219], v[200:203], v[104:107]
	v_lshlrev_b32_e32 v250, 1, v168
	s_and_b32 s5, s4, 1
	s_min_u32 s6, s4, 13
	s_xor_b32 s7, s5, 1
	s_mul_i32 s7, s7, 0x12000
	v_add3_u32 v250, s7, v250, v170
	s_waitcnt vmcnt(7)
	ds_write_b128 v250, v[128:131]
	v_mfma_f32_16x16x32_bf16 v[100:103], v[216:219], v[204:207], v[100:103]
	v_mfma_f32_16x16x32_bf16 v[96:99], v[216:219], v[208:211], v[96:99]
	s_lshl_b32 s33, s6, 7
	s_add_u32 s6, s0, s33
	v_lshlrev_b32_e32 v251, 1, v171
	v_add3_u32 v251, s7, v251, v170
	v_lshlrev_b32_e32 v252, 1, v172
	v_add3_u32 v252, s7, v252, v170
	v_lshlrev_b32_e32 v253, 1, v173
	v_add3_u32 v253, s7, v253, v170
	s_addc_u32 s7, s1, 0
	v_lshl_add_u64 v[128:129], s[6:7], 0, v[160:161]
	s_nop 0
	global_load_dwordx4 v[128:131], v[128:129], off offset:256
	ds_read_b128 v[212:215], v176 offset:9216
	s_waitcnt lgkmcnt(3)
	v_mfma_f32_16x16x32_bf16 v[92:95], v[242:245], v[178:181], v[92:95]
	v_mfma_f32_16x16x32_bf16 v[88:91], v[242:245], v[200:203], v[88:91]
	v_mfma_f32_16x16x32_bf16 v[84:87], v[242:245], v[204:207], v[84:87]
	v_mfma_f32_16x16x32_bf16 v[80:83], v[242:245], v[208:211], v[80:83]
	s_waitcnt vmcnt(7)
	ds_write_b128 v251, v[132:135]
	ds_read_b128 v[216:219], v176 offset:11520
	s_waitcnt lgkmcnt(4)
	v_mfma_f32_16x16x32_bf16 v[76:79], v[246:249], v[178:181], v[76:79]
	v_mfma_f32_16x16x32_bf16 v[72:75], v[246:249], v[200:203], v[72:75]
	v_lshl_add_u64 v[132:133], s[6:7], 0, v[162:163]
	s_nop 0
	global_load_dwordx4 v[132:135], v[132:133], off offset:256
	v_mfma_f32_16x16x32_bf16 v[68:71], v[246:249], v[204:207], v[68:71]
	v_mfma_f32_16x16x32_bf16 v[64:67], v[246:249], v[208:211], v[64:67]
	ds_read_b128 v[242:245], v176 offset:13824
	s_waitcnt lgkmcnt(3)
	v_mfma_f32_16x16x32_bf16 v[60:63], v[212:215], v[178:181], v[60:63]
	v_mfma_f32_16x16x32_bf16 v[56:59], v[212:215], v[200:203], v[56:59]
	v_mfma_f32_16x16x32_bf16 v[52:55], v[212:215], v[204:207], v[52:55]
	s_waitcnt vmcnt(7)
	ds_write_b128 v252, v[136:139]
	v_mfma_f32_16x16x32_bf16 v[48:51], v[212:215], v[208:211], v[48:51]
	ds_read_b128 v[246:249], v176 offset:16128
	s_waitcnt lgkmcnt(3)
	v_mfma_f32_16x16x32_bf16 v[44:47], v[216:219], v[178:181], v[44:47]
	v_lshl_add_u64 v[136:137], s[6:7], 0, v[164:165]
	s_nop 0
	global_load_dwordx4 v[136:139], v[136:137], off offset:256
	v_mfma_f32_16x16x32_bf16 v[40:43], v[216:219], v[200:203], v[40:43]
	v_mfma_f32_16x16x32_bf16 v[36:39], v[216:219], v[204:207], v[36:39]
	v_mfma_f32_16x16x32_bf16 v[32:35], v[216:219], v[208:211], v[32:35]
	ds_read_b128 v[212:215], v176 offset:64
	s_waitcnt lgkmcnt(3)
	v_mfma_f32_16x16x32_bf16 v[28:31], v[242:245], v[178:181], v[28:31]
	s_waitcnt vmcnt(7)
	ds_write_b128 v253, v[140:143]
	v_mfma_f32_16x16x32_bf16 v[24:27], v[242:245], v[200:203], v[24:27]
	v_mfma_f32_16x16x32_bf16 v[20:23], v[242:245], v[204:207], v[20:23]
	v_lshl_add_u64 v[140:141], s[6:7], 0, v[166:167]
	s_nop 0
	global_load_dwordx4 v[140:143], v[140:141], off offset:256
	v_mfma_f32_16x16x32_bf16 v[16:19], v[242:245], v[208:211], v[16:19]
	ds_read_b128 v[216:219], v176 offset:2368
	s_waitcnt lgkmcnt(3)
	v_mfma_f32_16x16x32_bf16 v[8:11], v[246:249], v[178:181], v[8:11]
	ds_read_b128 v[178:181], v182 offset:36928
	v_mfma_f32_16x16x32_bf16 v[4:7], v[246:249], v[200:203], v[4:7]
	ds_read_b128 v[200:203], v182 offset:39232
	v_mfma_f32_16x16x32_bf16 v[0:3], v[246:249], v[204:207], v[0:3]
	ds_read_b128 v[204:207], v182 offset:41536
	v_mfma_f32_16x16x32_bf16 v[12:15], v[246:249], v[208:211], v[12:15]
	ds_read_b128 v[208:211], v182 offset:43840
	s_waitcnt vmcnt(7)
; DI f32x4 mfma16(bf16x8 a, bf16x8 b, f32x4 c) { return __builtin_amdgcn_mfma_f32_16x16x32_bf16(a, b, c, 0, 0, 0); }
; template <int MI, int NJ, bool SWAP, class AP, class BP>
; DI void gemm_main(f32x4 (&acc)[MI][NJ], const AP& ap, int a_kstep, const BP& bp, int b_kstep, int nk, bf16_t* smem) {
;     ...
;   auto gload = [&](int kt) {
;     const bf16_t* ab = ap.base + (size_t)kt * a_kstep; const bf16_t* bb = bp.base + (size_t)kt * b_kstep;
; #pragma unroll
;     for (int i = 0; i < CA; ++i) ra[i] = *(const u32x4*)(ab + pa[i]);
; #pragma unroll
;     for (int i = 0; i < CB; ++i) rb[i] = *(const u32x4*)(bb + pb[i]);
;   };
;   auto sstore = [&](int buf) {
;     bf16_t* As = smem + buf * L::STAGE; bf16_t* Bs = As + L::A_ELEMS;
; #pragma unroll
;     for (int i = 0; i < CA; ++i) { const int c = tid + NTHR * i; *(u32x4*)(As + (c >> 3) * LDT + (c & 7) * 8) = oka[i] ? ra[i] : (u32x4){0u, 0u, 0u, 0u}; }
; #pragma unroll
;     for (int i = 0; i < CB; ++i) { const int c = tid + NTHR * i; *(u32x4*)(Bs + (c >> 3) * LDT + (c & 7) * 8) = rb[i]; }
;     ...
;   for (int kt = 0; kt < nk; ++kt) {
;     const int buf = kt & 1;
;     sstore(buf ^ 1);
;     gload(kt + 2 < nk ? kt + 2 : nk - 1);
;     __builtin_amdgcn_sched_barrier(0);
;     const bf16_t* As = smem + buf * L::STAGE + (wm * 16 * MI + l15) * LDT + quad * 8;
;     const bf16_t* Bs = smem + buf * L::STAGE + L::A_ELEMS + (wn * 16 * NJ + l15) * LDT + quad * 8;
; #pragma unroll
;     for (int ks = 0; ks < 2; ++ks) {
;       if (MI * NJ >= 32 && ks == 1) asm volatile("" ::: "memory");
;       bf16x8 b[NJ];
; #pragma unroll
;       for (int j = 0; j < NJ; ++j) b[j] = *(const bf16x8*)(Bs + j * 16 * LDT + ks * 32);
; #pragma unroll
;       for (int i = 0; i < MI; ++i) {
;         const bf16x8 a = *(const bf16x8*)(As + i * 16 * LDT + ks * 32);
; #pragma unroll
;         for (int j = 0; j < NJ; ++j) acc[i][j] = SWAP ? mfma16(b[j], a, acc[i][j]) : mfma16(a, b[j], acc[i][j]);
;       }
;     }
;     __syncthreads();
;   }
	ds_write_b128 v250, v[144:147] offset:36864
	ds_read_b128 v[242:245], v176 offset:4672
	s_waitcnt lgkmcnt(5)
	v_mfma_f32_16x16x32_bf16 v[124:127], v[212:215], v[178:181], v[124:127]
	s_waitcnt lgkmcnt(4)
	v_mfma_f32_16x16x32_bf16 v[120:123], v[212:215], v[200:203], v[120:123]
	s_add_u32 s6, s2, s33
	s_addc_u32 s7, s3, 0
	v_lshl_add_u64 v[144:145], s[6:7], 0, v[160:161]
	s_nop 0
	global_load_dwordx4 v[144:147], v[144:145], off offset:256
	s_waitcnt lgkmcnt(3)
	v_mfma_f32_16x16x32_bf16 v[116:119], v[212:215], v[204:207], v[116:119]
	s_waitcnt lgkmcnt(2)
	v_mfma_f32_16x16x32_bf16 v[112:115], v[212:215], v[208:211], v[112:115]
	ds_read_b128 v[246:249], v176 offset:6976
	v_mfma_f32_16x16x32_bf16 v[108:111], v[216:219], v[178:181], v[108:111]
	v_mfma_f32_16x16x32_bf16 v[104:107], v[216:219], v[200:203], v[104:107]
	s_waitcnt vmcnt(7)
	ds_write_b128 v251, v[148:151] offset:36864
	v_mfma_f32_16x16x32_bf16 v[100:103], v[216:219], v[204:207], v[100:103]
	v_mfma_f32_16x16x32_bf16 v[96:99], v[216:219], v[208:211], v[96:99]
	v_lshl_add_u64 v[148:149], s[6:7], 0, v[162:163]
	s_nop 0
	global_load_dwordx4 v[148:151], v[148:149], off offset:256
	ds_read_b128 v[212:215], v176 offset:9280
	s_waitcnt lgkmcnt(3)
	v_mfma_f32_16x16x32_bf16 v[92:95], v[242:245], v[178:181], v[92:95]
	v_mfma_f32_16x16x32_bf16 v[88:91], v[242:245], v[200:203], v[88:91]
	v_mfma_f32_16x16x32_bf16 v[84:87], v[242:245], v[204:207], v[84:87]
	v_mfma_f32_16x16x32_bf16 v[80:83], v[242:245], v[208:211], v[80:83]
	ds_read_b128 v[216:219], v176 offset:11584
	s_waitcnt lgkmcnt(3)
	v_mfma_f32_16x16x32_bf16 v[76:79], v[246:249], v[178:181], v[76:79]
	s_waitcnt vmcnt(7)
	ds_write_b128 v252, v[152:155] offset:36864
	v_mfma_f32_16x16x32_bf16 v[72:75], v[246:249], v[200:203], v[72:75]
	v_mfma_f32_16x16x32_bf16 v[68:71], v[246:249], v[204:207], v[68:71]
	v_lshl_add_u64 v[152:153], s[6:7], 0, v[164:165]
	s_nop 0
	global_load_dwordx4 v[152:155], v[152:153], off offset:256
	v_mfma_f32_16x16x32_bf16 v[64:67], v[246:249], v[208:211], v[64:67]
	ds_read_b128 v[242:245], v176 offset:13888
	s_waitcnt lgkmcnt(3)
	v_mfma_f32_16x16x32_bf16 v[60:63], v[212:215], v[178:181], v[60:63]
	v_mfma_f32_16x16x32_bf16 v[56:59], v[212:215], v[200:203], v[56:59]
	v_mfma_f32_16x16x32_bf16 v[52:55], v[212:215], v[204:207], v[52:55]
	v_mfma_f32_16x16x32_bf16 v[48:51], v[212:215], v[208:211], v[48:51]
	s_waitcnt vmcnt(7)
	ds_write_b128 v253, v[156:159] offset:36864
	ds_read_b128 v[246:249], v176 offset:16192
	s_waitcnt lgkmcnt(4)
	v_mfma_f32_16x16x32_bf16 v[44:47], v[216:219], v[178:181], v[44:47]
	v_mfma_f32_16x16x32_bf16 v[40:43], v[216:219], v[200:203], v[40:43]
	v_lshl_add_u64 v[156:157], s[6:7], 0, v[166:167]
	s_nop 0
	global_load_dwordx4 v[156:159], v[156:157], off offset:256
	v_mfma_f32_16x16x32_bf16 v[36:39], v[216:219], v[204:207], v[36:39]
	v_mfma_f32_16x16x32_bf16 v[32:35], v[216:219], v[208:211], v[32:35]
	s_add_i32 s4, s4, 1
	s_and_b32 s98, s4, 1
	s_mul_i32 s98, s98, 0x12000
	v_add3_u32 v176, s98, v174, v175
	v_add3_u32 v182, s98, v169, v175
	s_cmp_lg_u32 s4, 16
	s_waitcnt lgkmcnt(0)
	s_barrier
	s_cbranch_scc0 .Lgm1_exit
	ds_read_b128 v[212:215], v176
	ds_read_b128 v[216:219], v176 offset:2304
	v_mfma_f32_16x16x32_bf16 v[28:31], v[242:245], v[178:181], v[28:31]
	v_mfma_f32_16x16x32_bf16 v[8:11], v[246:249], v[178:181], v[8:11]
	ds_read_b128 v[178:181], v182 offset:36864
	v_mfma_f32_16x16x32_bf16 v[24:27], v[242:245], v[200:203], v[24:27]
	v_mfma_f32_16x16x32_bf16 v[4:7], v[246:249], v[200:203], v[4:7]
	ds_read_b128 v[200:203], v182 offset:39168
	v_mfma_f32_16x16x32_bf16 v[20:23], v[242:245], v[204:207], v[20:23]
	v_mfma_f32_16x16x32_bf16 v[0:3], v[246:249], v[204:207], v[0:3]
	ds_read_b128 v[204:207], v182 offset:41472
	v_mfma_f32_16x16x32_bf16 v[16:19], v[242:245], v[208:211], v[16:19]
	v_mfma_f32_16x16x32_bf16 v[12:15], v[246:249], v[208:211], v[12:15]
	ds_read_b128 v[208:211], v182 offset:43776
	s_branch .Lgm1_main

; DI f32x4 mfma16(bf16x8 a, bf16x8 b, f32x4 c) { return __builtin_amdgcn_mfma_f32_16x16x32_bf16(a, b, c, 0, 0, 0); }
; template <int MI, int NJ, bool SWAP, class AP, class BP>
; DI void gemm_main(f32x4 (&acc)[MI][NJ], const AP& ap, int a_kstep, const BP& bp, int b_kstep, int nk, bf16_t* smem) {
;     ...
;   auto gload = [&](int kt) {
;     const bf16_t* ab = ap.base + (size_t)kt * a_kstep; const bf16_t* bb = bp.base + (size_t)kt * b_kstep;
; #pragma unroll
;     for (int i = 0; i < CA; ++i) ra[i] = *(const u32x4*)(ab + pa[i]);
; #pragma unroll
;     for (int i = 0; i < CB; ++i) rb[i] = *(const u32x4*)(bb + pb[i]);
;   };
;   auto sstore = [&](int buf) {
;     bf16_t* As = smem + buf * L::STAGE; bf16_t* Bs = As + L::A_ELEMS;
; #pragma unroll
;     for (int i = 0; i < CA; ++i) { const int c = tid + NTHR * i; *(u32x4*)(As + (c >> 3) * LDT + (c & 7) * 8) = oka[i] ? ra[i] : (u32x4){0u, 0u, 0u, 0u}; }
; #pragma unroll
;     for (int i = 0; i < CB; ++i) { const int c = tid + NTHR * i; *(u32x4*)(Bs + (c >> 3) * LDT + (c & 7) * 8) = rb[i]; }
;     ...
;   for (int kt = 0; kt < nk; ++kt) {
;     const int buf = kt & 1;
;     sstore(buf ^ 1);
;     gload(kt + 2 < nk ? kt + 2 : nk - 1);
;     __builtin_amdgcn_sched_barrier(0);
;     const bf16_t* As = smem + buf * L::STAGE + (wm * 16 * MI + l15) * LDT + quad * 8;
;     const bf16_t* Bs = smem + buf * L::STAGE + L::A_ELEMS + (wn * 16 * NJ + l15) * LDT + quad * 8;
; #pragma unroll
;     for (int ks = 0; ks < 2; ++ks) {
;       if (MI * NJ >= 32 && ks == 1) asm volatile("" ::: "memory");
;       bf16x8 b[NJ];
; #pragma unroll
;       for (int j = 0; j < NJ; ++j) b[j] = *(const bf16x8*)(Bs + j * 16 * LDT + ks * 32);
; #pragma unroll
;       for (int i = 0; i < MI; ++i) {
;         const bf16x8 a = *(const bf16x8*)(As + i * 16 * LDT + ks * 32);
; #pragma unroll
;         for (int j = 0; j < NJ; ++j) acc[i][j] = SWAP ? mfma16(b[j], a, acc[i][j]) : mfma16(a, b[j], acc[i][j]);
;       }
;     }
.Lgm2_main:
	ds_read_b128 v[242:245], v182 offset:4608
	s_waitcnt lgkmcnt(4)
	v_mfma_f32_16x16x32_bf16 v[156:159], v[178:181], v[198:201], v[156:159]
	s_waitcnt lgkmcnt(3)
	v_mfma_f32_16x16x32_bf16 v[152:155], v[186:189], v[198:201], v[152:155]
	s_waitcnt lgkmcnt(2)
	v_mfma_f32_16x16x32_bf16 v[148:151], v[190:193], v[198:201], v[148:151]
	s_waitcnt lgkmcnt(1)
	v_mfma_f32_16x16x32_bf16 v[144:147], v[194:197], v[198:201], v[144:147]
	ds_read_b128 v[246:249], v182 offset:6912
	v_mfma_f32_16x16x32_bf16 v[108:111], v[178:181], v[202:205], v[108:111]
	v_mfma_f32_16x16x32_bf16 v[104:107], v[186:189], v[202:205], v[104:107]
	s_and_b32 s33, s16, 1
	s_min_u32 s52, s16, 3
	s_xor_b32 s53, s33, 1
	s_mul_i32 s53, s53, 0x12000
	v_add3_u32 v250, s53, v173, v171
	s_waitcnt vmcnt(7)
	ds_write_b128 v250, v[112:115]
	v_mfma_f32_16x16x32_bf16 v[100:103], v[190:193], v[202:205], v[100:103]
	v_mfma_f32_16x16x32_bf16 v[96:99], v[194:197], v[202:205], v[96:99]
	s_lshl_b32 s54, s52, 7
	s_add_u32 s52, s0, s54
	v_add3_u32 v251, s53, v174, v171
	v_add3_u32 v252, s53, v175, v171
	v_add3_u32 v253, s53, v176, v171
	s_addc_u32 s53, s1, 0
	v_lshl_add_u64 v[112:113], s[52:53], 0, v[162:163]
	s_nop 0
	global_load_dwordx4 v[112:115], v[112:113], off offset:256
	ds_read_b128 v[198:201], v182 offset:9216
	s_waitcnt lgkmcnt(3)
	v_mfma_f32_16x16x32_bf16 v[92:95], v[178:181], v[242:245], v[92:95]
	v_mfma_f32_16x16x32_bf16 v[88:91], v[186:189], v[242:245], v[88:91]
	v_mfma_f32_16x16x32_bf16 v[84:87], v[190:193], v[242:245], v[84:87]
	v_mfma_f32_16x16x32_bf16 v[80:83], v[194:197], v[242:245], v[80:83]
	s_waitcnt vmcnt(6)
	ds_write_b128 v251, v[116:119]
	ds_read_b128 v[202:205], v182 offset:11520
	s_waitcnt lgkmcnt(4)
	v_mfma_f32_16x16x32_bf16 v[76:79], v[178:181], v[246:249], v[76:79]
	v_mfma_f32_16x16x32_bf16 v[72:75], v[186:189], v[246:249], v[72:75]
	v_lshl_add_u64 v[116:117], s[52:53], 0, v[164:165]
	s_nop 0
	global_load_dwordx4 v[116:119], v[116:117], off offset:256
	v_mfma_f32_16x16x32_bf16 v[68:71], v[190:193], v[246:249], v[68:71]
	v_mfma_f32_16x16x32_bf16 v[64:67], v[194:197], v[246:249], v[64:67]
	ds_read_b128 v[242:245], v182 offset:13824
	s_waitcnt lgkmcnt(3)
	v_mfma_f32_16x16x32_bf16 v[60:63], v[178:181], v[198:201], v[60:63]
	v_mfma_f32_16x16x32_bf16 v[56:59], v[186:189], v[198:201], v[56:59]
	v_mfma_f32_16x16x32_bf16 v[52:55], v[190:193], v[198:201], v[52:55]
	s_waitcnt vmcnt(6)
	ds_write_b128 v252, v[120:123]
	v_mfma_f32_16x16x32_bf16 v[48:51], v[194:197], v[198:201], v[48:51]
	ds_read_b128 v[246:249], v182 offset:16128
	s_waitcnt lgkmcnt(3)
	v_mfma_f32_16x16x32_bf16 v[44:47], v[178:181], v[202:205], v[44:47]
	v_lshl_add_u64 v[120:121], s[52:53], 0, v[166:167]
	s_nop 0
	global_load_dwordx4 v[120:123], v[120:121], off offset:256
	v_mfma_f32_16x16x32_bf16 v[40:43], v[186:189], v[202:205], v[40:43]
	v_mfma_f32_16x16x32_bf16 v[36:39], v[190:193], v[202:205], v[36:39]
	v_mfma_f32_16x16x32_bf16 v[32:35], v[194:197], v[202:205], v[32:35]
	ds_read_b128 v[198:201], v182 offset:64
	s_waitcnt lgkmcnt(3)
	v_mfma_f32_16x16x32_bf16 v[28:31], v[178:181], v[242:245], v[28:31]
	s_waitcnt vmcnt(6)
	ds_write_b128 v253, v[124:127]
	v_mfma_f32_16x16x32_bf16 v[24:27], v[186:189], v[242:245], v[24:27]
	v_mfma_f32_16x16x32_bf16 v[20:23], v[190:193], v[242:245], v[20:23]
	v_lshl_add_u64 v[124:125], s[52:53], 0, v[168:169]
	s_nop 0
	global_load_dwordx4 v[124:127], v[124:125], off offset:256
	v_mfma_f32_16x16x32_bf16 v[16:19], v[194:197], v[242:245], v[16:19]
	ds_read_b128 v[202:205], v182 offset:2368
	s_waitcnt lgkmcnt(3)
	v_mfma_f32_16x16x32_bf16 v[8:11], v[178:181], v[246:249], v[8:11]
	ds_read_b128 v[178:181], v183 offset:36928
	v_mfma_f32_16x16x32_bf16 v[4:7], v[186:189], v[246:249], v[4:7]
	ds_read_b128 v[186:189], v183 offset:39232
	v_mfma_f32_16x16x32_bf16 v[0:3], v[190:193], v[246:249], v[0:3]
	ds_read_b128 v[190:193], v183 offset:41536
	v_mfma_f32_16x16x32_bf16 v[12:15], v[194:197], v[246:249], v[12:15]
	ds_read_b128 v[194:197], v183 offset:43840
	ds_write_b128 v250, v[128:131] offset:36864
	ds_read_b128 v[242:245], v182 offset:4672
	s_waitcnt lgkmcnt(5)
; DI f32x4 mfma16(bf16x8 a, bf16x8 b, f32x4 c) { return __builtin_amdgcn_mfma_f32_16x16x32_bf16(a, b, c, 0, 0, 0); }
; template <int MI, int NJ, bool SWAP, class AP, class BP>
; DI void gemm_main(f32x4 (&acc)[MI][NJ], const AP& ap, int a_kstep, const BP& bp, int b_kstep, int nk, bf16_t* smem) {
;     ...
;   auto gload = [&](int kt) {
;     const bf16_t* ab = ap.base + (size_t)kt * a_kstep; const bf16_t* bb = bp.base + (size_t)kt * b_kstep;
; #pragma unroll
;     for (int i = 0; i < CA; ++i) ra[i] = *(const u32x4*)(ab + pa[i]);
; #pragma unroll
;     for (int i = 0; i < CB; ++i) rb[i] = *(const u32x4*)(bb + pb[i]);
;   };
;   auto sstore = [&](int buf) {
;     bf16_t* As = smem + buf * L::STAGE; bf16_t* Bs = As + L::A_ELEMS;
; #pragma unroll
;     for (int i = 0; i < CA; ++i) { const int c = tid + NTHR * i; *(u32x4*)(As + (c >> 3) * LDT + (c & 7) * 8) = oka[i] ? ra[i] : (u32x4){0u, 0u, 0u, 0u}; }
; #pragma unroll
;     for (int i = 0; i < CB; ++i) { const int c = tid + NTHR * i; *(u32x4*)(Bs + (c >> 3) * LDT + (c & 7) * 8) = rb[i]; }
;     ...
;   for (int kt = 0; kt < nk; ++kt) {
;     const int buf = kt & 1;
;     sstore(buf ^ 1);
;     gload(kt + 2 < nk ? kt + 2 : nk - 1);
;     __builtin_amdgcn_sched_barrier(0);
;     const bf16_t* As = smem + buf * L::STAGE + (wm * 16 * MI + l15) * LDT + quad * 8;
;     const bf16_t* Bs = smem + buf * L::STAGE + L::A_ELEMS + (wn * 16 * NJ + l15) * LDT + quad * 8;
; #pragma unroll
;     for (int ks = 0; ks < 2; ++ks) {
;       if (MI * NJ >= 32 && ks == 1) asm volatile("" ::: "memory");
;       bf16x8 b[NJ];
; #pragma unroll
;       for (int j = 0; j < NJ; ++j) b[j] = *(const bf16x8*)(Bs + j * 16 * LDT + ks * 32);
; #pragma unroll
;       for (int i = 0; i < MI; ++i) {
;         const bf16x8 a = *(const bf16x8*)(As + i * 16 * LDT + ks * 32);
; #pragma unroll
;         for (int j = 0; j < NJ; ++j) acc[i][j] = SWAP ? mfma16(b[j], a, acc[i][j]) : mfma16(a, b[j], acc[i][j]);
;       }
;     }
;     __syncthreads();
;   }
	v_mfma_f32_16x16x32_bf16 v[156:159], v[178:181], v[198:201], v[156:159]
	s_waitcnt lgkmcnt(4)
	v_mfma_f32_16x16x32_bf16 v[152:155], v[186:189], v[198:201], v[152:155]
	s_add_u32 s52, s2, s54
	s_addc_u32 s53, s3, 0
	v_lshl_add_u64 v[128:129], s[52:53], 0, v[162:163]
	s_nop 0
	global_load_dwordx4 v[128:131], v[128:129], off offset:256
	s_waitcnt lgkmcnt(3)
	v_mfma_f32_16x16x32_bf16 v[148:151], v[190:193], v[198:201], v[148:151]
	s_waitcnt lgkmcnt(2)
	v_mfma_f32_16x16x32_bf16 v[144:147], v[194:197], v[198:201], v[144:147]
	ds_read_b128 v[246:249], v182 offset:6976
	v_mfma_f32_16x16x32_bf16 v[108:111], v[178:181], v[202:205], v[108:111]
	v_mfma_f32_16x16x32_bf16 v[104:107], v[186:189], v[202:205], v[104:107]
	s_waitcnt vmcnt(7)
	ds_write_b128 v251, v[132:135] offset:36864
	v_mfma_f32_16x16x32_bf16 v[100:103], v[190:193], v[202:205], v[100:103]
	v_mfma_f32_16x16x32_bf16 v[96:99], v[194:197], v[202:205], v[96:99]
	v_lshl_add_u64 v[132:133], s[52:53], 0, v[164:165]
	s_nop 0
	global_load_dwordx4 v[132:135], v[132:133], off offset:256
	ds_read_b128 v[198:201], v182 offset:9280
	s_waitcnt lgkmcnt(3)
	v_mfma_f32_16x16x32_bf16 v[92:95], v[178:181], v[242:245], v[92:95]
	v_mfma_f32_16x16x32_bf16 v[88:91], v[186:189], v[242:245], v[88:91]
	v_mfma_f32_16x16x32_bf16 v[84:87], v[190:193], v[242:245], v[84:87]
	v_mfma_f32_16x16x32_bf16 v[80:83], v[194:197], v[242:245], v[80:83]
	ds_read_b128 v[202:205], v182 offset:11584
	s_waitcnt lgkmcnt(3)
	v_mfma_f32_16x16x32_bf16 v[76:79], v[178:181], v[246:249], v[76:79]
	s_waitcnt vmcnt(7)
	ds_write_b128 v252, v[136:139] offset:36864
	v_mfma_f32_16x16x32_bf16 v[72:75], v[186:189], v[246:249], v[72:75]
	v_mfma_f32_16x16x32_bf16 v[68:71], v[190:193], v[246:249], v[68:71]
	v_lshl_add_u64 v[136:137], s[52:53], 0, v[166:167]
	s_nop 0
	global_load_dwordx4 v[136:139], v[136:137], off offset:256
	v_mfma_f32_16x16x32_bf16 v[64:67], v[194:197], v[246:249], v[64:67]
	ds_read_b128 v[242:245], v182 offset:13888
	s_waitcnt lgkmcnt(3)
	v_mfma_f32_16x16x32_bf16 v[60:63], v[178:181], v[198:201], v[60:63]
	v_mfma_f32_16x16x32_bf16 v[56:59], v[186:189], v[198:201], v[56:59]
	v_mfma_f32_16x16x32_bf16 v[52:55], v[190:193], v[198:201], v[52:55]
	v_mfma_f32_16x16x32_bf16 v[48:51], v[194:197], v[198:201], v[48:51]
	s_waitcnt vmcnt(7)
	ds_write_b128 v253, v[140:143] offset:36864
	ds_read_b128 v[246:249], v182 offset:16192
	s_waitcnt lgkmcnt(4)
	v_mfma_f32_16x16x32_bf16 v[44:47], v[178:181], v[202:205], v[44:47]
	v_mfma_f32_16x16x32_bf16 v[40:43], v[186:189], v[202:205], v[40:43]
	v_lshl_add_u64 v[140:141], s[52:53], 0, v[168:169]
	s_nop 0
	global_load_dwordx4 v[140:143], v[140:141], off offset:256
	v_mfma_f32_16x16x32_bf16 v[36:39], v[190:193], v[202:205], v[36:39]
	v_mfma_f32_16x16x32_bf16 v[32:35], v[194:197], v[202:205], v[32:35]
	s_add_i32 s16, s16, 1
	s_and_b32 s98, s16, 1
	s_mul_i32 s98, s98, 0x12000
	v_add3_u32 v183, s98, v160, v177
	v_add3_u32 v182, s98, v172, v177
	s_cmp_lg_u32 s16, 6
	s_waitcnt lgkmcnt(0)
	s_barrier
	s_cbranch_scc0 .Lgm2_exit
	ds_read_b128 v[198:201], v182
	ds_read_b128 v[202:205], v182 offset:2304
	v_mfma_f32_16x16x32_bf16 v[28:31], v[178:181], v[242:245], v[28:31]
	v_mfma_f32_16x16x32_bf16 v[8:11], v[178:181], v[246:249], v[8:11]
	ds_read_b128 v[178:181], v183 offset:36864
	v_mfma_f32_16x16x32_bf16 v[24:27], v[186:189], v[242:245], v[24:27]
	v_mfma_f32_16x16x32_bf16 v[4:7], v[186:189], v[246:249], v[4:7]
	ds_read_b128 v[186:189], v183 offset:39168
	v_mfma_f32_16x16x32_bf16 v[20:23], v[190:193], v[242:245], v[20:23]
	v_mfma_f32_16x16x32_bf16 v[0:3], v[190:193], v[246:249], v[0:3]
	ds_read_b128 v[190:193], v183 offset:41472
	v_mfma_f32_16x16x32_bf16 v[16:19], v[194:197], v[242:245], v[16:19]
	v_mfma_f32_16x16x32_bf16 v[12:15], v[194:197], v[246:249], v[12:15]
	ds_read_b128 v[194:197], v183 offset:43776
	s_branch .Lgm2_main

; DI f32x4 mfma16(bf16x8 a, bf16x8 b, f32x4 c) { return __builtin_amdgcn_mfma_f32_16x16x32_bf16(a, b, c, 0, 0, 0); }
; template <int MI, int NJ, bool SWAP, class AP, class BP>
; DI void gemm_main(f32x4 (&acc)[MI][NJ], const AP& ap, int a_kstep, const BP& bp, int b_kstep, int nk, bf16_t* smem) {
;     ...
;   auto gload = [&](int kt) {
;     const bf16_t* ab = ap.base + (size_t)kt * a_kstep; const bf16_t* bb = bp.base + (size_t)kt * b_kstep;
; #pragma unroll
;     for (int i = 0; i < CA; ++i) ra[i] = *(const u32x4*)(ab + pa[i]);
; #pragma unroll
;     for (int i = 0; i < CB; ++i) rb[i] = *(const u32x4*)(bb + pb[i]);
;   };
;   auto sstore = [&](int buf) {
;     bf16_t* As = smem + buf * L::STAGE; bf16_t* Bs = As + L::A_ELEMS;
; #pragma unroll
;     for (int i = 0; i < CA; ++i) { const int c = tid + NTHR * i; *(u32x4*)(As + (c >> 3) * LDT + (c & 7) * 8) = oka[i] ? ra[i] : (u32x4){0u, 0u, 0u, 0u}; }
; #pragma unroll
;     for (int i = 0; i < CB; ++i) { const int c = tid + NTHR * i; *(u32x4*)(Bs + (c >> 3) * LDT + (c & 7) * 8) = rb[i]; }
;     ...
;   for (int kt = 0; kt < nk; ++kt) {
;     const int buf = kt & 1;
;     sstore(buf ^ 1);
;     gload(kt + 2 < nk ? kt + 2 : nk - 1);
;     __builtin_amdgcn_sched_barrier(0);
;     const bf16_t* As = smem + buf * L::STAGE + (wm * 16 * MI + l15) * LDT + quad * 8;
;     const bf16_t* Bs = smem + buf * L::STAGE + L::A_ELEMS + (wn * 16 * NJ + l15) * LDT + quad * 8;
; #pragma unroll
;     for (int ks = 0; ks < 2; ++ks) {
;       if (MI * NJ >= 32 && ks == 1) asm volatile("" ::: "memory");
;       bf16x8 b[NJ];
; #pragma unroll
;       for (int j = 0; j < NJ; ++j) b[j] = *(const bf16x8*)(Bs + j * 16 * LDT + ks * 32);
; #pragma unroll
;       for (int i = 0; i < MI; ++i) {
;         const bf16x8 a = *(const bf16x8*)(As + i * 16 * LDT + ks * 32);
; #pragma unroll
;         for (int j = 0; j < NJ; ++j) acc[i][j] = SWAP ? mfma16(b[j], a, acc[i][j]) : mfma16(a, b[j], acc[i][j]);
;       }
;     }
.Lgm3_main:
	ds_read_b128 v[242:245], v182 offset:4608
	s_waitcnt lgkmcnt(4)
	v_mfma_f32_16x16x32_bf16 v[156:159], v[178:181], v[198:201], v[156:159]
	s_waitcnt lgkmcnt(3)
	v_mfma_f32_16x16x32_bf16 v[152:155], v[186:189], v[198:201], v[152:155]
	s_waitcnt lgkmcnt(2)
	v_mfma_f32_16x16x32_bf16 v[148:151], v[190:193], v[198:201], v[148:151]
	s_waitcnt lgkmcnt(1)
	v_mfma_f32_16x16x32_bf16 v[144:147], v[194:197], v[198:201], v[144:147]
	ds_read_b128 v[246:249], v182 offset:6912
	v_mfma_f32_16x16x32_bf16 v[108:111], v[178:181], v[202:205], v[108:111]
	v_mfma_f32_16x16x32_bf16 v[104:107], v[186:189], v[202:205], v[104:107]
	v_lshlrev_b32_e32 v250, 1, v160
	s_and_b32 s54, s33, 1
	s_xor_b32 s52, s54, 1
	s_mul_i32 s52, s52, 0x12000
	v_add3_u32 v250, s52, v250, v172
	s_waitcnt vmcnt(7)
	ds_write_b128 v250, v[112:115]
	v_mfma_f32_16x16x32_bf16 v[100:103], v[190:193], v[202:205], v[100:103]
	v_mfma_f32_16x16x32_bf16 v[96:99], v[194:197], v[202:205], v[96:99]
	s_cmp_eq_u32 s33, 0
	s_cselect_b32 s55, s48, 0x180
	v_lshlrev_b32_e32 v251, 1, v173
	v_add3_u32 v251, s52, v251, v172
	v_lshlrev_b32_e32 v252, 1, v174
	v_add3_u32 v252, s52, v252, v172
	v_lshlrev_b32_e32 v253, 1, v175
	v_add3_u32 v253, s52, v253, v172
	s_add_u32 s52, s0, s55
	s_addc_u32 s53, s1, 0
	v_lshl_add_u64 v[112:113], s[52:53], 0, v[162:163]
	s_nop 0
	global_load_dwordx4 v[112:115], v[112:113], off
	ds_read_b128 v[198:201], v182 offset:9216
	s_waitcnt lgkmcnt(3)
	v_mfma_f32_16x16x32_bf16 v[92:95], v[178:181], v[242:245], v[92:95]
	v_mfma_f32_16x16x32_bf16 v[88:91], v[186:189], v[242:245], v[88:91]
	v_mfma_f32_16x16x32_bf16 v[84:87], v[190:193], v[242:245], v[84:87]
	v_mfma_f32_16x16x32_bf16 v[80:83], v[194:197], v[242:245], v[80:83]
	s_waitcnt vmcnt(7)
	ds_write_b128 v251, v[116:119]
	ds_read_b128 v[202:205], v182 offset:11520
	s_waitcnt lgkmcnt(4)
	v_mfma_f32_16x16x32_bf16 v[76:79], v[178:181], v[246:249], v[76:79]
	v_mfma_f32_16x16x32_bf16 v[72:75], v[186:189], v[246:249], v[72:75]
	v_lshl_add_u64 v[116:117], s[52:53], 0, v[164:165]
	s_nop 0
	global_load_dwordx4 v[116:119], v[116:117], off
	v_mfma_f32_16x16x32_bf16 v[68:71], v[190:193], v[246:249], v[68:71]
	v_mfma_f32_16x16x32_bf16 v[64:67], v[194:197], v[246:249], v[64:67]
	ds_read_b128 v[242:245], v182 offset:13824
	s_waitcnt lgkmcnt(3)
	v_mfma_f32_16x16x32_bf16 v[60:63], v[178:181], v[198:201], v[60:63]
	v_mfma_f32_16x16x32_bf16 v[56:59], v[186:189], v[198:201], v[56:59]
	v_mfma_f32_16x16x32_bf16 v[52:55], v[190:193], v[198:201], v[52:55]
	s_waitcnt vmcnt(7)
	ds_write_b128 v252, v[120:123]
	v_mfma_f32_16x16x32_bf16 v[48:51], v[194:197], v[198:201], v[48:51]
	ds_read_b128 v[246:249], v182 offset:16128
	s_waitcnt lgkmcnt(3)
	v_mfma_f32_16x16x32_bf16 v[44:47], v[178:181], v[202:205], v[44:47]
	v_lshl_add_u64 v[120:121], s[52:53], 0, v[166:167]
	s_nop 0
	global_load_dwordx4 v[120:123], v[120:121], off
	v_mfma_f32_16x16x32_bf16 v[40:43], v[186:189], v[202:205], v[40:43]
	v_mfma_f32_16x16x32_bf16 v[36:39], v[190:193], v[202:205], v[36:39]
	v_mfma_f32_16x16x32_bf16 v[32:35], v[194:197], v[202:205], v[32:35]
	ds_read_b128 v[198:201], v182 offset:64
	s_waitcnt lgkmcnt(3)
	v_mfma_f32_16x16x32_bf16 v[28:31], v[178:181], v[242:245], v[28:31]
	s_waitcnt vmcnt(7)
	ds_write_b128 v253, v[124:127]
	v_mfma_f32_16x16x32_bf16 v[24:27], v[186:189], v[242:245], v[24:27]
	v_mfma_f32_16x16x32_bf16 v[20:23], v[190:193], v[242:245], v[20:23]
	v_lshl_add_u64 v[124:125], s[52:53], 0, v[168:169]
	s_nop 0
	global_load_dwordx4 v[124:127], v[124:125], off
	v_mfma_f32_16x16x32_bf16 v[16:19], v[194:197], v[242:245], v[16:19]
	ds_read_b128 v[202:205], v182 offset:2368
	s_waitcnt lgkmcnt(3)
	v_mfma_f32_16x16x32_bf16 v[8:11], v[178:181], v[246:249], v[8:11]
	ds_read_b128 v[178:181], v183 offset:36928
	v_mfma_f32_16x16x32_bf16 v[4:7], v[186:189], v[246:249], v[4:7]
	ds_read_b128 v[186:189], v183 offset:39232
	v_mfma_f32_16x16x32_bf16 v[0:3], v[190:193], v[246:249], v[0:3]
	ds_read_b128 v[190:193], v183 offset:41536
	v_mfma_f32_16x16x32_bf16 v[12:15], v[194:197], v[246:249], v[12:15]
	ds_read_b128 v[194:197], v183 offset:43840
	s_waitcnt vmcnt(7)
; DI f32x4 mfma16(bf16x8 a, bf16x8 b, f32x4 c) { return __builtin_amdgcn_mfma_f32_16x16x32_bf16(a, b, c, 0, 0, 0); }
; template <int MI, int NJ, bool SWAP, class AP, class BP>
; DI void gemm_main(f32x4 (&acc)[MI][NJ], const AP& ap, int a_kstep, const BP& bp, int b_kstep, int nk, bf16_t* smem) {
;     ...
;   auto gload = [&](int kt) {
;     const bf16_t* ab = ap.base + (size_t)kt * a_kstep; const bf16_t* bb = bp.base + (size_t)kt * b_kstep;
; #pragma unroll
;     for (int i = 0; i < CA; ++i) ra[i] = *(const u32x4*)(ab + pa[i]);
; #pragma unroll
;     for (int i = 0; i < CB; ++i) rb[i] = *(const u32x4*)(bb + pb[i]);
;   };
;   auto sstore = [&](int buf) {
;     bf16_t* As = smem + buf * L::STAGE; bf16_t* Bs = As + L::A_ELEMS;
; #pragma unroll
;     for (int i = 0; i < CA; ++i) { const int c = tid + NTHR * i; *(u32x4*)(As + (c >> 3) * LDT + (c & 7) * 8) = oka[i] ? ra[i] : (u32x4){0u, 0u, 0u, 0u}; }
; #pragma unroll
;     for (int i = 0; i < CB; ++i) { const int c = tid + NTHR * i; *(u32x4*)(Bs + (c >> 3) * LDT + (c & 7) * 8) = rb[i]; }
;     ...
;   for (int kt = 0; kt < nk; ++kt) {
;     const int buf = kt & 1;
;     sstore(buf ^ 1);
;     gload(kt + 2 < nk ? kt + 2 : nk - 1);
;     __builtin_amdgcn_sched_barrier(0);
;     const bf16_t* As = smem + buf * L::STAGE + (wm * 16 * MI + l15) * LDT + quad * 8;
;     const bf16_t* Bs = smem + buf * L::STAGE + L::A_ELEMS + (wn * 16 * NJ + l15) * LDT + quad * 8;
; #pragma unroll
;     for (int ks = 0; ks < 2; ++ks) {
;       if (MI * NJ >= 32 && ks == 1) asm volatile("" ::: "memory");
;       bf16x8 b[NJ];
; #pragma unroll
;       for (int j = 0; j < NJ; ++j) b[j] = *(const bf16x8*)(Bs + j * 16 * LDT + ks * 32);
; #pragma unroll
;       for (int i = 0; i < MI; ++i) {
;         const bf16x8 a = *(const bf16x8*)(As + i * 16 * LDT + ks * 32);
; #pragma unroll
;         for (int j = 0; j < NJ; ++j) acc[i][j] = SWAP ? mfma16(b[j], a, acc[i][j]) : mfma16(a, b[j], acc[i][j]);
;       }
;     }
;     __syncthreads();
;   }
	ds_write_b128 v250, v[128:131] offset:36864
	ds_read_b128 v[242:245], v182 offset:4672
	s_waitcnt lgkmcnt(5)
	v_mfma_f32_16x16x32_bf16 v[156:159], v[178:181], v[198:201], v[156:159]
	s_waitcnt lgkmcnt(4)
	v_mfma_f32_16x16x32_bf16 v[152:155], v[186:189], v[198:201], v[152:155]
	s_add_u32 s52, s2, s55
	s_addc_u32 s53, s3, 0
	v_lshl_add_u64 v[128:129], s[52:53], 0, v[162:163]
	s_nop 0
	global_load_dwordx4 v[128:131], v[128:129], off
	s_waitcnt lgkmcnt(3)
	v_mfma_f32_16x16x32_bf16 v[148:151], v[190:193], v[198:201], v[148:151]
	s_waitcnt lgkmcnt(2)
	v_mfma_f32_16x16x32_bf16 v[144:147], v[194:197], v[198:201], v[144:147]
	ds_read_b128 v[246:249], v182 offset:6976
	v_mfma_f32_16x16x32_bf16 v[108:111], v[178:181], v[202:205], v[108:111]
	v_mfma_f32_16x16x32_bf16 v[104:107], v[186:189], v[202:205], v[104:107]
	s_waitcnt vmcnt(7)
	ds_write_b128 v251, v[132:135] offset:36864
	v_mfma_f32_16x16x32_bf16 v[100:103], v[190:193], v[202:205], v[100:103]
	v_mfma_f32_16x16x32_bf16 v[96:99], v[194:197], v[202:205], v[96:99]
	v_lshl_add_u64 v[132:133], s[52:53], 0, v[164:165]
	s_nop 0
	global_load_dwordx4 v[132:135], v[132:133], off
	ds_read_b128 v[198:201], v182 offset:9280
	s_waitcnt lgkmcnt(3)
	v_mfma_f32_16x16x32_bf16 v[92:95], v[178:181], v[242:245], v[92:95]
	v_mfma_f32_16x16x32_bf16 v[88:91], v[186:189], v[242:245], v[88:91]
	v_mfma_f32_16x16x32_bf16 v[84:87], v[190:193], v[242:245], v[84:87]
	v_mfma_f32_16x16x32_bf16 v[80:83], v[194:197], v[242:245], v[80:83]
	ds_read_b128 v[202:205], v182 offset:11584
	s_waitcnt lgkmcnt(3)
	v_mfma_f32_16x16x32_bf16 v[76:79], v[178:181], v[246:249], v[76:79]
	s_waitcnt vmcnt(7)
	ds_write_b128 v252, v[136:139] offset:36864
	v_mfma_f32_16x16x32_bf16 v[72:75], v[186:189], v[246:249], v[72:75]
	v_mfma_f32_16x16x32_bf16 v[68:71], v[190:193], v[246:249], v[68:71]
	v_lshl_add_u64 v[136:137], s[52:53], 0, v[166:167]
	s_nop 0
	global_load_dwordx4 v[136:139], v[136:137], off
	v_mfma_f32_16x16x32_bf16 v[64:67], v[194:197], v[246:249], v[64:67]
	ds_read_b128 v[242:245], v182 offset:13888
	s_waitcnt lgkmcnt(3)
	v_mfma_f32_16x16x32_bf16 v[60:63], v[178:181], v[198:201], v[60:63]
	v_mfma_f32_16x16x32_bf16 v[56:59], v[186:189], v[198:201], v[56:59]
	v_mfma_f32_16x16x32_bf16 v[52:55], v[190:193], v[198:201], v[52:55]
	v_mfma_f32_16x16x32_bf16 v[48:51], v[194:197], v[198:201], v[48:51]
	s_waitcnt vmcnt(7)
	ds_write_b128 v253, v[140:143] offset:36864
	ds_read_b128 v[246:249], v182 offset:16192
	s_waitcnt lgkmcnt(4)
	v_mfma_f32_16x16x32_bf16 v[44:47], v[178:181], v[202:205], v[44:47]
	v_mfma_f32_16x16x32_bf16 v[40:43], v[186:189], v[202:205], v[40:43]
	v_lshl_add_u64 v[140:141], s[52:53], 0, v[168:169]
	s_nop 0
	global_load_dwordx4 v[140:143], v[140:141], off
	v_mfma_f32_16x16x32_bf16 v[36:39], v[190:193], v[202:205], v[36:39]
	v_mfma_f32_16x16x32_bf16 v[32:35], v[194:197], v[202:205], v[32:35]
	s_add_i32 s33, s33, 1
	s_and_b32 s98, s33, 1
	s_mul_i32 s98, s98, 0x12000
	v_add3_u32 v183, s98, v171, v177
	v_add3_u32 v182, s98, v176, v177
	s_cmp_lg_u32 s33, 4
	s_waitcnt lgkmcnt(0)
	s_barrier
	s_cbranch_scc0 .Lgm3_exit
	ds_read_b128 v[198:201], v182
	ds_read_b128 v[202:205], v182 offset:2304
	v_mfma_f32_16x16x32_bf16 v[28:31], v[178:181], v[242:245], v[28:31]
	v_mfma_f32_16x16x32_bf16 v[8:11], v[178:181], v[246:249], v[8:11]
	ds_read_b128 v[178:181], v183 offset:36864
	v_mfma_f32_16x16x32_bf16 v[24:27], v[186:189], v[242:245], v[24:27]
	v_mfma_f32_16x16x32_bf16 v[4:7], v[186:189], v[246:249], v[4:7]
	ds_read_b128 v[186:189], v183 offset:39168
	v_mfma_f32_16x16x32_bf16 v[20:23], v[190:193], v[242:245], v[20:23]
	v_mfma_f32_16x16x32_bf16 v[0:3], v[190:193], v[246:249], v[0:3]
	ds_read_b128 v[190:193], v183 offset:41472
	v_mfma_f32_16x16x32_bf16 v[16:19], v[194:197], v[242:245], v[16:19]
	v_mfma_f32_16x16x32_bf16 v[12:15], v[194:197], v[246:249], v[12:15]
	ds_read_b128 v[194:197], v183 offset:43776
	s_branch .Lgm3_main

; DI f32x4 mfma16(bf16x8 a, bf16x8 b, f32x4 c) { return __builtin_amdgcn_mfma_f32_16x16x32_bf16(a, b, c, 0, 0, 0); }
; template <int MI, int NJ, bool SWAP, class AP, class BP>
; DI void gemm_main(f32x4 (&acc)[MI][NJ], const AP& ap, int a_kstep, const BP& bp, int b_kstep, int nk, bf16_t* smem) {
;     ...
;   auto gload = [&](int kt) {
;     const bf16_t* ab = ap.base + (size_t)kt * a_kstep; const bf16_t* bb = bp.base + (size_t)kt * b_kstep;
; #pragma unroll
;     for (int i = 0; i < CA; ++i) ra[i] = *(const u32x4*)(ab + pa[i]);
; #pragma unroll
;     for (int i = 0; i < CB; ++i) rb[i] = *(const u32x4*)(bb + pb[i]);
;   };
;   auto sstore = [&](int buf) {
;     bf16_t* As = smem + buf * L::STAGE; bf16_t* Bs = As + L::A_ELEMS;
; #pragma unroll
;     for (int i = 0; i < CA; ++i) { const int c = tid + NTHR * i; *(u32x4*)(As + (c >> 3) * LDT + (c & 7) * 8) = oka[i] ? ra[i] : (u32x4){0u, 0u, 0u, 0u}; }
; #pragma unroll
;     for (int i = 0; i < CB; ++i) { const int c = tid + NTHR * i; *(u32x4*)(Bs + (c >> 3) * LDT + (c & 7) * 8) = rb[i]; }
;     ...
;   for (int kt = 0; kt < nk; ++kt) {
;     const int buf = kt & 1;
;     sstore(buf ^ 1);
;     gload(kt + 2 < nk ? kt + 2 : nk - 1);
;     __builtin_amdgcn_sched_barrier(0);
;     const bf16_t* As = smem + buf * L::STAGE + (wm * 16 * MI + l15) * LDT + quad * 8;
;     const bf16_t* Bs = smem + buf * L::STAGE + L::A_ELEMS + (wn * 16 * NJ + l15) * LDT + quad * 8;
; #pragma unroll
;     for (int ks = 0; ks < 2; ++ks) {
;       if (MI * NJ >= 32 && ks == 1) asm volatile("" ::: "memory");
;       bf16x8 b[NJ];
; #pragma unroll
;       for (int j = 0; j < NJ; ++j) b[j] = *(const bf16x8*)(Bs + j * 16 * LDT + ks * 32);
; #pragma unroll
;       for (int i = 0; i < MI; ++i) {
;         const bf16x8 a = *(const bf16x8*)(As + i * 16 * LDT + ks * 32);
; #pragma unroll
;         for (int j = 0; j < NJ; ++j) acc[i][j] = SWAP ? mfma16(b[j], a, acc[i][j]) : mfma16(a, b[j], acc[i][j]);
;       }
;     }
.Lgm4_main:
	ds_read_b128 v[242:245], v182 offset:4608
	s_waitcnt lgkmcnt(4)
	v_mfma_f32_16x16x32_bf16 v[140:143], v[198:201], v[178:181], v[140:143]
	s_waitcnt lgkmcnt(3)
	v_mfma_f32_16x16x32_bf16 v[120:123], v[198:201], v[186:189], v[120:123]
	s_waitcnt lgkmcnt(2)
	v_mfma_f32_16x16x32_bf16 v[116:119], v[198:201], v[190:193], v[116:119]
	s_waitcnt lgkmcnt(1)
	v_mfma_f32_16x16x32_bf16 v[112:115], v[198:201], v[194:197], v[112:115]
	ds_read_b128 v[246:249], v182 offset:6912
	v_mfma_f32_16x16x32_bf16 v[108:111], v[202:205], v[178:181], v[108:111]
	v_mfma_f32_16x16x32_bf16 v[104:107], v[202:205], v[186:189], v[104:107]
	v_lshlrev_b32_e32 v250, 1, v160
	s_and_b32 s16, s5, 1
	s_xor_b32 s33, s16, 1
	s_mul_i32 s33, s33, 0x12000
	v_add3_u32 v250, s33, v250, v172
	s_waitcnt vmcnt(7)
	ds_write_b128 v250, v[124:127]
	v_mfma_f32_16x16x32_bf16 v[100:103], v[202:205], v[190:193], v[100:103]
	v_mfma_f32_16x16x32_bf16 v[96:99], v[202:205], v[194:197], v[96:99]
	s_cmp_eq_u32 s5, 0
	v_lshlrev_b32_e32 v251, 1, v173
	v_add3_u32 v251, s33, v251, v172
	v_lshlrev_b32_e32 v252, 1, v174
	v_add3_u32 v252, s33, v252, v172
	v_lshlrev_b32_e32 v253, 1, v175
	v_add3_u32 v253, s33, v253, v172
	s_cselect_b32 s33, s48, 0x180
	s_add_u32 s52, s0, s33
	s_addc_u32 s53, s1, 0
	v_lshl_add_u64 v[124:125], s[52:53], 0, v[162:163]
	s_nop 0
	global_load_dwordx4 v[124:127], v[124:125], off
	ds_read_b128 v[198:201], v182 offset:9216
	s_waitcnt lgkmcnt(3)
	v_mfma_f32_16x16x32_bf16 v[92:95], v[242:245], v[178:181], v[92:95]
	v_mfma_f32_16x16x32_bf16 v[88:91], v[242:245], v[186:189], v[88:91]
	v_mfma_f32_16x16x32_bf16 v[84:87], v[242:245], v[190:193], v[84:87]
	v_mfma_f32_16x16x32_bf16 v[80:83], v[242:245], v[194:197], v[80:83]
	s_waitcnt vmcnt(7)
	ds_write_b128 v251, v[128:131]
	ds_read_b128 v[202:205], v182 offset:11520
	s_waitcnt lgkmcnt(4)
	v_mfma_f32_16x16x32_bf16 v[76:79], v[246:249], v[178:181], v[76:79]
	v_mfma_f32_16x16x32_bf16 v[72:75], v[246:249], v[186:189], v[72:75]
	v_lshl_add_u64 v[128:129], s[52:53], 0, v[164:165]
	s_nop 0
	global_load_dwordx4 v[128:131], v[128:129], off
	v_mfma_f32_16x16x32_bf16 v[68:71], v[246:249], v[190:193], v[68:71]
	v_mfma_f32_16x16x32_bf16 v[64:67], v[246:249], v[194:197], v[64:67]
	ds_read_b128 v[242:245], v182 offset:13824
	s_waitcnt lgkmcnt(3)
	v_mfma_f32_16x16x32_bf16 v[60:63], v[198:201], v[178:181], v[60:63]
	v_mfma_f32_16x16x32_bf16 v[56:59], v[198:201], v[186:189], v[56:59]
	v_mfma_f32_16x16x32_bf16 v[52:55], v[198:201], v[190:193], v[52:55]
	s_waitcnt vmcnt(7)
	ds_write_b128 v252, v[132:135]
	v_mfma_f32_16x16x32_bf16 v[48:51], v[198:201], v[194:197], v[48:51]
	ds_read_b128 v[246:249], v182 offset:16128
	s_waitcnt lgkmcnt(3)
	v_mfma_f32_16x16x32_bf16 v[44:47], v[202:205], v[178:181], v[44:47]
	v_lshl_add_u64 v[132:133], s[52:53], 0, v[166:167]
	s_nop 0
	global_load_dwordx4 v[132:135], v[132:133], off
	v_mfma_f32_16x16x32_bf16 v[40:43], v[202:205], v[186:189], v[40:43]
	v_mfma_f32_16x16x32_bf16 v[36:39], v[202:205], v[190:193], v[36:39]
	v_mfma_f32_16x16x32_bf16 v[32:35], v[202:205], v[194:197], v[32:35]
	ds_read_b128 v[198:201], v182 offset:64
	s_waitcnt lgkmcnt(3)
	v_mfma_f32_16x16x32_bf16 v[28:31], v[242:245], v[178:181], v[28:31]
	s_waitcnt vmcnt(7)
	ds_write_b128 v253, v[136:139]
	v_mfma_f32_16x16x32_bf16 v[24:27], v[242:245], v[186:189], v[24:27]
	v_mfma_f32_16x16x32_bf16 v[20:23], v[242:245], v[190:193], v[20:23]
	v_lshl_add_u64 v[136:137], s[52:53], 0, v[168:169]
	s_nop 0
	global_load_dwordx4 v[136:139], v[136:137], off
	v_mfma_f32_16x16x32_bf16 v[16:19], v[242:245], v[194:197], v[16:19]
	ds_read_b128 v[202:205], v182 offset:2368
	s_waitcnt lgkmcnt(3)
	v_mfma_f32_16x16x32_bf16 v[8:11], v[246:249], v[178:181], v[8:11]
	ds_read_b128 v[178:181], v183 offset:36928
	v_mfma_f32_16x16x32_bf16 v[4:7], v[246:249], v[186:189], v[4:7]
	ds_read_b128 v[186:189], v183 offset:39232
	v_mfma_f32_16x16x32_bf16 v[0:3], v[246:249], v[190:193], v[0:3]
	ds_read_b128 v[190:193], v183 offset:41536
	v_mfma_f32_16x16x32_bf16 v[12:15], v[246:249], v[194:197], v[12:15]
	ds_read_b128 v[194:197], v183 offset:43840
	s_waitcnt vmcnt(7)
; DI f32x4 mfma16(bf16x8 a, bf16x8 b, f32x4 c) { return __builtin_amdgcn_mfma_f32_16x16x32_bf16(a, b, c, 0, 0, 0); }
; template <int MI, int NJ, bool SWAP, class AP, class BP>
; DI void gemm_main(f32x4 (&acc)[MI][NJ], const AP& ap, int a_kstep, const BP& bp, int b_kstep, int nk, bf16_t* smem) {
;     ...
;   auto gload = [&](int kt) {
;     const bf16_t* ab = ap.base + (size_t)kt * a_kstep; const bf16_t* bb = bp.base + (size_t)kt * b_kstep;
; #pragma unroll
;     for (int i = 0; i < CA; ++i) ra[i] = *(const u32x4*)(ab + pa[i]);
; #pragma unroll
;     for (int i = 0; i < CB; ++i) rb[i] = *(const u32x4*)(bb + pb[i]);
;   };
;   auto sstore = [&](int buf) {
;     bf16_t* As = smem + buf * L::STAGE; bf16_t* Bs = As + L::A_ELEMS;
; #pragma unroll
;     for (int i = 0; i < CA; ++i) { const int c = tid + NTHR * i; *(u32x4*)(As + (c >> 3) * LDT + (c & 7) * 8) = oka[i] ? ra[i] : (u32x4){0u, 0u, 0u, 0u}; }
; #pragma unroll
;     for (int i = 0; i < CB; ++i) { const int c = tid + NTHR * i; *(u32x4*)(Bs + (c >> 3) * LDT + (c & 7) * 8) = rb[i]; }
;     ...
;   for (int kt = 0; kt < nk; ++kt) {
;     const int buf = kt & 1;
;     sstore(buf ^ 1);
;     gload(kt + 2 < nk ? kt + 2 : nk - 1);
;     __builtin_amdgcn_sched_barrier(0);
;     const bf16_t* As = smem + buf * L::STAGE + (wm * 16 * MI + l15) * LDT + quad * 8;
;     const bf16_t* Bs = smem + buf * L::STAGE + L::A_ELEMS + (wn * 16 * NJ + l15) * LDT + quad * 8;
; #pragma unroll
;     for (int ks = 0; ks < 2; ++ks) {
;       if (MI * NJ >= 32 && ks == 1) asm volatile("" ::: "memory");
;       bf16x8 b[NJ];
; #pragma unroll
;       for (int j = 0; j < NJ; ++j) b[j] = *(const bf16x8*)(Bs + j * 16 * LDT + ks * 32);
; #pragma unroll
;       for (int i = 0; i < MI; ++i) {
;         const bf16x8 a = *(const bf16x8*)(As + i * 16 * LDT + ks * 32);
; #pragma unroll
;         for (int j = 0; j < NJ; ++j) acc[i][j] = SWAP ? mfma16(b[j], a, acc[i][j]) : mfma16(a, b[j], acc[i][j]);
;       }
;     }
;     __syncthreads();
;   }
	ds_write_b128 v250, v[144:147] offset:36864
	ds_read_b128 v[242:245], v182 offset:4672
	s_waitcnt lgkmcnt(5)
	v_mfma_f32_16x16x32_bf16 v[140:143], v[198:201], v[178:181], v[140:143]
	s_waitcnt lgkmcnt(4)
	v_mfma_f32_16x16x32_bf16 v[120:123], v[198:201], v[186:189], v[120:123]
	s_add_u32 s52, s2, s33
	s_addc_u32 s53, s3, 0
	v_lshl_add_u64 v[144:145], s[52:53], 0, v[162:163]
	s_nop 0
	global_load_dwordx4 v[144:147], v[144:145], off
	s_waitcnt lgkmcnt(3)
	v_mfma_f32_16x16x32_bf16 v[116:119], v[198:201], v[190:193], v[116:119]
	s_waitcnt lgkmcnt(2)
	v_mfma_f32_16x16x32_bf16 v[112:115], v[198:201], v[194:197], v[112:115]
	ds_read_b128 v[246:249], v182 offset:6976
	v_mfma_f32_16x16x32_bf16 v[108:111], v[202:205], v[178:181], v[108:111]
	v_mfma_f32_16x16x32_bf16 v[104:107], v[202:205], v[186:189], v[104:107]
	s_waitcnt vmcnt(7)
	ds_write_b128 v251, v[148:151] offset:36864
	v_mfma_f32_16x16x32_bf16 v[100:103], v[202:205], v[190:193], v[100:103]
	v_mfma_f32_16x16x32_bf16 v[96:99], v[202:205], v[194:197], v[96:99]
	v_lshl_add_u64 v[148:149], s[52:53], 0, v[164:165]
	s_nop 0
	global_load_dwordx4 v[148:151], v[148:149], off
	ds_read_b128 v[198:201], v182 offset:9280
	s_waitcnt lgkmcnt(3)
	v_mfma_f32_16x16x32_bf16 v[92:95], v[242:245], v[178:181], v[92:95]
	v_mfma_f32_16x16x32_bf16 v[88:91], v[242:245], v[186:189], v[88:91]
	v_mfma_f32_16x16x32_bf16 v[84:87], v[242:245], v[190:193], v[84:87]
	v_mfma_f32_16x16x32_bf16 v[80:83], v[242:245], v[194:197], v[80:83]
	ds_read_b128 v[202:205], v182 offset:11584
	s_waitcnt lgkmcnt(3)
	v_mfma_f32_16x16x32_bf16 v[76:79], v[246:249], v[178:181], v[76:79]
	s_waitcnt vmcnt(7)
	ds_write_b128 v252, v[152:155] offset:36864
	v_mfma_f32_16x16x32_bf16 v[72:75], v[246:249], v[186:189], v[72:75]
	v_mfma_f32_16x16x32_bf16 v[68:71], v[246:249], v[190:193], v[68:71]
	v_lshl_add_u64 v[152:153], s[52:53], 0, v[166:167]
	s_nop 0
	global_load_dwordx4 v[152:155], v[152:153], off
	v_mfma_f32_16x16x32_bf16 v[64:67], v[246:249], v[194:197], v[64:67]
	ds_read_b128 v[242:245], v182 offset:13888
	s_waitcnt lgkmcnt(3)
	v_mfma_f32_16x16x32_bf16 v[60:63], v[198:201], v[178:181], v[60:63]
	v_mfma_f32_16x16x32_bf16 v[56:59], v[198:201], v[186:189], v[56:59]
	v_mfma_f32_16x16x32_bf16 v[52:55], v[198:201], v[190:193], v[52:55]
	v_mfma_f32_16x16x32_bf16 v[48:51], v[198:201], v[194:197], v[48:51]
	s_waitcnt vmcnt(7)
	ds_write_b128 v253, v[156:159] offset:36864
	ds_read_b128 v[246:249], v182 offset:16192
	s_waitcnt lgkmcnt(4)
	v_mfma_f32_16x16x32_bf16 v[44:47], v[202:205], v[178:181], v[44:47]
	v_mfma_f32_16x16x32_bf16 v[40:43], v[202:205], v[186:189], v[40:43]
	v_lshl_add_u64 v[156:157], s[52:53], 0, v[168:169]
	s_nop 0
	global_load_dwordx4 v[156:159], v[156:157], off
	v_mfma_f32_16x16x32_bf16 v[36:39], v[202:205], v[190:193], v[36:39]
	v_mfma_f32_16x16x32_bf16 v[32:35], v[202:205], v[194:197], v[32:35]
	s_add_i32 s5, s5, 1
	s_and_b32 s98, s5, 1
	s_mul_i32 s98, s98, 0x12000
	v_add3_u32 v182, s98, v176, v177
	v_add3_u32 v183, s98, v171, v177
	s_cmp_lg_u32 s5, 4
	s_waitcnt lgkmcnt(0)
	s_barrier
	s_cbranch_scc0 .Lgm4_exit
	ds_read_b128 v[198:201], v182
	ds_read_b128 v[202:205], v182 offset:2304
	v_mfma_f32_16x16x32_bf16 v[28:31], v[242:245], v[178:181], v[28:31]
	v_mfma_f32_16x16x32_bf16 v[8:11], v[246:249], v[178:181], v[8:11]
	ds_read_b128 v[178:181], v183 offset:36864
	v_mfma_f32_16x16x32_bf16 v[24:27], v[242:245], v[186:189], v[24:27]
	v_mfma_f32_16x16x32_bf16 v[4:7], v[246:249], v[186:189], v[4:7]
	ds_read_b128 v[186:189], v183 offset:39168
	v_mfma_f32_16x16x32_bf16 v[20:23], v[242:245], v[190:193], v[20:23]
	v_mfma_f32_16x16x32_bf16 v[0:3], v[246:249], v[190:193], v[0:3]
	ds_read_b128 v[190:193], v183 offset:41472
	v_mfma_f32_16x16x32_bf16 v[16:19], v[242:245], v[194:197], v[16:19]
	v_mfma_f32_16x16x32_bf16 v[12:15], v[246:249], v[194:197], v[12:15]
	ds_read_b128 v[194:197], v183 offset:43776
	s_branch .Lgm4_main

; DI f32x4 mfma16(bf16x8 a, bf16x8 b, f32x4 c) { return __builtin_amdgcn_mfma_f32_16x16x32_bf16(a, b, c, 0, 0, 0); }
; template <int MI, int NJ, bool SWAP, class AP, class BP>
; DI void gemm_main(f32x4 (&acc)[MI][NJ], const AP& ap, int a_kstep, const BP& bp, int b_kstep, int nk, bf16_t* smem) {
;     ...
;   auto gload = [&](int kt) {
;     const bf16_t* ab = ap.base + (size_t)kt * a_kstep; const bf16_t* bb = bp.base + (size_t)kt * b_kstep;
; #pragma unroll
;     for (int i = 0; i < CA; ++i) ra[i] = *(const u32x4*)(ab + pa[i]);
; #pragma unroll
;     for (int i = 0; i < CB; ++i) rb[i] = *(const u32x4*)(bb + pb[i]);
;   };
;   auto sstore = [&](int buf) {
;     bf16_t* As = smem + buf * L::STAGE; bf16_t* Bs = As + L::A_ELEMS;
; #pragma unroll
;     for (int i = 0; i < CA; ++i) { const int c = tid + NTHR * i; *(u32x4*)(As + (c >> 3) * LDT + (c & 7) * 8) = oka[i] ? ra[i] : (u32x4){0u, 0u, 0u, 0u}; }
; #pragma unroll
;     for (int i = 0; i < CB; ++i) { const int c = tid + NTHR * i; *(u32x4*)(Bs + (c >> 3) * LDT + (c & 7) * 8) = rb[i]; }
;     ...
;   for (int kt = 0; kt < nk; ++kt) {
;     const int buf = kt & 1;
;     sstore(buf ^ 1);
;     gload(kt + 2 < nk ? kt + 2 : nk - 1);
;     __builtin_amdgcn_sched_barrier(0);
;     const bf16_t* As = smem + buf * L::STAGE + (wm * 16 * MI + l15) * LDT + quad * 8;
;     const bf16_t* Bs = smem + buf * L::STAGE + L::A_ELEMS + (wn * 16 * NJ + l15) * LDT + quad * 8;
; #pragma unroll
;     for (int ks = 0; ks < 2; ++ks) {
;       if (MI * NJ >= 32 && ks == 1) asm volatile("" ::: "memory");
;       bf16x8 b[NJ];
; #pragma unroll
;       for (int j = 0; j < NJ; ++j) b[j] = *(const bf16x8*)(Bs + j * 16 * LDT + ks * 32);
; #pragma unroll
;       for (int i = 0; i < MI; ++i) {
;         const bf16x8 a = *(const bf16x8*)(As + i * 16 * LDT + ks * 32);
; #pragma unroll
;         for (int j = 0; j < NJ; ++j) acc[i][j] = SWAP ? mfma16(b[j], a, acc[i][j]) : mfma16(a, b[j], acc[i][j]);
;       }
;     }
.Lgm5_main:
	ds_read_b128 v[242:245], v177 offset:4608
	s_waitcnt lgkmcnt(4)
	v_mfma_f32_16x16x32_bf16 v[156:159], v[178:181], v[194:197], v[156:159]
	s_waitcnt lgkmcnt(3)
	v_mfma_f32_16x16x32_bf16 v[152:155], v[182:185], v[194:197], v[152:155]
	s_waitcnt lgkmcnt(2)
	v_mfma_f32_16x16x32_bf16 v[148:151], v[186:189], v[194:197], v[148:151]
	s_waitcnt lgkmcnt(1)
	v_mfma_f32_16x16x32_bf16 v[128:131], v[190:193], v[194:197], v[128:131]
	ds_read_b128 v[246:249], v177 offset:6912
	v_mfma_f32_16x16x32_bf16 v[108:111], v[178:181], v[198:201], v[108:111]
	v_mfma_f32_16x16x32_bf16 v[104:107], v[182:185], v[198:201], v[104:107]
	s_and_b32 s15, s1, 1
	s_min_u32 s16, s1, 13
	s_xor_b32 s17, s15, 1
	s_mul_i32 s17, s17, 0x12000
	v_add3_u32 v250, s17, v172, v170
	s_waitcnt vmcnt(7)
	ds_write_b128 v250, v[112:115]
	v_mfma_f32_16x16x32_bf16 v[100:103], v[186:189], v[198:201], v[100:103]
	v_mfma_f32_16x16x32_bf16 v[96:99], v[190:193], v[198:201], v[96:99]
	s_lshl_b32 s26, s16, 7
	s_add_u32 s16, s2, s26
	v_add3_u32 v251, s17, v174, v170
	v_add3_u32 v252, s17, v175, v170
	v_add3_u32 v253, s17, v176, v170
	s_addc_u32 s17, s3, 0
	v_lshl_add_u64 v[112:113], s[16:17], 0, v[162:163]
	s_nop 0
	global_load_dwordx4 v[112:115], v[112:113], off offset:256
	ds_read_b128 v[194:197], v177 offset:9216
	s_waitcnt lgkmcnt(3)
	v_mfma_f32_16x16x32_bf16 v[92:95], v[178:181], v[242:245], v[92:95]
	v_mfma_f32_16x16x32_bf16 v[88:91], v[182:185], v[242:245], v[88:91]
	v_mfma_f32_16x16x32_bf16 v[84:87], v[186:189], v[242:245], v[84:87]
	v_mfma_f32_16x16x32_bf16 v[80:83], v[190:193], v[242:245], v[80:83]
	s_waitcnt vmcnt(7)
	ds_write_b128 v251, v[116:119]
	ds_read_b128 v[198:201], v177 offset:11520
	s_waitcnt lgkmcnt(4)
	v_mfma_f32_16x16x32_bf16 v[76:79], v[178:181], v[246:249], v[76:79]
	v_mfma_f32_16x16x32_bf16 v[72:75], v[182:185], v[246:249], v[72:75]
	v_lshl_add_u64 v[116:117], s[16:17], 0, v[164:165]
	s_nop 0
	global_load_dwordx4 v[116:119], v[116:117], off offset:256
	v_mfma_f32_16x16x32_bf16 v[68:71], v[186:189], v[246:249], v[68:71]
	v_mfma_f32_16x16x32_bf16 v[64:67], v[190:193], v[246:249], v[64:67]
	ds_read_b128 v[242:245], v177 offset:13824
	s_waitcnt lgkmcnt(3)
	v_mfma_f32_16x16x32_bf16 v[60:63], v[178:181], v[194:197], v[60:63]
	v_mfma_f32_16x16x32_bf16 v[56:59], v[182:185], v[194:197], v[56:59]
	v_mfma_f32_16x16x32_bf16 v[52:55], v[186:189], v[194:197], v[52:55]
	s_waitcnt vmcnt(7)
	ds_write_b128 v252, v[120:123]
	v_mfma_f32_16x16x32_bf16 v[48:51], v[190:193], v[194:197], v[48:51]
	ds_read_b128 v[246:249], v177 offset:16128
	s_waitcnt lgkmcnt(3)
	v_mfma_f32_16x16x32_bf16 v[44:47], v[178:181], v[198:201], v[44:47]
	v_lshl_add_u64 v[120:121], s[16:17], 0, v[166:167]
	s_nop 0
	global_load_dwordx4 v[120:123], v[120:121], off offset:256
	v_mfma_f32_16x16x32_bf16 v[40:43], v[182:185], v[198:201], v[40:43]
	v_mfma_f32_16x16x32_bf16 v[36:39], v[186:189], v[198:201], v[36:39]
	v_mfma_f32_16x16x32_bf16 v[32:35], v[190:193], v[198:201], v[32:35]
	ds_read_b128 v[194:197], v177 offset:64
	s_waitcnt lgkmcnt(3)
	v_mfma_f32_16x16x32_bf16 v[28:31], v[178:181], v[242:245], v[28:31]
	s_waitcnt vmcnt(7)
	ds_write_b128 v253, v[124:127]
	v_mfma_f32_16x16x32_bf16 v[24:27], v[182:185], v[242:245], v[24:27]
	v_mfma_f32_16x16x32_bf16 v[20:23], v[186:189], v[242:245], v[20:23]
	v_lshl_add_u64 v[124:125], s[16:17], 0, v[168:169]
	s_nop 0
	global_load_dwordx4 v[124:127], v[124:125], off offset:256
	v_mfma_f32_16x16x32_bf16 v[16:19], v[190:193], v[242:245], v[16:19]
	ds_read_b128 v[198:201], v177 offset:2368
	s_waitcnt lgkmcnt(3)
	v_mfma_f32_16x16x32_bf16 v[8:11], v[178:181], v[246:249], v[8:11]
	ds_read_b128 v[178:181], v202 offset:36928
	v_mfma_f32_16x16x32_bf16 v[4:7], v[182:185], v[246:249], v[4:7]
	ds_read_b128 v[182:185], v202 offset:39232
	v_mfma_f32_16x16x32_bf16 v[0:3], v[186:189], v[246:249], v[0:3]
	ds_read_b128 v[186:189], v202 offset:41536
	v_mfma_f32_16x16x32_bf16 v[12:15], v[190:193], v[246:249], v[12:15]
	ds_read_b128 v[190:193], v202 offset:43840
	s_waitcnt vmcnt(7)
; DI f32x4 mfma16(bf16x8 a, bf16x8 b, f32x4 c) { return __builtin_amdgcn_mfma_f32_16x16x32_bf16(a, b, c, 0, 0, 0); }
; template <int MI, int NJ, bool SWAP, class AP, class BP>
; DI void gemm_main(f32x4 (&acc)[MI][NJ], const AP& ap, int a_kstep, const BP& bp, int b_kstep, int nk, bf16_t* smem) {
;     ...
;   auto gload = [&](int kt) {
;     const bf16_t* ab = ap.base + (size_t)kt * a_kstep; const bf16_t* bb = bp.base + (size_t)kt * b_kstep;
; #pragma unroll
;     for (int i = 0; i < CA; ++i) ra[i] = *(const u32x4*)(ab + pa[i]);
; #pragma unroll
;     for (int i = 0; i < CB; ++i) rb[i] = *(const u32x4*)(bb + pb[i]);
;   };
;   auto sstore = [&](int buf) {
;     bf16_t* As = smem + buf * L::STAGE; bf16_t* Bs = As + L::A_ELEMS;
; #pragma unroll
;     for (int i = 0; i < CA; ++i) { const int c = tid + NTHR * i; *(u32x4*)(As + (c >> 3) * LDT + (c & 7) * 8) = oka[i] ? ra[i] : (u32x4){0u, 0u, 0u, 0u}; }
; #pragma unroll
;     for (int i = 0; i < CB; ++i) { const int c = tid + NTHR * i; *(u32x4*)(Bs + (c >> 3) * LDT + (c & 7) * 8) = rb[i]; }
;     ...
;   for (int kt = 0; kt < nk; ++kt) {
;     const int buf = kt & 1;
;     sstore(buf ^ 1);
;     gload(kt + 2 < nk ? kt + 2 : nk - 1);
;     __builtin_amdgcn_sched_barrier(0);
;     const bf16_t* As = smem + buf * L::STAGE + (wm * 16 * MI + l15) * LDT + quad * 8;
;     const bf16_t* Bs = smem + buf * L::STAGE + L::A_ELEMS + (wn * 16 * NJ + l15) * LDT + quad * 8;
; #pragma unroll
;     for (int ks = 0; ks < 2; ++ks) {
;       if (MI * NJ >= 32 && ks == 1) asm volatile("" ::: "memory");
;       bf16x8 b[NJ];
; #pragma unroll
;       for (int j = 0; j < NJ; ++j) b[j] = *(const bf16x8*)(Bs + j * 16 * LDT + ks * 32);
; #pragma unroll
;       for (int i = 0; i < MI; ++i) {
;         const bf16x8 a = *(const bf16x8*)(As + i * 16 * LDT + ks * 32);
; #pragma unroll
;         for (int j = 0; j < NJ; ++j) acc[i][j] = SWAP ? mfma16(b[j], a, acc[i][j]) : mfma16(a, b[j], acc[i][j]);
;       }
;     }
;     __syncthreads();
;   }
	ds_write_b128 v250, v[132:135] offset:36864
	ds_read_b128 v[242:245], v177 offset:4672
	s_waitcnt lgkmcnt(5)
	v_mfma_f32_16x16x32_bf16 v[156:159], v[178:181], v[194:197], v[156:159]
	s_waitcnt lgkmcnt(4)
	v_mfma_f32_16x16x32_bf16 v[152:155], v[182:185], v[194:197], v[152:155]
	s_add_u32 s16, s12, s26
	s_addc_u32 s17, s13, 0
	v_lshl_add_u64 v[132:133], s[16:17], 0, v[162:163]
	s_nop 0
	global_load_dwordx4 v[132:135], v[132:133], off offset:256
	s_waitcnt lgkmcnt(3)
	v_mfma_f32_16x16x32_bf16 v[148:151], v[186:189], v[194:197], v[148:151]
	s_waitcnt lgkmcnt(2)
	v_mfma_f32_16x16x32_bf16 v[128:131], v[190:193], v[194:197], v[128:131]
	ds_read_b128 v[246:249], v177 offset:6976
	v_mfma_f32_16x16x32_bf16 v[108:111], v[178:181], v[198:201], v[108:111]
	v_mfma_f32_16x16x32_bf16 v[104:107], v[182:185], v[198:201], v[104:107]
	s_waitcnt vmcnt(7)
	ds_write_b128 v251, v[136:139] offset:36864
	v_mfma_f32_16x16x32_bf16 v[100:103], v[186:189], v[198:201], v[100:103]
	v_mfma_f32_16x16x32_bf16 v[96:99], v[190:193], v[198:201], v[96:99]
	v_lshl_add_u64 v[136:137], s[16:17], 0, v[164:165]
	s_nop 0
	global_load_dwordx4 v[136:139], v[136:137], off offset:256
	ds_read_b128 v[194:197], v177 offset:9280
	s_waitcnt lgkmcnt(3)
	v_mfma_f32_16x16x32_bf16 v[92:95], v[178:181], v[242:245], v[92:95]
	v_mfma_f32_16x16x32_bf16 v[88:91], v[182:185], v[242:245], v[88:91]
	v_mfma_f32_16x16x32_bf16 v[84:87], v[186:189], v[242:245], v[84:87]
	v_mfma_f32_16x16x32_bf16 v[80:83], v[190:193], v[242:245], v[80:83]
	ds_read_b128 v[198:201], v177 offset:11584
	s_waitcnt lgkmcnt(3)
	v_mfma_f32_16x16x32_bf16 v[76:79], v[178:181], v[246:249], v[76:79]
	s_waitcnt vmcnt(7)
	ds_write_b128 v252, v[140:143] offset:36864
	v_mfma_f32_16x16x32_bf16 v[72:75], v[182:185], v[246:249], v[72:75]
	v_mfma_f32_16x16x32_bf16 v[68:71], v[186:189], v[246:249], v[68:71]
	v_lshl_add_u64 v[140:141], s[16:17], 0, v[166:167]
	s_nop 0
	global_load_dwordx4 v[140:143], v[140:141], off offset:256
	v_mfma_f32_16x16x32_bf16 v[64:67], v[190:193], v[246:249], v[64:67]
	ds_read_b128 v[242:245], v177 offset:13888
	s_waitcnt lgkmcnt(3)
	v_mfma_f32_16x16x32_bf16 v[60:63], v[178:181], v[194:197], v[60:63]
	v_mfma_f32_16x16x32_bf16 v[56:59], v[182:185], v[194:197], v[56:59]
	v_mfma_f32_16x16x32_bf16 v[52:55], v[186:189], v[194:197], v[52:55]
	v_mfma_f32_16x16x32_bf16 v[48:51], v[190:193], v[194:197], v[48:51]
	s_waitcnt vmcnt(7)
	ds_write_b128 v253, v[144:147] offset:36864
	ds_read_b128 v[246:249], v177 offset:16192
	s_waitcnt lgkmcnt(4)
	v_mfma_f32_16x16x32_bf16 v[44:47], v[178:181], v[198:201], v[44:47]
	v_mfma_f32_16x16x32_bf16 v[40:43], v[182:185], v[198:201], v[40:43]
	v_lshl_add_u64 v[144:145], s[16:17], 0, v[168:169]
	s_nop 0
	global_load_dwordx4 v[144:147], v[144:145], off offset:256
	v_mfma_f32_16x16x32_bf16 v[36:39], v[186:189], v[198:201], v[36:39]
	v_mfma_f32_16x16x32_bf16 v[32:35], v[190:193], v[198:201], v[32:35]
	s_add_i32 s1, s1, 1
	s_and_b32 s98, s1, 1
	s_mul_i32 s98, s98, 0x12000
	v_add3_u32 v202, s98, v160, v173
	v_add3_u32 v177, s98, v171, v173
	s_cmp_lg_u32 s1, 16
	s_waitcnt lgkmcnt(0)
	s_barrier
	s_cbranch_scc0 .Lgm5_exit
	ds_read_b128 v[194:197], v177
	ds_read_b128 v[198:201], v177 offset:2304
	v_mfma_f32_16x16x32_bf16 v[28:31], v[178:181], v[242:245], v[28:31]
	v_mfma_f32_16x16x32_bf16 v[8:11], v[178:181], v[246:249], v[8:11]
	ds_read_b128 v[178:181], v202 offset:36864
	v_mfma_f32_16x16x32_bf16 v[24:27], v[182:185], v[242:245], v[24:27]
	v_mfma_f32_16x16x32_bf16 v[4:7], v[182:185], v[246:249], v[4:7]
	ds_read_b128 v[182:185], v202 offset:39168
	v_mfma_f32_16x16x32_bf16 v[20:23], v[186:189], v[242:245], v[20:23]
	v_mfma_f32_16x16x32_bf16 v[0:3], v[186:189], v[246:249], v[0:3]
	ds_read_b128 v[186:189], v202 offset:41472
	v_mfma_f32_16x16x32_bf16 v[16:19], v[190:193], v[242:245], v[16:19]
	v_mfma_f32_16x16x32_bf16 v[12:15], v[190:193], v[246:249], v[12:15]
	ds_read_b128 v[190:193], v202 offset:43776
	s_branch .Lgm5_main

; DI f32x4 mfma16(bf16x8 a, bf16x8 b, f32x4 c) { return __builtin_amdgcn_mfma_f32_16x16x32_bf16(a, b, c, 0, 0, 0); }
; template <int MI, int NJ, bool SWAP, class AP, class BP>
; DI void gemm_main(f32x4 (&acc)[MI][NJ], const AP& ap, int a_kstep, const BP& bp, int b_kstep, int nk, bf16_t* smem) {
;     ...
;   auto gload = [&](int kt) {
;     const bf16_t* ab = ap.base + (size_t)kt * a_kstep; const bf16_t* bb = bp.base + (size_t)kt * b_kstep;
; #pragma unroll
;     for (int i = 0; i < CA; ++i) ra[i] = *(const u32x4*)(ab + pa[i]);
; #pragma unroll
;     for (int i = 0; i < CB; ++i) rb[i] = *(const u32x4*)(bb + pb[i]);
;   };
;   auto sstore = [&](int buf) {
;     bf16_t* As = smem + buf * L::STAGE; bf16_t* Bs = As + L::A_ELEMS;
; #pragma unroll
;     for (int i = 0; i < CA; ++i) { const int c = tid + NTHR * i; *(u32x4*)(As + (c >> 3) * LDT + (c & 7) * 8) = oka[i] ? ra[i] : (u32x4){0u, 0u, 0u, 0u}; }
; #pragma unroll
;     for (int i = 0; i < CB; ++i) { const int c = tid + NTHR * i; *(u32x4*)(Bs + (c >> 3) * LDT + (c & 7) * 8) = rb[i]; }
;     ...
;   for (int kt = 0; kt < nk; ++kt) {
;     const int buf = kt & 1;
;     sstore(buf ^ 1);
;     gload(kt + 2 < nk ? kt + 2 : nk - 1);
;     __builtin_amdgcn_sched_barrier(0);
;     const bf16_t* As = smem + buf * L::STAGE + (wm * 16 * MI + l15) * LDT + quad * 8;
;     const bf16_t* Bs = smem + buf * L::STAGE + L::A_ELEMS + (wn * 16 * NJ + l15) * LDT + quad * 8;
; #pragma unroll
;     for (int ks = 0; ks < 2; ++ks) {
;       if (MI * NJ >= 32 && ks == 1) asm volatile("" ::: "memory");
;       bf16x8 b[NJ];
; #pragma unroll
;       for (int j = 0; j < NJ; ++j) b[j] = *(const bf16x8*)(Bs + j * 16 * LDT + ks * 32);
; #pragma unroll
;       for (int i = 0; i < MI; ++i) {
;         const bf16x8 a = *(const bf16x8*)(As + i * 16 * LDT + ks * 32);
; #pragma unroll
;         for (int j = 0; j < NJ; ++j) acc[i][j] = SWAP ? mfma16(b[j], a, acc[i][j]) : mfma16(a, b[j], acc[i][j]);
;       }
;     }
.Lgm6_main:
	ds_read_b128 v[246:249], v181 offset:4608
	s_waitcnt lgkmcnt(4)
	v_mfma_f32_16x16x32_bf16 v[156:159], v[182:185], v[198:201], v[156:159]
	s_waitcnt lgkmcnt(3)
	v_mfma_f32_16x16x32_bf16 v[152:155], v[186:189], v[198:201], v[152:155]
	s_waitcnt lgkmcnt(2)
	v_mfma_f32_16x16x32_bf16 v[148:151], v[190:193], v[198:201], v[148:151]
	s_waitcnt lgkmcnt(1)
	v_mfma_f32_16x16x32_bf16 v[144:147], v[194:197], v[198:201], v[144:147]
	ds_read_b128 v[250:253], v181 offset:6912
	v_mfma_f32_16x16x32_bf16 v[108:111], v[182:185], v[242:245], v[108:111]
	v_mfma_f32_16x16x32_bf16 v[104:107], v[186:189], v[242:245], v[104:107]
	s_waitcnt vmcnt(7)
	v_cndmask_b32_e32 v139, 0, v139, vcc
	v_cndmask_b32_e32 v138, 0, v138, vcc
	v_cndmask_b32_e32 v137, 0, v137, vcc
	v_cndmask_b32_e32 v136, 0, v136, vcc
	s_and_b32 s31, s30, 1
	s_xor_b32 s33, s31, 1
	s_mul_i32 s33, s33, 0x12000
	v_add3_u32 v254, s33, v172, v169
	ds_write_b128 v254, v[136:139]
	v_mfma_f32_16x16x32_bf16 v[100:103], v[190:193], v[242:245], v[100:103]
	v_mfma_f32_16x16x32_bf16 v[96:99], v[194:197], v[242:245], v[96:99]
	v_add3_u32 v238, s33, v173, v169
	v_add3_u32 v239, s33, v174, v169
	v_add3_u32 v255, s33, v175, v169
	s_min_u32 s33, s30, 13
	s_lshl_b32 s33, s33, 7
	s_add_u32 s34, s12, s33
	s_addc_u32 s35, s13, 0
	s_nop 0
	global_load_dwordx4 v[136:139], v176, s[34:35] offset:256
	ds_read_b128 v[198:201], v181 offset:9216
	s_waitcnt lgkmcnt(3)
	v_mfma_f32_16x16x32_bf16 v[92:95], v[182:185], v[246:249], v[92:95]
	v_mfma_f32_16x16x32_bf16 v[88:91], v[186:189], v[246:249], v[88:91]
	v_mfma_f32_16x16x32_bf16 v[84:87], v[190:193], v[246:249], v[84:87]
	v_mfma_f32_16x16x32_bf16 v[80:83], v[194:197], v[246:249], v[80:83]
	s_waitcnt vmcnt(7)
	v_cndmask_b32_e64 v127, 0, v127, s[0:1]
	v_cndmask_b32_e64 v126, 0, v126, s[0:1]
	v_cndmask_b32_e64 v125, 0, v125, s[0:1]
	v_cndmask_b32_e64 v124, 0, v124, s[0:1]
	ds_write_b128 v238, v[124:127]
	ds_read_b128 v[242:245], v181 offset:11520
	s_waitcnt lgkmcnt(4)
	v_mfma_f32_16x16x32_bf16 v[76:79], v[182:185], v[250:253], v[76:79]
	v_mfma_f32_16x16x32_bf16 v[72:75], v[186:189], v[250:253], v[72:75]
	s_nop 0
	global_load_dwordx4 v[124:127], v177, s[34:35] offset:256
	v_mfma_f32_16x16x32_bf16 v[68:71], v[190:193], v[250:253], v[68:71]
	v_mfma_f32_16x16x32_bf16 v[64:67], v[194:197], v[250:253], v[64:67]
	ds_read_b128 v[246:249], v181 offset:13824
	s_waitcnt lgkmcnt(3)
	v_mfma_f32_16x16x32_bf16 v[60:63], v[182:185], v[198:201], v[60:63]
	v_mfma_f32_16x16x32_bf16 v[56:59], v[186:189], v[198:201], v[56:59]
	v_mfma_f32_16x16x32_bf16 v[52:55], v[190:193], v[198:201], v[52:55]
	s_waitcnt vmcnt(7)
	v_cndmask_b32_e64 v115, 0, v115, s[2:3]
	v_cndmask_b32_e64 v114, 0, v114, s[2:3]
	v_cndmask_b32_e64 v113, 0, v113, s[2:3]
	v_cndmask_b32_e64 v112, 0, v112, s[2:3]
	ds_write_b128 v239, v[112:115]
	v_mfma_f32_16x16x32_bf16 v[48:51], v[194:197], v[198:201], v[48:51]
	ds_read_b128 v[250:253], v181 offset:16128
	s_waitcnt lgkmcnt(3)
	v_mfma_f32_16x16x32_bf16 v[44:47], v[182:185], v[242:245], v[44:47]
	v_mfma_f32_16x16x32_bf16 v[40:43], v[186:189], v[242:245], v[40:43]
	v_mfma_f32_16x16x32_bf16 v[36:39], v[190:193], v[242:245], v[36:39]
	v_mfma_f32_16x16x32_bf16 v[32:35], v[194:197], v[242:245], v[32:35]
	ds_read_b128 v[198:201], v181 offset:64
	s_waitcnt lgkmcnt(3)
	v_mfma_f32_16x16x32_bf16 v[28:31], v[182:185], v[246:249], v[28:31]
	s_waitcnt vmcnt(6)
	v_cndmask_b32_e64 v112, 0, v116, s[4:5]
	v_cndmask_b32_e64 v115, 0, v119, s[4:5]
	v_cndmask_b32_e64 v114, 0, v118, s[4:5]
	v_cndmask_b32_e64 v113, 0, v117, s[4:5]
	ds_write_b128 v255, v[112:115]
	v_mfma_f32_16x16x32_bf16 v[24:27], v[186:189], v[246:249], v[24:27]
	v_mfma_f32_16x16x32_bf16 v[20:23], v[190:193], v[246:249], v[20:23]
	s_nop 0
	global_load_dwordx4 v[112:115], v178, s[34:35] offset:256
	s_nop 0
	global_load_dwordx4 v[116:119], v179, s[34:35] offset:256
	v_mfma_f32_16x16x32_bf16 v[16:19], v[194:197], v[246:249], v[16:19]
	ds_read_b128 v[242:245], v181 offset:2368
	s_waitcnt lgkmcnt(3)
; DI f32x4 mfma16(bf16x8 a, bf16x8 b, f32x4 c) { return __builtin_amdgcn_mfma_f32_16x16x32_bf16(a, b, c, 0, 0, 0); }
; template <int MI, int NJ, bool SWAP, class AP, class BP>
; DI void gemm_main(f32x4 (&acc)[MI][NJ], const AP& ap, int a_kstep, const BP& bp, int b_kstep, int nk, bf16_t* smem) {
;     ...
;   auto gload = [&](int kt) {
;     const bf16_t* ab = ap.base + (size_t)kt * a_kstep; const bf16_t* bb = bp.base + (size_t)kt * b_kstep;
; #pragma unroll
;     for (int i = 0; i < CA; ++i) ra[i] = *(const u32x4*)(ab + pa[i]);
; #pragma unroll
;     for (int i = 0; i < CB; ++i) rb[i] = *(const u32x4*)(bb + pb[i]);
;   };
;   auto sstore = [&](int buf) {
;     bf16_t* As = smem + buf * L::STAGE; bf16_t* Bs = As + L::A_ELEMS;
; #pragma unroll
;     for (int i = 0; i < CA; ++i) { const int c = tid + NTHR * i; *(u32x4*)(As + (c >> 3) * LDT + (c & 7) * 8) = oka[i] ? ra[i] : (u32x4){0u, 0u, 0u, 0u}; }
; #pragma unroll
;     for (int i = 0; i < CB; ++i) { const int c = tid + NTHR * i; *(u32x4*)(Bs + (c >> 3) * LDT + (c & 7) * 8) = rb[i]; }
;     ...
;   for (int kt = 0; kt < nk; ++kt) {
;     const int buf = kt & 1;
;     sstore(buf ^ 1);
;     gload(kt + 2 < nk ? kt + 2 : nk - 1);
;     __builtin_amdgcn_sched_barrier(0);
;     const bf16_t* As = smem + buf * L::STAGE + (wm * 16 * MI + l15) * LDT + quad * 8;
;     const bf16_t* Bs = smem + buf * L::STAGE + L::A_ELEMS + (wn * 16 * NJ + l15) * LDT + quad * 8;
; #pragma unroll
;     for (int ks = 0; ks < 2; ++ks) {
;       if (MI * NJ >= 32 && ks == 1) asm volatile("" ::: "memory");
;       bf16x8 b[NJ];
; #pragma unroll
;       for (int j = 0; j < NJ; ++j) b[j] = *(const bf16x8*)(Bs + j * 16 * LDT + ks * 32);
; #pragma unroll
;       for (int i = 0; i < MI; ++i) {
;         const bf16x8 a = *(const bf16x8*)(As + i * 16 * LDT + ks * 32);
; #pragma unroll
;         for (int j = 0; j < NJ; ++j) acc[i][j] = SWAP ? mfma16(b[j], a, acc[i][j]) : mfma16(a, b[j], acc[i][j]);
;       }
;     }
;     __syncthreads();
;   }
	v_mfma_f32_16x16x32_bf16 v[12:15], v[182:185], v[250:253], v[12:15]
	ds_read_b128 v[182:185], v202 offset:36928
	v_mfma_f32_16x16x32_bf16 v[8:11], v[186:189], v[250:253], v[8:11]
	ds_read_b128 v[186:189], v202 offset:39232
	v_mfma_f32_16x16x32_bf16 v[4:7], v[190:193], v[250:253], v[4:7]
	ds_read_b128 v[190:193], v202 offset:41536
	v_mfma_f32_16x16x32_bf16 v[0:3], v[194:197], v[250:253], v[0:3]
	ds_read_b128 v[194:197], v202 offset:43840
	s_waitcnt vmcnt(7)
	ds_write_b128 v254, v[120:123] offset:36864
	ds_read_b128 v[246:249], v181 offset:4672
	s_waitcnt lgkmcnt(5)
	v_mfma_f32_16x16x32_bf16 v[156:159], v[182:185], v[198:201], v[156:159]
	s_waitcnt lgkmcnt(4)
	v_mfma_f32_16x16x32_bf16 v[152:155], v[186:189], v[198:201], v[152:155]
	s_add_u32 s34, s14, s33
	s_addc_u32 s35, s15, 0
	v_lshl_add_u64 v[120:121], v[160:161], 1, s[34:35]
	s_nop 0
	global_load_dwordx4 v[120:123], v[120:121], off offset:256
	s_waitcnt lgkmcnt(3)
	v_mfma_f32_16x16x32_bf16 v[148:151], v[190:193], v[198:201], v[148:151]
	s_waitcnt lgkmcnt(2)
	v_mfma_f32_16x16x32_bf16 v[144:147], v[194:197], v[198:201], v[144:147]
	ds_read_b128 v[250:253], v181 offset:6976
	v_mfma_f32_16x16x32_bf16 v[108:111], v[182:185], v[242:245], v[108:111]
	v_mfma_f32_16x16x32_bf16 v[104:107], v[186:189], v[242:245], v[104:107]
	s_waitcnt vmcnt(7)
	ds_write_b128 v238, v[128:131] offset:36864
	v_mfma_f32_16x16x32_bf16 v[100:103], v[190:193], v[242:245], v[100:103]
	v_mfma_f32_16x16x32_bf16 v[96:99], v[194:197], v[242:245], v[96:99]
	v_lshl_add_u64 v[128:129], v[162:163], 1, s[34:35]
	s_nop 0
	global_load_dwordx4 v[128:131], v[128:129], off offset:256
	ds_read_b128 v[198:201], v181 offset:9280
	s_waitcnt lgkmcnt(3)
	v_mfma_f32_16x16x32_bf16 v[92:95], v[182:185], v[246:249], v[92:95]
	v_mfma_f32_16x16x32_bf16 v[88:91], v[186:189], v[246:249], v[88:91]
	v_mfma_f32_16x16x32_bf16 v[84:87], v[190:193], v[246:249], v[84:87]
	v_mfma_f32_16x16x32_bf16 v[80:83], v[194:197], v[246:249], v[80:83]
	ds_read_b128 v[242:245], v181 offset:11584
	s_waitcnt lgkmcnt(3)
	v_mfma_f32_16x16x32_bf16 v[76:79], v[182:185], v[250:253], v[76:79]
	s_waitcnt vmcnt(7)
	ds_write_b128 v239, v[132:135] offset:36864
	v_mfma_f32_16x16x32_bf16 v[72:75], v[186:189], v[250:253], v[72:75]
	v_mfma_f32_16x16x32_bf16 v[68:71], v[190:193], v[250:253], v[68:71]
	v_lshl_add_u64 v[132:133], v[164:165], 1, s[34:35]
	s_nop 0
	global_load_dwordx4 v[132:135], v[132:133], off offset:256
	v_mfma_f32_16x16x32_bf16 v[64:67], v[194:197], v[250:253], v[64:67]
	ds_read_b128 v[246:249], v181 offset:13888
	s_waitcnt lgkmcnt(3)
	v_mfma_f32_16x16x32_bf16 v[60:63], v[182:185], v[198:201], v[60:63]
	v_mfma_f32_16x16x32_bf16 v[56:59], v[186:189], v[198:201], v[56:59]
	v_mfma_f32_16x16x32_bf16 v[52:55], v[190:193], v[198:201], v[52:55]
	v_mfma_f32_16x16x32_bf16 v[48:51], v[194:197], v[198:201], v[48:51]
	s_waitcnt vmcnt(7)
	ds_write_b128 v255, v[140:143] offset:36864
	ds_read_b128 v[250:253], v181 offset:16192
	s_waitcnt lgkmcnt(4)
	v_mfma_f32_16x16x32_bf16 v[44:47], v[182:185], v[242:245], v[44:47]
	v_mfma_f32_16x16x32_bf16 v[40:43], v[186:189], v[242:245], v[40:43]
	v_lshl_add_u64 v[140:141], v[166:167], 1, s[34:35]
	s_nop 0
	global_load_dwordx4 v[140:143], v[140:141], off offset:256
	v_mfma_f32_16x16x32_bf16 v[36:39], v[190:193], v[242:245], v[36:39]
	v_mfma_f32_16x16x32_bf16 v[32:35], v[194:197], v[242:245], v[32:35]
	s_add_i32 s30, s30, 1
	s_and_b32 s98, s30, 1
	s_mul_i32 s98, s98, 0x12000
	v_add3_u32 v181, s98, v170, v180
	v_add3_u32 v202, s98, v171, v180
	s_cmp_lg_u32 s30, 16
	s_waitcnt lgkmcnt(0)
	s_barrier
	s_cbranch_scc0 .Lgm6_exit
	ds_read_b128 v[198:201], v181
	ds_read_b128 v[242:245], v181 offset:2304
	v_mfma_f32_16x16x32_bf16 v[28:31], v[182:185], v[246:249], v[28:31]
	v_mfma_f32_16x16x32_bf16 v[12:15], v[182:185], v[250:253], v[12:15]
	ds_read_b128 v[182:185], v202 offset:36864
	v_mfma_f32_16x16x32_bf16 v[24:27], v[186:189], v[246:249], v[24:27]
	v_mfma_f32_16x16x32_bf16 v[8:11], v[186:189], v[250:253], v[8:11]
	ds_read_b128 v[186:189], v202 offset:39168
	v_mfma_f32_16x16x32_bf16 v[20:23], v[190:193], v[246:249], v[20:23]
	v_mfma_f32_16x16x32_bf16 v[4:7], v[190:193], v[250:253], v[4:7]
	ds_read_b128 v[190:193], v202 offset:41472
	v_mfma_f32_16x16x32_bf16 v[16:19], v[194:197], v[246:249], v[16:19]
	v_mfma_f32_16x16x32_bf16 v[0:3], v[194:197], v[250:253], v[0:3]
	ds_read_b128 v[194:197], v202 offset:43776
	s_branch .Lgm6_main

; DI f32x4 mfma16(bf16x8 a, bf16x8 b, f32x4 c) { return __builtin_amdgcn_mfma_f32_16x16x32_bf16(a, b, c, 0, 0, 0); }
; template <int MI, int NJ, bool SWAP, class AP, class BP>
; DI void gemm_main(f32x4 (&acc)[MI][NJ], const AP& ap, int a_kstep, const BP& bp, int b_kstep, int nk, bf16_t* smem) {
;     ...
;   auto gload = [&](int kt) {
;     const bf16_t* ab = ap.base + (size_t)kt * a_kstep; const bf16_t* bb = bp.base + (size_t)kt * b_kstep;
; #pragma unroll
;     for (int i = 0; i < CA; ++i) ra[i] = *(const u32x4*)(ab + pa[i]);
; #pragma unroll
;     for (int i = 0; i < CB; ++i) rb[i] = *(const u32x4*)(bb + pb[i]);
;   };
;   auto sstore = [&](int buf) {
;     bf16_t* As = smem + buf * L::STAGE; bf16_t* Bs = As + L::A_ELEMS;
; #pragma unroll
;     for (int i = 0; i < CA; ++i) { const int c = tid + NTHR * i; *(u32x4*)(As + (c >> 3) * LDT + (c & 7) * 8) = oka[i] ? ra[i] : (u32x4){0u, 0u, 0u, 0u}; }
; #pragma unroll
;     for (int i = 0; i < CB; ++i) { const int c = tid + NTHR * i; *(u32x4*)(Bs + (c >> 3) * LDT + (c & 7) * 8) = rb[i]; }
;     ...
;   for (int kt = 0; kt < nk; ++kt) {
;     const int buf = kt & 1;
;     sstore(buf ^ 1);
;     gload(kt + 2 < nk ? kt + 2 : nk - 1);
;     __builtin_amdgcn_sched_barrier(0);
;     const bf16_t* As = smem + buf * L::STAGE + (wm * 16 * MI + l15) * LDT + quad * 8;
;     const bf16_t* Bs = smem + buf * L::STAGE + L::A_ELEMS + (wn * 16 * NJ + l15) * LDT + quad * 8;
; #pragma unroll
;     for (int ks = 0; ks < 2; ++ks) {
;       if (MI * NJ >= 32 && ks == 1) asm volatile("" ::: "memory");
;       bf16x8 b[NJ];
; #pragma unroll
;       for (int j = 0; j < NJ; ++j) b[j] = *(const bf16x8*)(Bs + j * 16 * LDT + ks * 32);
; #pragma unroll
;       for (int i = 0; i < MI; ++i) {
;         const bf16x8 a = *(const bf16x8*)(As + i * 16 * LDT + ks * 32);
; #pragma unroll
;         for (int j = 0; j < NJ; ++j) acc[i][j] = SWAP ? mfma16(b[j], a, acc[i][j]) : mfma16(a, b[j], acc[i][j]);
;       }
;     }
.Lgm7_main:
	ds_read_b128 v[242:245], v177 offset:4608
	s_waitcnt lgkmcnt(4)
	v_mfma_f32_16x16x32_bf16 v[156:159], v[178:181], v[194:197], v[156:159]
	s_waitcnt lgkmcnt(3)
	v_mfma_f32_16x16x32_bf16 v[152:155], v[182:185], v[194:197], v[152:155]
	s_waitcnt lgkmcnt(2)
	v_mfma_f32_16x16x32_bf16 v[148:151], v[186:189], v[194:197], v[148:151]
	s_waitcnt lgkmcnt(1)
	v_mfma_f32_16x16x32_bf16 v[144:147], v[190:193], v[194:197], v[144:147]
	ds_read_b128 v[246:249], v177 offset:6912
	v_mfma_f32_16x16x32_bf16 v[108:111], v[178:181], v[198:201], v[108:111]
	v_mfma_f32_16x16x32_bf16 v[104:107], v[182:185], v[198:201], v[104:107]
	s_and_b32 s24, s21, 1
	s_min_u32 s22, s21, 41
	s_xor_b32 s23, s24, 1
	s_mul_i32 s23, s23, 0x12000
	v_add3_u32 v250, s23, v172, v170
	s_waitcnt vmcnt(7)
	ds_write_b128 v250, v[112:115]
	v_mfma_f32_16x16x32_bf16 v[100:103], v[186:189], v[198:201], v[100:103]
	v_mfma_f32_16x16x32_bf16 v[96:99], v[190:193], v[198:201], v[96:99]
	s_lshl_b32 s25, s22, 7
	s_add_u32 s22, s6, s25
	v_add3_u32 v251, s23, v173, v170
	v_add3_u32 v252, s23, v174, v170
	v_add3_u32 v253, s23, v175, v170
	s_addc_u32 s23, s7, 0
	v_lshl_add_u64 v[112:113], s[22:23], 0, v[162:163]
	s_nop 0
	global_load_dwordx4 v[112:115], v[112:113], off offset:256
	ds_read_b128 v[194:197], v177 offset:9216
	s_waitcnt lgkmcnt(3)
	v_mfma_f32_16x16x32_bf16 v[92:95], v[178:181], v[242:245], v[92:95]
	v_mfma_f32_16x16x32_bf16 v[88:91], v[182:185], v[242:245], v[88:91]
	v_mfma_f32_16x16x32_bf16 v[84:87], v[186:189], v[242:245], v[84:87]
	v_mfma_f32_16x16x32_bf16 v[80:83], v[190:193], v[242:245], v[80:83]
	s_waitcnt vmcnt(7)
	ds_write_b128 v251, v[116:119]
	ds_read_b128 v[198:201], v177 offset:11520
	s_waitcnt lgkmcnt(4)
	v_mfma_f32_16x16x32_bf16 v[76:79], v[178:181], v[246:249], v[76:79]
	v_mfma_f32_16x16x32_bf16 v[72:75], v[182:185], v[246:249], v[72:75]
	v_lshl_add_u64 v[116:117], s[22:23], 0, v[164:165]
	s_nop 0
	global_load_dwordx4 v[116:119], v[116:117], off offset:256
	v_mfma_f32_16x16x32_bf16 v[68:71], v[186:189], v[246:249], v[68:71]
	v_mfma_f32_16x16x32_bf16 v[64:67], v[190:193], v[246:249], v[64:67]
	ds_read_b128 v[242:245], v177 offset:13824
	s_waitcnt lgkmcnt(3)
	v_mfma_f32_16x16x32_bf16 v[60:63], v[178:181], v[194:197], v[60:63]
	v_mfma_f32_16x16x32_bf16 v[56:59], v[182:185], v[194:197], v[56:59]
	v_mfma_f32_16x16x32_bf16 v[52:55], v[186:189], v[194:197], v[52:55]
	s_waitcnt vmcnt(7)
	ds_write_b128 v252, v[120:123]
	v_mfma_f32_16x16x32_bf16 v[48:51], v[190:193], v[194:197], v[48:51]
	ds_read_b128 v[246:249], v177 offset:16128
	s_waitcnt lgkmcnt(3)
	v_mfma_f32_16x16x32_bf16 v[44:47], v[178:181], v[198:201], v[44:47]
	v_lshl_add_u64 v[120:121], s[22:23], 0, v[166:167]
	s_nop 0
	global_load_dwordx4 v[120:123], v[120:121], off offset:256
	v_mfma_f32_16x16x32_bf16 v[40:43], v[182:185], v[198:201], v[40:43]
	v_mfma_f32_16x16x32_bf16 v[36:39], v[186:189], v[198:201], v[36:39]
	v_mfma_f32_16x16x32_bf16 v[32:35], v[190:193], v[198:201], v[32:35]
	ds_read_b128 v[194:197], v177 offset:64
	s_waitcnt lgkmcnt(3)
	v_mfma_f32_16x16x32_bf16 v[28:31], v[178:181], v[242:245], v[28:31]
	s_waitcnt vmcnt(7)
	ds_write_b128 v253, v[124:127]
	v_mfma_f32_16x16x32_bf16 v[24:27], v[182:185], v[242:245], v[24:27]
	v_mfma_f32_16x16x32_bf16 v[20:23], v[186:189], v[242:245], v[20:23]
	v_lshl_add_u64 v[124:125], s[22:23], 0, v[168:169]
	s_nop 0
	global_load_dwordx4 v[124:127], v[124:125], off offset:256
	v_mfma_f32_16x16x32_bf16 v[16:19], v[190:193], v[242:245], v[16:19]
	ds_read_b128 v[198:201], v177 offset:2368
	s_waitcnt lgkmcnt(3)
	v_mfma_f32_16x16x32_bf16 v[8:11], v[178:181], v[246:249], v[8:11]
	ds_read_b128 v[178:181], v202 offset:36928
	v_mfma_f32_16x16x32_bf16 v[4:7], v[182:185], v[246:249], v[4:7]
	ds_read_b128 v[182:185], v202 offset:39232
	v_mfma_f32_16x16x32_bf16 v[0:3], v[186:189], v[246:249], v[0:3]
	ds_read_b128 v[186:189], v202 offset:41536
	v_mfma_f32_16x16x32_bf16 v[12:15], v[190:193], v[246:249], v[12:15]
	ds_read_b128 v[190:193], v202 offset:43840
	s_waitcnt vmcnt(7)
; DI f32x4 mfma16(bf16x8 a, bf16x8 b, f32x4 c) { return __builtin_amdgcn_mfma_f32_16x16x32_bf16(a, b, c, 0, 0, 0); }
; template <int MI, int NJ, bool SWAP, class AP, class BP>
; DI void gemm_main(f32x4 (&acc)[MI][NJ], const AP& ap, int a_kstep, const BP& bp, int b_kstep, int nk, bf16_t* smem) {
;     ...
;   auto gload = [&](int kt) {
;     const bf16_t* ab = ap.base + (size_t)kt * a_kstep; const bf16_t* bb = bp.base + (size_t)kt * b_kstep;
; #pragma unroll
;     for (int i = 0; i < CA; ++i) ra[i] = *(const u32x4*)(ab + pa[i]);
; #pragma unroll
;     for (int i = 0; i < CB; ++i) rb[i] = *(const u32x4*)(bb + pb[i]);
;   };
;   auto sstore = [&](int buf) {
;     bf16_t* As = smem + buf * L::STAGE; bf16_t* Bs = As + L::A_ELEMS;
; #pragma unroll
;     for (int i = 0; i < CA; ++i) { const int c = tid + NTHR * i; *(u32x4*)(As + (c >> 3) * LDT + (c & 7) * 8) = oka[i] ? ra[i] : (u32x4){0u, 0u, 0u, 0u}; }
; #pragma unroll
;     for (int i = 0; i < CB; ++i) { const int c = tid + NTHR * i; *(u32x4*)(Bs + (c >> 3) * LDT + (c & 7) * 8) = rb[i]; }
;     ...
;   for (int kt = 0; kt < nk; ++kt) {
;     const int buf = kt & 1;
;     sstore(buf ^ 1);
;     gload(kt + 2 < nk ? kt + 2 : nk - 1);
;     __builtin_amdgcn_sched_barrier(0);
;     const bf16_t* As = smem + buf * L::STAGE + (wm * 16 * MI + l15) * LDT + quad * 8;
;     const bf16_t* Bs = smem + buf * L::STAGE + L::A_ELEMS + (wn * 16 * NJ + l15) * LDT + quad * 8;
; #pragma unroll
;     for (int ks = 0; ks < 2; ++ks) {
;       if (MI * NJ >= 32 && ks == 1) asm volatile("" ::: "memory");
;       bf16x8 b[NJ];
; #pragma unroll
;       for (int j = 0; j < NJ; ++j) b[j] = *(const bf16x8*)(Bs + j * 16 * LDT + ks * 32);
; #pragma unroll
;       for (int i = 0; i < MI; ++i) {
;         const bf16x8 a = *(const bf16x8*)(As + i * 16 * LDT + ks * 32);
; #pragma unroll
;         for (int j = 0; j < NJ; ++j) acc[i][j] = SWAP ? mfma16(b[j], a, acc[i][j]) : mfma16(a, b[j], acc[i][j]);
;       }
;     }
;     __syncthreads();
;   }
	ds_write_b128 v250, v[128:131] offset:36864
	ds_read_b128 v[242:245], v177 offset:4672
	s_waitcnt lgkmcnt(5)
	v_mfma_f32_16x16x32_bf16 v[156:159], v[178:181], v[194:197], v[156:159]
	s_waitcnt lgkmcnt(4)
	v_mfma_f32_16x16x32_bf16 v[152:155], v[182:185], v[194:197], v[152:155]
	s_add_u32 s22, s8, s25
	s_addc_u32 s23, s9, 0
	v_lshl_add_u64 v[128:129], s[22:23], 0, v[162:163]
	s_nop 0
	global_load_dwordx4 v[128:131], v[128:129], off offset:256
	s_waitcnt lgkmcnt(3)
	v_mfma_f32_16x16x32_bf16 v[148:151], v[186:189], v[194:197], v[148:151]
	s_waitcnt lgkmcnt(2)
	v_mfma_f32_16x16x32_bf16 v[144:147], v[190:193], v[194:197], v[144:147]
	ds_read_b128 v[246:249], v177 offset:6976
	v_mfma_f32_16x16x32_bf16 v[108:111], v[178:181], v[198:201], v[108:111]
	v_mfma_f32_16x16x32_bf16 v[104:107], v[182:185], v[198:201], v[104:107]
	s_waitcnt vmcnt(7)
	ds_write_b128 v251, v[132:135] offset:36864
	v_mfma_f32_16x16x32_bf16 v[100:103], v[186:189], v[198:201], v[100:103]
	v_mfma_f32_16x16x32_bf16 v[96:99], v[190:193], v[198:201], v[96:99]
	v_lshl_add_u64 v[132:133], s[22:23], 0, v[164:165]
	s_nop 0
	global_load_dwordx4 v[132:135], v[132:133], off offset:256
	ds_read_b128 v[194:197], v177 offset:9280
	s_waitcnt lgkmcnt(3)
	v_mfma_f32_16x16x32_bf16 v[92:95], v[178:181], v[242:245], v[92:95]
	v_mfma_f32_16x16x32_bf16 v[88:91], v[182:185], v[242:245], v[88:91]
	v_mfma_f32_16x16x32_bf16 v[84:87], v[186:189], v[242:245], v[84:87]
	v_mfma_f32_16x16x32_bf16 v[80:83], v[190:193], v[242:245], v[80:83]
	ds_read_b128 v[198:201], v177 offset:11584
	s_waitcnt lgkmcnt(3)
	v_mfma_f32_16x16x32_bf16 v[76:79], v[178:181], v[246:249], v[76:79]
	s_waitcnt vmcnt(7)
	ds_write_b128 v252, v[136:139] offset:36864
	v_mfma_f32_16x16x32_bf16 v[72:75], v[182:185], v[246:249], v[72:75]
	v_mfma_f32_16x16x32_bf16 v[68:71], v[186:189], v[246:249], v[68:71]
	v_lshl_add_u64 v[136:137], s[22:23], 0, v[166:167]
	s_nop 0
	global_load_dwordx4 v[136:139], v[136:137], off offset:256
	v_mfma_f32_16x16x32_bf16 v[64:67], v[190:193], v[246:249], v[64:67]
	ds_read_b128 v[242:245], v177 offset:13888
	s_waitcnt lgkmcnt(3)
	v_mfma_f32_16x16x32_bf16 v[60:63], v[178:181], v[194:197], v[60:63]
	v_mfma_f32_16x16x32_bf16 v[56:59], v[182:185], v[194:197], v[56:59]
	v_mfma_f32_16x16x32_bf16 v[52:55], v[186:189], v[194:197], v[52:55]
	v_mfma_f32_16x16x32_bf16 v[48:51], v[190:193], v[194:197], v[48:51]
	s_waitcnt vmcnt(7)
	ds_write_b128 v253, v[140:143] offset:36864
	ds_read_b128 v[246:249], v177 offset:16192
	s_waitcnt lgkmcnt(4)
	v_mfma_f32_16x16x32_bf16 v[44:47], v[178:181], v[198:201], v[44:47]
	v_mfma_f32_16x16x32_bf16 v[40:43], v[182:185], v[198:201], v[40:43]
	v_lshl_add_u64 v[140:141], s[22:23], 0, v[168:169]
	s_nop 0
	global_load_dwordx4 v[140:143], v[140:141], off offset:256
	v_mfma_f32_16x16x32_bf16 v[36:39], v[186:189], v[198:201], v[36:39]
	v_mfma_f32_16x16x32_bf16 v[32:35], v[190:193], v[198:201], v[32:35]
	s_add_i32 s21, s21, 1
	s_and_b32 s98, s21, 1
	s_mul_i32 s98, s98, 0x12000
	v_add3_u32 v202, s98, v160, v176
	v_add3_u32 v177, s98, v171, v176
	s_cmp_lg_u32 s21, 44
	s_waitcnt lgkmcnt(0)
	s_barrier
	s_cbranch_scc0 .Lgm7_exit
	ds_read_b128 v[194:197], v177
	ds_read_b128 v[198:201], v177 offset:2304
	v_mfma_f32_16x16x32_bf16 v[28:31], v[178:181], v[242:245], v[28:31]
	v_mfma_f32_16x16x32_bf16 v[8:11], v[178:181], v[246:249], v[8:11]
	ds_read_b128 v[178:181], v202 offset:36864
	v_mfma_f32_16x16x32_bf16 v[24:27], v[182:185], v[242:245], v[24:27]
	v_mfma_f32_16x16x32_bf16 v[4:7], v[182:185], v[246:249], v[4:7]
	ds_read_b128 v[182:185], v202 offset:39168
	v_mfma_f32_16x16x32_bf16 v[20:23], v[186:189], v[242:245], v[20:23]
	v_mfma_f32_16x16x32_bf16 v[0:3], v[186:189], v[246:249], v[0:3]
	ds_read_b128 v[186:189], v202 offset:41472
	v_mfma_f32_16x16x32_bf16 v[16:19], v[190:193], v[242:245], v[16:19]
	v_mfma_f32_16x16x32_bf16 v[12:15], v[190:193], v[246:249], v[12:15]
	ds_read_b128 v[190:193], v202 offset:43776
	s_branch .Lgm7_main

; DI f32x4 mfma16(bf16x8 a, bf16x8 b, f32x4 c) { return __builtin_amdgcn_mfma_f32_16x16x32_bf16(a, b, c, 0, 0, 0); }
; template <int MI, int NJ, bool SWAP, class AP, class BP>
; DI void gemm_main(f32x4 (&acc)[MI][NJ], const AP& ap, int a_kstep, const BP& bp, int b_kstep, int nk, bf16_t* smem) {
;     ...
;   auto gload = [&](int kt) {
;     const bf16_t* ab = ap.base + (size_t)kt * a_kstep; const bf16_t* bb = bp.base + (size_t)kt * b_kstep;
; #pragma unroll
;     for (int i = 0; i < CA; ++i) ra[i] = *(const u32x4*)(ab + pa[i]);
; #pragma unroll
;     for (int i = 0; i < CB; ++i) rb[i] = *(const u32x4*)(bb + pb[i]);
;   };
;   auto sstore = [&](int buf) {
;     bf16_t* As = smem + buf * L::STAGE; bf16_t* Bs = As + L::A_ELEMS;
; #pragma unroll
;     for (int i = 0; i < CA; ++i) { const int c = tid + NTHR * i; *(u32x4*)(As + (c >> 3) * LDT + (c & 7) * 8) = oka[i] ? ra[i] : (u32x4){0u, 0u, 0u, 0u}; }
; #pragma unroll
;     for (int i = 0; i < CB; ++i) { const int c = tid + NTHR * i; *(u32x4*)(Bs + (c >> 3) * LDT + (c & 7) * 8) = rb[i]; }
;     ...
;   for (int kt = 0; kt < nk; ++kt) {
;     const int buf = kt & 1;
;     sstore(buf ^ 1);
;     gload(kt + 2 < nk ? kt + 2 : nk - 1);
;     __builtin_amdgcn_sched_barrier(0);
;     const bf16_t* As = smem + buf * L::STAGE + (wm * 16 * MI + l15) * LDT + quad * 8;
;     const bf16_t* Bs = smem + buf * L::STAGE + L::A_ELEMS + (wn * 16 * NJ + l15) * LDT + quad * 8;
; #pragma unroll
;     for (int ks = 0; ks < 2; ++ks) {
;       if (MI * NJ >= 32 && ks == 1) asm volatile("" ::: "memory");
;       bf16x8 b[NJ];
; #pragma unroll
;       for (int j = 0; j < NJ; ++j) b[j] = *(const bf16x8*)(Bs + j * 16 * LDT + ks * 32);
; #pragma unroll
;       for (int i = 0; i < MI; ++i) {
;         const bf16x8 a = *(const bf16x8*)(As + i * 16 * LDT + ks * 32);
; #pragma unroll
;         for (int j = 0; j < NJ; ++j) acc[i][j] = SWAP ? mfma16(b[j], a, acc[i][j]) : mfma16(a, b[j], acc[i][j]);
;       }
;     }
.Lgm8_main:
	ds_read_b128 v[246:249], v210 offset:4608
	s_waitcnt lgkmcnt(4)
	v_mfma_f32_16x16x32_bf16 v[124:127], v[190:193], v[206:209], v[124:127]
	s_waitcnt lgkmcnt(3)
	v_mfma_f32_16x16x32_bf16 v[120:123], v[194:197], v[206:209], v[120:123]
	s_waitcnt lgkmcnt(2)
	v_mfma_f32_16x16x32_bf16 v[116:119], v[198:201], v[206:209], v[116:119]
	s_waitcnt lgkmcnt(1)
	v_mfma_f32_16x16x32_bf16 v[112:115], v[202:205], v[206:209], v[112:115]
	ds_read_b128 v[250:253], v210 offset:6912
	v_mfma_f32_16x16x32_bf16 v[108:111], v[190:193], v[242:245], v[108:111]
	v_mfma_f32_16x16x32_bf16 v[104:107], v[194:197], v[242:245], v[104:107]
	s_and_b32 s5, s4, 1
	s_xor_b32 s23, s5, 1
	s_mul_i32 s23, s23, 0x12000
	v_add3_u32 v254, s23, v185, v183
	s_waitcnt vmcnt(7)
	ds_write_b128 v254, v[128:131]
	v_mfma_f32_16x16x32_bf16 v[100:103], v[198:201], v[242:245], v[100:103]
	v_mfma_f32_16x16x32_bf16 v[96:99], v[202:205], v[242:245], v[96:99]
	s_min_u32 s99, s4, 13
	s_lshl_b32 s99, s99, 7
	s_add_u32 s26, s0, s99
	s_addc_u32 s27, s1, 0
	v_lshl_add_u64 v[128:129], s[26:27], 0, v[162:163]
	s_nop 0
	global_load_dwordx4 v[128:131], v[128:129], off offset:256
	ds_read_b128 v[206:209], v210 offset:9216
	s_waitcnt lgkmcnt(3)
	v_mfma_f32_16x16x32_bf16 v[92:95], v[190:193], v[246:249], v[92:95]
	v_mfma_f32_16x16x32_bf16 v[88:91], v[194:197], v[246:249], v[88:91]
	v_mfma_f32_16x16x32_bf16 v[84:87], v[198:201], v[246:249], v[84:87]
	v_mfma_f32_16x16x32_bf16 v[80:83], v[202:205], v[246:249], v[80:83]
	v_add3_u32 v238, s23, v187, v183
	s_waitcnt vmcnt(7)
	ds_write_b128 v238, v[132:135]
	ds_read_b128 v[242:245], v210 offset:11520
	s_waitcnt lgkmcnt(4)
	v_mfma_f32_16x16x32_bf16 v[76:79], v[190:193], v[250:253], v[76:79]
	v_mfma_f32_16x16x32_bf16 v[72:75], v[194:197], v[250:253], v[72:75]
	v_lshl_add_u64 v[132:133], s[26:27], 0, v[164:165]
	s_nop 0
	global_load_dwordx4 v[132:135], v[132:133], off offset:256
	v_mfma_f32_16x16x32_bf16 v[68:71], v[198:201], v[250:253], v[68:71]
	v_mfma_f32_16x16x32_bf16 v[64:67], v[202:205], v[250:253], v[64:67]
	ds_read_b128 v[246:249], v210 offset:13824
	s_waitcnt lgkmcnt(3)
	v_mfma_f32_16x16x32_bf16 v[60:63], v[190:193], v[206:209], v[60:63]
	v_mfma_f32_16x16x32_bf16 v[56:59], v[194:197], v[206:209], v[56:59]
	v_mfma_f32_16x16x32_bf16 v[52:55], v[198:201], v[206:209], v[52:55]
	v_add3_u32 v239, s23, v188, v183
	s_waitcnt vmcnt(7)
	ds_write_b128 v239, v[136:139]
	v_mfma_f32_16x16x32_bf16 v[48:51], v[202:205], v[206:209], v[48:51]
	ds_read_b128 v[250:253], v210 offset:16128
	s_waitcnt lgkmcnt(3)
	v_mfma_f32_16x16x32_bf16 v[44:47], v[190:193], v[242:245], v[44:47]
	v_lshl_add_u64 v[136:137], s[26:27], 0, v[166:167]
	s_nop 0
	global_load_dwordx4 v[136:139], v[136:137], off offset:256
	v_mfma_f32_16x16x32_bf16 v[40:43], v[194:197], v[242:245], v[40:43]
	v_mfma_f32_16x16x32_bf16 v[36:39], v[198:201], v[242:245], v[36:39]
	v_mfma_f32_16x16x32_bf16 v[32:35], v[202:205], v[242:245], v[32:35]
	ds_read_b128 v[206:209], v210 offset:64
	s_waitcnt lgkmcnt(3)
	v_mfma_f32_16x16x32_bf16 v[28:31], v[190:193], v[246:249], v[28:31]
	v_add3_u32 v255, s23, v189, v183
	s_waitcnt vmcnt(7)
	ds_write_b128 v255, v[140:143]
	v_mfma_f32_16x16x32_bf16 v[24:27], v[194:197], v[246:249], v[24:27]
	v_mfma_f32_16x16x32_bf16 v[20:23], v[198:201], v[246:249], v[20:23]
	v_lshl_add_u64 v[140:141], s[26:27], 0, v[168:169]
	s_nop 0
	global_load_dwordx4 v[140:143], v[140:141], off offset:256
	v_mfma_f32_16x16x32_bf16 v[16:19], v[202:205], v[246:249], v[16:19]
	ds_read_b128 v[242:245], v210 offset:2368
	s_waitcnt lgkmcnt(3)
	v_mfma_f32_16x16x32_bf16 v[12:15], v[190:193], v[250:253], v[12:15]
	ds_read_b128 v[190:193], v211 offset:36928
	v_mfma_f32_16x16x32_bf16 v[8:11], v[194:197], v[250:253], v[8:11]
	ds_read_b128 v[194:197], v211 offset:39232
	v_mfma_f32_16x16x32_bf16 v[4:7], v[198:201], v[250:253], v[4:7]
	ds_read_b128 v[198:201], v211 offset:41536
	v_mfma_f32_16x16x32_bf16 v[0:3], v[202:205], v[250:253], v[0:3]
	ds_read_b128 v[202:205], v211 offset:43840
	s_waitcnt vmcnt(7)
; DI f32x4 mfma16(bf16x8 a, bf16x8 b, f32x4 c) { return __builtin_amdgcn_mfma_f32_16x16x32_bf16(a, b, c, 0, 0, 0); }
; template <int MI, int NJ, bool SWAP, class AP, class BP>
; DI void gemm_main(f32x4 (&acc)[MI][NJ], const AP& ap, int a_kstep, const BP& bp, int b_kstep, int nk, bf16_t* smem) {
;     ...
;   auto gload = [&](int kt) {
;     const bf16_t* ab = ap.base + (size_t)kt * a_kstep; const bf16_t* bb = bp.base + (size_t)kt * b_kstep;
; #pragma unroll
;     for (int i = 0; i < CA; ++i) ra[i] = *(const u32x4*)(ab + pa[i]);
; #pragma unroll
;     for (int i = 0; i < CB; ++i) rb[i] = *(const u32x4*)(bb + pb[i]);
;   };
;   auto sstore = [&](int buf) {
;     bf16_t* As = smem + buf * L::STAGE; bf16_t* Bs = As + L::A_ELEMS;
; #pragma unroll
;     for (int i = 0; i < CA; ++i) { const int c = tid + NTHR * i; *(u32x4*)(As + (c >> 3) * LDT + (c & 7) * 8) = oka[i] ? ra[i] : (u32x4){0u, 0u, 0u, 0u}; }
; #pragma unroll
;     for (int i = 0; i < CB; ++i) { const int c = tid + NTHR * i; *(u32x4*)(Bs + (c >> 3) * LDT + (c & 7) * 8) = rb[i]; }
;     ...
;   for (int kt = 0; kt < nk; ++kt) {
;     const int buf = kt & 1;
;     sstore(buf ^ 1);
;     gload(kt + 2 < nk ? kt + 2 : nk - 1);
;     __builtin_amdgcn_sched_barrier(0);
;     const bf16_t* As = smem + buf * L::STAGE + (wm * 16 * MI + l15) * LDT + quad * 8;
;     const bf16_t* Bs = smem + buf * L::STAGE + L::A_ELEMS + (wn * 16 * NJ + l15) * LDT + quad * 8;
; #pragma unroll
;     for (int ks = 0; ks < 2; ++ks) {
;       if (MI * NJ >= 32 && ks == 1) asm volatile("" ::: "memory");
;       bf16x8 b[NJ];
; #pragma unroll
;       for (int j = 0; j < NJ; ++j) b[j] = *(const bf16x8*)(Bs + j * 16 * LDT + ks * 32);
; #pragma unroll
;       for (int i = 0; i < MI; ++i) {
;         const bf16x8 a = *(const bf16x8*)(As + i * 16 * LDT + ks * 32);
; #pragma unroll
;         for (int j = 0; j < NJ; ++j) acc[i][j] = SWAP ? mfma16(b[j], a, acc[i][j]) : mfma16(a, b[j], acc[i][j]);
;       }
;     }
;     __syncthreads();
;   }
	ds_write_b128 v254, v[144:147] offset:36864
	ds_read_b128 v[246:249], v210 offset:4672
	s_waitcnt lgkmcnt(5)
	v_mfma_f32_16x16x32_bf16 v[124:127], v[190:193], v[206:209], v[124:127]
	s_waitcnt lgkmcnt(4)
	v_mfma_f32_16x16x32_bf16 v[120:123], v[194:197], v[206:209], v[120:123]
	s_add_u32 s26, s2, s99
	s_addc_u32 s27, s3, 0
	v_lshl_add_u64 v[144:145], s[26:27], 0, v[162:163]
	s_nop 0
	global_load_dwordx4 v[144:147], v[144:145], off offset:256
	s_waitcnt lgkmcnt(3)
	v_mfma_f32_16x16x32_bf16 v[116:119], v[198:201], v[206:209], v[116:119]
	s_waitcnt lgkmcnt(2)
	v_mfma_f32_16x16x32_bf16 v[112:115], v[202:205], v[206:209], v[112:115]
	ds_read_b128 v[250:253], v210 offset:6976
	v_mfma_f32_16x16x32_bf16 v[108:111], v[190:193], v[242:245], v[108:111]
	v_mfma_f32_16x16x32_bf16 v[104:107], v[194:197], v[242:245], v[104:107]
	s_waitcnt vmcnt(7)
	ds_write_b128 v238, v[148:151] offset:36864
	v_mfma_f32_16x16x32_bf16 v[100:103], v[198:201], v[242:245], v[100:103]
	v_mfma_f32_16x16x32_bf16 v[96:99], v[202:205], v[242:245], v[96:99]
	v_lshl_add_u64 v[148:149], s[26:27], 0, v[164:165]
	s_nop 0
	global_load_dwordx4 v[148:151], v[148:149], off offset:256
	ds_read_b128 v[206:209], v210 offset:9280
	s_waitcnt lgkmcnt(3)
	v_mfma_f32_16x16x32_bf16 v[92:95], v[190:193], v[246:249], v[92:95]
	v_mfma_f32_16x16x32_bf16 v[88:91], v[194:197], v[246:249], v[88:91]
	v_mfma_f32_16x16x32_bf16 v[84:87], v[198:201], v[246:249], v[84:87]
	v_mfma_f32_16x16x32_bf16 v[80:83], v[202:205], v[246:249], v[80:83]
	ds_read_b128 v[242:245], v210 offset:11584
	s_waitcnt lgkmcnt(3)
	v_mfma_f32_16x16x32_bf16 v[76:79], v[190:193], v[250:253], v[76:79]
	s_waitcnt vmcnt(7)
	ds_write_b128 v239, v[152:155] offset:36864
	v_mfma_f32_16x16x32_bf16 v[72:75], v[194:197], v[250:253], v[72:75]
	v_mfma_f32_16x16x32_bf16 v[68:71], v[198:201], v[250:253], v[68:71]
	v_lshl_add_u64 v[152:153], s[26:27], 0, v[166:167]
	s_nop 0
	global_load_dwordx4 v[152:155], v[152:153], off offset:256
	v_mfma_f32_16x16x32_bf16 v[64:67], v[202:205], v[250:253], v[64:67]
	ds_read_b128 v[246:249], v210 offset:13888
	s_waitcnt lgkmcnt(3)
	v_mfma_f32_16x16x32_bf16 v[60:63], v[190:193], v[206:209], v[60:63]
	v_mfma_f32_16x16x32_bf16 v[56:59], v[194:197], v[206:209], v[56:59]
	v_mfma_f32_16x16x32_bf16 v[52:55], v[198:201], v[206:209], v[52:55]
	v_mfma_f32_16x16x32_bf16 v[48:51], v[202:205], v[206:209], v[48:51]
	s_waitcnt vmcnt(7)
	ds_write_b128 v255, v[156:159] offset:36864
	ds_read_b128 v[250:253], v210 offset:16192
	s_waitcnt lgkmcnt(4)
	v_mfma_f32_16x16x32_bf16 v[44:47], v[190:193], v[242:245], v[44:47]
	v_mfma_f32_16x16x32_bf16 v[40:43], v[194:197], v[242:245], v[40:43]
	v_lshl_add_u64 v[156:157], s[26:27], 0, v[168:169]
	s_nop 0
	global_load_dwordx4 v[156:159], v[156:157], off offset:256
	v_mfma_f32_16x16x32_bf16 v[36:39], v[198:201], v[242:245], v[36:39]
	v_mfma_f32_16x16x32_bf16 v[32:35], v[202:205], v[242:245], v[32:35]
	s_add_i32 s4, s4, 1
	s_and_b32 s98, s4, 1
	s_mul_i32 s98, s98, 0x12000
	v_add3_u32 v210, s98, v184, v186
	v_add3_u32 v211, s98, v160, v186
	s_cmp_lg_u32 s4, 16
	s_waitcnt lgkmcnt(0)
	s_barrier
	s_cbranch_scc0 .Lgm8_exit
	ds_read_b128 v[206:209], v210
	ds_read_b128 v[242:245], v210 offset:2304
	v_mfma_f32_16x16x32_bf16 v[28:31], v[190:193], v[246:249], v[28:31]
	v_mfma_f32_16x16x32_bf16 v[12:15], v[190:193], v[250:253], v[12:15]
	ds_read_b128 v[190:193], v211 offset:36864
	v_mfma_f32_16x16x32_bf16 v[24:27], v[194:197], v[246:249], v[24:27]
	v_mfma_f32_16x16x32_bf16 v[8:11], v[194:197], v[250:253], v[8:11]
	ds_read_b128 v[194:197], v211 offset:39168
	v_mfma_f32_16x16x32_bf16 v[20:23], v[198:201], v[246:249], v[20:23]
	v_mfma_f32_16x16x32_bf16 v[4:7], v[198:201], v[250:253], v[4:7]
	ds_read_b128 v[198:201], v211 offset:41472
	v_mfma_f32_16x16x32_bf16 v[16:19], v[202:205], v[246:249], v[16:19]
	v_mfma_f32_16x16x32_bf16 v[0:3], v[202:205], v[250:253], v[0:3]
	ds_read_b128 v[202:205], v211 offset:43776
	s_branch .Lgm8_main

; DI f32x4 mfma16(bf16x8 a, bf16x8 b, f32x4 c) { return __builtin_amdgcn_mfma_f32_16x16x32_bf16(a, b, c, 0, 0, 0); }
; template <int MI, int NJ, bool SWAP, class AP, class BP>
; DI void gemm_main(f32x4 (&acc)[MI][NJ], const AP& ap, int a_kstep, const BP& bp, int b_kstep, int nk, bf16_t* smem) {
;     ...
;   auto gload = [&](int kt) {
;     const bf16_t* ab = ap.base + (size_t)kt * a_kstep; const bf16_t* bb = bp.base + (size_t)kt * b_kstep;
; #pragma unroll
;     for (int i = 0; i < CA; ++i) ra[i] = *(const u32x4*)(ab + pa[i]);
; #pragma unroll
;     for (int i = 0; i < CB; ++i) rb[i] = *(const u32x4*)(bb + pb[i]);
;   };
;   auto sstore = [&](int buf) {
;     bf16_t* As = smem + buf * L::STAGE; bf16_t* Bs = As + L::A_ELEMS;
; #pragma unroll
;     for (int i = 0; i < CA; ++i) { const int c = tid + NTHR * i; *(u32x4*)(As + (c >> 3) * LDT + (c & 7) * 8) = oka[i] ? ra[i] : (u32x4){0u, 0u, 0u, 0u}; }
; #pragma unroll
;     for (int i = 0; i < CB; ++i) { const int c = tid + NTHR * i; *(u32x4*)(Bs + (c >> 3) * LDT + (c & 7) * 8) = rb[i]; }
;     ...
;   for (int kt = 0; kt < nk; ++kt) {
;     const int buf = kt & 1;
;     sstore(buf ^ 1);
;     gload(kt + 2 < nk ? kt + 2 : nk - 1);
;     __builtin_amdgcn_sched_barrier(0);
;     const bf16_t* As = smem + buf * L::STAGE + (wm * 16 * MI + l15) * LDT + quad * 8;
;     const bf16_t* Bs = smem + buf * L::STAGE + L::A_ELEMS + (wn * 16 * NJ + l15) * LDT + quad * 8;
; #pragma unroll
;     for (int ks = 0; ks < 2; ++ks) {
;       if (MI * NJ >= 32 && ks == 1) asm volatile("" ::: "memory");
;       bf16x8 b[NJ];
; #pragma unroll
;       for (int j = 0; j < NJ; ++j) b[j] = *(const bf16x8*)(Bs + j * 16 * LDT + ks * 32);
; #pragma unroll
;       for (int i = 0; i < MI; ++i) {
;         const bf16x8 a = *(const bf16x8*)(As + i * 16 * LDT + ks * 32);
; #pragma unroll
;         for (int j = 0; j < NJ; ++j) acc[i][j] = SWAP ? mfma16(b[j], a, acc[i][j]) : mfma16(a, b[j], acc[i][j]);
;       }
;     }
.Lgm10_main:
	ds_read_b128 v[246:249], v198 offset:4608
	s_waitcnt lgkmcnt(4)
	v_mfma_f32_16x16x32_bf16 v[156:159], v[178:181], v[194:197], v[156:159]
	s_waitcnt lgkmcnt(3)
	v_mfma_f32_16x16x32_bf16 v[152:155], v[182:185], v[194:197], v[152:155]
	s_waitcnt lgkmcnt(2)
	v_mfma_f32_16x16x32_bf16 v[148:151], v[186:189], v[194:197], v[148:151]
	s_waitcnt lgkmcnt(1)
	v_mfma_f32_16x16x32_bf16 v[144:147], v[190:193], v[194:197], v[144:147]
	ds_read_b128 v[250:253], v198 offset:6912
	v_mfma_f32_16x16x32_bf16 v[108:111], v[178:181], v[242:245], v[108:111]
	v_mfma_f32_16x16x32_bf16 v[104:107], v[182:185], v[242:245], v[104:107]
	s_and_b32 s33, s8, 1
	s_xor_b32 s37, s33, 1
	s_mul_i32 s37, s37, 0x12000
	v_add3_u32 v254, s37, v173, v171
	s_waitcnt vmcnt(7)
	ds_write_b128 v254, v[112:115]
	v_mfma_f32_16x16x32_bf16 v[100:103], v[186:189], v[242:245], v[100:103]
	v_mfma_f32_16x16x32_bf16 v[96:99], v[190:193], v[242:245], v[96:99]
	s_min_u32 s99, s8, 3
	s_lshl_b32 s99, s99, 7
	s_add_u32 s38, s0, s99
	s_addc_u32 s39, s1, 0
	v_lshl_add_u64 v[112:113], s[38:39], 0, v[162:163]
	s_nop 0
	global_load_dwordx4 v[112:115], v[112:113], off offset:256
	ds_read_b128 v[194:197], v198 offset:9216
	s_waitcnt lgkmcnt(3)
	v_mfma_f32_16x16x32_bf16 v[92:95], v[178:181], v[246:249], v[92:95]
	v_mfma_f32_16x16x32_bf16 v[88:91], v[182:185], v[246:249], v[88:91]
	v_mfma_f32_16x16x32_bf16 v[84:87], v[186:189], v[246:249], v[84:87]
	v_mfma_f32_16x16x32_bf16 v[80:83], v[190:193], v[246:249], v[80:83]
	v_add3_u32 v238, s37, v174, v171
	s_waitcnt vmcnt(6)
	ds_write_b128 v238, v[116:119]
	ds_read_b128 v[242:245], v198 offset:11520
	s_waitcnt lgkmcnt(4)
	v_mfma_f32_16x16x32_bf16 v[76:79], v[178:181], v[250:253], v[76:79]
	v_mfma_f32_16x16x32_bf16 v[72:75], v[182:185], v[250:253], v[72:75]
	v_lshl_add_u64 v[116:117], s[38:39], 0, v[164:165]
	s_nop 0
	global_load_dwordx4 v[116:119], v[116:117], off offset:256
	v_mfma_f32_16x16x32_bf16 v[68:71], v[186:189], v[250:253], v[68:71]
	v_mfma_f32_16x16x32_bf16 v[64:67], v[190:193], v[250:253], v[64:67]
	ds_read_b128 v[246:249], v198 offset:13824
	s_waitcnt lgkmcnt(3)
	v_mfma_f32_16x16x32_bf16 v[60:63], v[178:181], v[194:197], v[60:63]
	v_mfma_f32_16x16x32_bf16 v[56:59], v[182:185], v[194:197], v[56:59]
	v_mfma_f32_16x16x32_bf16 v[52:55], v[186:189], v[194:197], v[52:55]
	v_add3_u32 v239, s37, v175, v171
	s_waitcnt vmcnt(6)
	ds_write_b128 v239, v[120:123]
	v_mfma_f32_16x16x32_bf16 v[48:51], v[190:193], v[194:197], v[48:51]
	ds_read_b128 v[250:253], v198 offset:16128
	s_waitcnt lgkmcnt(3)
	v_mfma_f32_16x16x32_bf16 v[44:47], v[178:181], v[242:245], v[44:47]
	v_lshl_add_u64 v[120:121], s[38:39], 0, v[166:167]
	s_nop 0
	global_load_dwordx4 v[120:123], v[120:121], off offset:256
	v_mfma_f32_16x16x32_bf16 v[40:43], v[182:185], v[242:245], v[40:43]
	v_mfma_f32_16x16x32_bf16 v[36:39], v[186:189], v[242:245], v[36:39]
	v_mfma_f32_16x16x32_bf16 v[32:35], v[190:193], v[242:245], v[32:35]
	ds_read_b128 v[194:197], v198 offset:64
	s_waitcnt lgkmcnt(3)
	v_mfma_f32_16x16x32_bf16 v[28:31], v[178:181], v[246:249], v[28:31]
	v_add3_u32 v255, s37, v176, v171
	s_waitcnt vmcnt(6)
	ds_write_b128 v255, v[124:127]
	v_mfma_f32_16x16x32_bf16 v[24:27], v[182:185], v[246:249], v[24:27]
	v_mfma_f32_16x16x32_bf16 v[20:23], v[186:189], v[246:249], v[20:23]
	v_lshl_add_u64 v[124:125], s[38:39], 0, v[168:169]
	s_nop 0
	global_load_dwordx4 v[124:127], v[124:125], off offset:256
	v_mfma_f32_16x16x32_bf16 v[16:19], v[190:193], v[246:249], v[16:19]
	ds_read_b128 v[242:245], v198 offset:2368
	s_waitcnt lgkmcnt(3)
	v_mfma_f32_16x16x32_bf16 v[12:15], v[178:181], v[250:253], v[12:15]
	ds_read_b128 v[178:181], v199 offset:36928
	v_mfma_f32_16x16x32_bf16 v[8:11], v[182:185], v[250:253], v[8:11]
	ds_read_b128 v[182:185], v199 offset:39232
	v_mfma_f32_16x16x32_bf16 v[4:7], v[186:189], v[250:253], v[4:7]
	ds_read_b128 v[186:189], v199 offset:41536
	v_mfma_f32_16x16x32_bf16 v[0:3], v[190:193], v[250:253], v[0:3]
	ds_read_b128 v[190:193], v199 offset:43840
	ds_write_b128 v254, v[128:131] offset:36864
	ds_read_b128 v[246:249], v198 offset:4672
	s_waitcnt lgkmcnt(5)
; DI f32x4 mfma16(bf16x8 a, bf16x8 b, f32x4 c) { return __builtin_amdgcn_mfma_f32_16x16x32_bf16(a, b, c, 0, 0, 0); }
; template <int MI, int NJ, bool SWAP, class AP, class BP>
; DI void gemm_main(f32x4 (&acc)[MI][NJ], const AP& ap, int a_kstep, const BP& bp, int b_kstep, int nk, bf16_t* smem) {
;     ...
;   auto gload = [&](int kt) {
;     const bf16_t* ab = ap.base + (size_t)kt * a_kstep; const bf16_t* bb = bp.base + (size_t)kt * b_kstep;
; #pragma unroll
;     for (int i = 0; i < CA; ++i) ra[i] = *(const u32x4*)(ab + pa[i]);
; #pragma unroll
;     for (int i = 0; i < CB; ++i) rb[i] = *(const u32x4*)(bb + pb[i]);
;   };
;   auto sstore = [&](int buf) {
;     bf16_t* As = smem + buf * L::STAGE; bf16_t* Bs = As + L::A_ELEMS;
; #pragma unroll
;     for (int i = 0; i < CA; ++i) { const int c = tid + NTHR * i; *(u32x4*)(As + (c >> 3) * LDT + (c & 7) * 8) = oka[i] ? ra[i] : (u32x4){0u, 0u, 0u, 0u}; }
; #pragma unroll
;     for (int i = 0; i < CB; ++i) { const int c = tid + NTHR * i; *(u32x4*)(Bs + (c >> 3) * LDT + (c & 7) * 8) = rb[i]; }
;     ...
;   for (int kt = 0; kt < nk; ++kt) {
;     const int buf = kt & 1;
;     sstore(buf ^ 1);
;     gload(kt + 2 < nk ? kt + 2 : nk - 1);
;     __builtin_amdgcn_sched_barrier(0);
;     const bf16_t* As = smem + buf * L::STAGE + (wm * 16 * MI + l15) * LDT + quad * 8;
;     const bf16_t* Bs = smem + buf * L::STAGE + L::A_ELEMS + (wn * 16 * NJ + l15) * LDT + quad * 8;
; #pragma unroll
;     for (int ks = 0; ks < 2; ++ks) {
;       if (MI * NJ >= 32 && ks == 1) asm volatile("" ::: "memory");
;       bf16x8 b[NJ];
; #pragma unroll
;       for (int j = 0; j < NJ; ++j) b[j] = *(const bf16x8*)(Bs + j * 16 * LDT + ks * 32);
; #pragma unroll
;       for (int i = 0; i < MI; ++i) {
;         const bf16x8 a = *(const bf16x8*)(As + i * 16 * LDT + ks * 32);
; #pragma unroll
;         for (int j = 0; j < NJ; ++j) acc[i][j] = SWAP ? mfma16(b[j], a, acc[i][j]) : mfma16(a, b[j], acc[i][j]);
;       }
;     }
;     __syncthreads();
;   }
	v_mfma_f32_16x16x32_bf16 v[156:159], v[178:181], v[194:197], v[156:159]
	s_waitcnt lgkmcnt(4)
	v_mfma_f32_16x16x32_bf16 v[152:155], v[182:185], v[194:197], v[152:155]
	s_add_u32 s38, s2, s99
	s_addc_u32 s39, s3, 0
	v_lshl_add_u64 v[128:129], s[38:39], 0, v[162:163]
	s_nop 0
	global_load_dwordx4 v[128:131], v[128:129], off offset:256
	s_waitcnt lgkmcnt(3)
	v_mfma_f32_16x16x32_bf16 v[148:151], v[186:189], v[194:197], v[148:151]
	s_waitcnt lgkmcnt(2)
	v_mfma_f32_16x16x32_bf16 v[144:147], v[190:193], v[194:197], v[144:147]
	ds_read_b128 v[250:253], v198 offset:6976
	v_mfma_f32_16x16x32_bf16 v[108:111], v[178:181], v[242:245], v[108:111]
	v_mfma_f32_16x16x32_bf16 v[104:107], v[182:185], v[242:245], v[104:107]
	s_waitcnt vmcnt(7)
	ds_write_b128 v238, v[132:135] offset:36864
	v_mfma_f32_16x16x32_bf16 v[100:103], v[186:189], v[242:245], v[100:103]
	v_mfma_f32_16x16x32_bf16 v[96:99], v[190:193], v[242:245], v[96:99]
	v_lshl_add_u64 v[132:133], s[38:39], 0, v[164:165]
	s_nop 0
	global_load_dwordx4 v[132:135], v[132:133], off offset:256
	ds_read_b128 v[194:197], v198 offset:9280
	s_waitcnt lgkmcnt(3)
	v_mfma_f32_16x16x32_bf16 v[92:95], v[178:181], v[246:249], v[92:95]
	v_mfma_f32_16x16x32_bf16 v[88:91], v[182:185], v[246:249], v[88:91]
	v_mfma_f32_16x16x32_bf16 v[84:87], v[186:189], v[246:249], v[84:87]
	v_mfma_f32_16x16x32_bf16 v[80:83], v[190:193], v[246:249], v[80:83]
	ds_read_b128 v[242:245], v198 offset:11584
	s_waitcnt lgkmcnt(3)
	v_mfma_f32_16x16x32_bf16 v[76:79], v[178:181], v[250:253], v[76:79]
	s_waitcnt vmcnt(7)
	ds_write_b128 v239, v[136:139] offset:36864
	v_mfma_f32_16x16x32_bf16 v[72:75], v[182:185], v[250:253], v[72:75]
	v_mfma_f32_16x16x32_bf16 v[68:71], v[186:189], v[250:253], v[68:71]
	v_lshl_add_u64 v[136:137], s[38:39], 0, v[166:167]
	s_nop 0
	global_load_dwordx4 v[136:139], v[136:137], off offset:256
	v_mfma_f32_16x16x32_bf16 v[64:67], v[190:193], v[250:253], v[64:67]
	ds_read_b128 v[246:249], v198 offset:13888
	s_waitcnt lgkmcnt(3)
	v_mfma_f32_16x16x32_bf16 v[60:63], v[178:181], v[194:197], v[60:63]
	v_mfma_f32_16x16x32_bf16 v[56:59], v[182:185], v[194:197], v[56:59]
	v_mfma_f32_16x16x32_bf16 v[52:55], v[186:189], v[194:197], v[52:55]
	v_mfma_f32_16x16x32_bf16 v[48:51], v[190:193], v[194:197], v[48:51]
	s_waitcnt vmcnt(7)
	ds_write_b128 v255, v[140:143] offset:36864
	ds_read_b128 v[250:253], v198 offset:16192
	s_waitcnt lgkmcnt(4)
	v_mfma_f32_16x16x32_bf16 v[44:47], v[178:181], v[242:245], v[44:47]
	v_mfma_f32_16x16x32_bf16 v[40:43], v[182:185], v[242:245], v[40:43]
	v_lshl_add_u64 v[140:141], s[38:39], 0, v[168:169]
	s_nop 0
	global_load_dwordx4 v[140:143], v[140:141], off offset:256
	v_mfma_f32_16x16x32_bf16 v[36:39], v[186:189], v[242:245], v[36:39]
	v_mfma_f32_16x16x32_bf16 v[32:35], v[190:193], v[242:245], v[32:35]
	s_add_i32 s8, s8, 1
	s_and_b32 s98, s8, 1
	s_mul_i32 s98, s98, 0x12000
	v_add3_u32 v198, s98, v172, v177
	v_add3_u32 v199, s98, v160, v177
	s_cmp_lg_u32 s8, 6
	s_waitcnt lgkmcnt(0)
	s_barrier
	s_cbranch_scc0 .Lgm10_exit
	ds_read_b128 v[194:197], v198
	ds_read_b128 v[242:245], v198 offset:2304
	v_mfma_f32_16x16x32_bf16 v[28:31], v[178:181], v[246:249], v[28:31]
	v_mfma_f32_16x16x32_bf16 v[12:15], v[178:181], v[250:253], v[12:15]
	ds_read_b128 v[178:181], v199 offset:36864
	v_mfma_f32_16x16x32_bf16 v[24:27], v[182:185], v[246:249], v[24:27]
	v_mfma_f32_16x16x32_bf16 v[8:11], v[182:185], v[250:253], v[8:11]
	ds_read_b128 v[182:185], v199 offset:39168
	v_mfma_f32_16x16x32_bf16 v[20:23], v[186:189], v[246:249], v[20:23]
	v_mfma_f32_16x16x32_bf16 v[4:7], v[186:189], v[250:253], v[4:7]
	ds_read_b128 v[186:189], v199 offset:41472
	v_mfma_f32_16x16x32_bf16 v[16:19], v[190:193], v[246:249], v[16:19]
	v_mfma_f32_16x16x32_bf16 v[0:3], v[190:193], v[250:253], v[0:3]
	ds_read_b128 v[190:193], v199 offset:43776
	s_branch .Lgm10_main

; DI f32x4 mfma16(bf16x8 a, bf16x8 b, f32x4 c) { return __builtin_amdgcn_mfma_f32_16x16x32_bf16(a, b, c, 0, 0, 0); }
; template <int MI, int NJ, bool SWAP, class AP, class BP>
; DI void gemm_main(f32x4 (&acc)[MI][NJ], const AP& ap, int a_kstep, const BP& bp, int b_kstep, int nk, bf16_t* smem) {
;     ...
;   auto gload = [&](int kt) {
;     const bf16_t* ab = ap.base + (size_t)kt * a_kstep; const bf16_t* bb = bp.base + (size_t)kt * b_kstep;
; #pragma unroll
;     for (int i = 0; i < CA; ++i) ra[i] = *(const u32x4*)(ab + pa[i]);
; #pragma unroll
;     for (int i = 0; i < CB; ++i) rb[i] = *(const u32x4*)(bb + pb[i]);
;   };
;   auto sstore = [&](int buf) {
;     bf16_t* As = smem + buf * L::STAGE; bf16_t* Bs = As + L::A_ELEMS;
; #pragma unroll
;     for (int i = 0; i < CA; ++i) { const int c = tid + NTHR * i; *(u32x4*)(As + (c >> 3) * LDT + (c & 7) * 8) = oka[i] ? ra[i] : (u32x4){0u, 0u, 0u, 0u}; }
; #pragma unroll
;     for (int i = 0; i < CB; ++i) { const int c = tid + NTHR * i; *(u32x4*)(Bs + (c >> 3) * LDT + (c & 7) * 8) = rb[i]; }
;   };
;   gload(0); sstore(0); gload(nk > 1 ? 1 : 0); __syncthreads();
; #pragma unroll 1
;   for (int kt = 0; kt < nk; ++kt) {
;     const int buf = kt & 1;
;     sstore(buf ^ 1);
;     gload(kt + 2 < nk ? kt + 2 : nk - 1);
;     __builtin_amdgcn_sched_barrier(0);
;     const bf16_t* As = smem + buf * L::STAGE + (wm * 16 * MI + l15) * LDT + quad * 8;
;     const bf16_t* Bs = smem + buf * L::STAGE + L::A_ELEMS + (wn * 16 * NJ + l15) * LDT + quad * 8;
; #pragma unroll
;     for (int ks = 0; ks < 2; ++ks) {
;       if (MI * NJ >= 32 && ks == 1) asm volatile("" ::: "memory");
;       bf16x8 b[NJ];
; #pragma unroll
;       for (int j = 0; j < NJ; ++j) b[j] = *(const bf16x8*)(Bs + j * 16 * LDT + ks * 32);
; #pragma unroll
;       for (int i = 0; i < MI; ++i) {
;         const bf16x8 a = *(const bf16x8*)(As + i * 16 * LDT + ks * 32);
; #pragma unroll
;         for (int j = 0; j < NJ; ++j) acc[i][j] = SWAP ? mfma16(b[j], a, acc[i][j]) : mfma16(a, b[j], acc[i][j]);
;       }
;     }
;     __syncthreads();
;   }
.Lgm13_main:
	ds_read_b128 v[242:245], v177 offset:4608
	s_waitcnt lgkmcnt(4)
	v_mfma_f32_16x16x32_bf16 v[156:159], v[178:181], v[194:197], v[156:159]
	s_waitcnt lgkmcnt(3)
	v_mfma_f32_16x16x32_bf16 v[152:155], v[182:185], v[194:197], v[152:155]
	s_waitcnt lgkmcnt(2)
	v_mfma_f32_16x16x32_bf16 v[148:151], v[186:189], v[194:197], v[148:151]
	s_waitcnt lgkmcnt(1)
	v_mfma_f32_16x16x32_bf16 v[144:147], v[190:193], v[194:197], v[144:147]
	ds_read_b128 v[246:249], v177 offset:6912
	v_mfma_f32_16x16x32_bf16 v[108:111], v[178:181], v[198:201], v[108:111]
	v_mfma_f32_16x16x32_bf16 v[104:107], v[182:185], v[198:201], v[104:107]
	s_and_b32 s15, s1, 1
	s_min_u32 s16, s1, 13
	s_xor_b32 s17, s15, 1
	s_mul_i32 s17, s17, 0x12000
	v_add3_u32 v250, s17, v172, v170
	s_waitcnt vmcnt(7)
	ds_write_b128 v250, v[112:115]
	v_mfma_f32_16x16x32_bf16 v[100:103], v[186:189], v[198:201], v[100:103]
	v_mfma_f32_16x16x32_bf16 v[96:99], v[190:193], v[198:201], v[96:99]
	s_lshl_b32 s26, s16, 7
	s_add_u32 s16, s2, s26
	v_add3_u32 v251, s17, v174, v170
	v_add3_u32 v252, s17, v175, v170
	v_add3_u32 v253, s17, v176, v170
	s_addc_u32 s17, s3, 0
	v_lshl_add_u64 v[112:113], s[16:17], 0, v[162:163]
	s_nop 0
	global_load_dwordx4 v[112:115], v[112:113], off offset:256
	ds_read_b128 v[194:197], v177 offset:9216
	s_waitcnt lgkmcnt(3)
	v_mfma_f32_16x16x32_bf16 v[92:95], v[178:181], v[242:245], v[92:95]
	v_mfma_f32_16x16x32_bf16 v[88:91], v[182:185], v[242:245], v[88:91]
	v_mfma_f32_16x16x32_bf16 v[84:87], v[186:189], v[242:245], v[84:87]
	v_mfma_f32_16x16x32_bf16 v[80:83], v[190:193], v[242:245], v[80:83]
	s_waitcnt vmcnt(7)
	ds_write_b128 v251, v[116:119]
	ds_read_b128 v[198:201], v177 offset:11520
	s_waitcnt lgkmcnt(4)
	v_mfma_f32_16x16x32_bf16 v[76:79], v[178:181], v[246:249], v[76:79]
	v_mfma_f32_16x16x32_bf16 v[72:75], v[182:185], v[246:249], v[72:75]
	v_lshl_add_u64 v[116:117], s[16:17], 0, v[164:165]
	s_nop 0
	global_load_dwordx4 v[116:119], v[116:117], off offset:256
	v_mfma_f32_16x16x32_bf16 v[68:71], v[186:189], v[246:249], v[68:71]
	v_mfma_f32_16x16x32_bf16 v[64:67], v[190:193], v[246:249], v[64:67]
	ds_read_b128 v[242:245], v177 offset:13824
	s_waitcnt lgkmcnt(3)
	v_mfma_f32_16x16x32_bf16 v[60:63], v[178:181], v[194:197], v[60:63]
	v_mfma_f32_16x16x32_bf16 v[56:59], v[182:185], v[194:197], v[56:59]
	v_mfma_f32_16x16x32_bf16 v[52:55], v[186:189], v[194:197], v[52:55]
	s_waitcnt vmcnt(7)
	ds_write_b128 v252, v[120:123]
	v_mfma_f32_16x16x32_bf16 v[48:51], v[190:193], v[194:197], v[48:51]
	ds_read_b128 v[246:249], v177 offset:16128
	s_waitcnt lgkmcnt(3)
	v_mfma_f32_16x16x32_bf16 v[44:47], v[178:181], v[198:201], v[44:47]
	v_lshl_add_u64 v[120:121], s[16:17], 0, v[166:167]
	s_nop 0
	global_load_dwordx4 v[120:123], v[120:121], off offset:256
	v_mfma_f32_16x16x32_bf16 v[40:43], v[182:185], v[198:201], v[40:43]
	v_mfma_f32_16x16x32_bf16 v[36:39], v[186:189], v[198:201], v[36:39]
	v_mfma_f32_16x16x32_bf16 v[32:35], v[190:193], v[198:201], v[32:35]
	ds_read_b128 v[194:197], v177 offset:64
	s_waitcnt lgkmcnt(3)
	v_mfma_f32_16x16x32_bf16 v[28:31], v[178:181], v[242:245], v[28:31]
	s_waitcnt vmcnt(7)
	ds_write_b128 v253, v[124:127]
	v_mfma_f32_16x16x32_bf16 v[24:27], v[182:185], v[242:245], v[24:27]
	v_mfma_f32_16x16x32_bf16 v[20:23], v[186:189], v[242:245], v[20:23]
	v_lshl_add_u64 v[124:125], s[16:17], 0, v[168:169]
	s_nop 0
	global_load_dwordx4 v[124:127], v[124:125], off offset:256
	v_mfma_f32_16x16x32_bf16 v[16:19], v[190:193], v[242:245], v[16:19]
	ds_read_b128 v[198:201], v177 offset:2368
	s_waitcnt lgkmcnt(3)
	v_mfma_f32_16x16x32_bf16 v[8:11], v[178:181], v[246:249], v[8:11]
	ds_read_b128 v[178:181], v202 offset:36928
	v_mfma_f32_16x16x32_bf16 v[4:7], v[182:185], v[246:249], v[4:7]
	ds_read_b128 v[182:185], v202 offset:39232
	v_mfma_f32_16x16x32_bf16 v[0:3], v[186:189], v[246:249], v[0:3]
	ds_read_b128 v[186:189], v202 offset:41536
	v_mfma_f32_16x16x32_bf16 v[12:15], v[190:193], v[246:249], v[12:15]
	ds_read_b128 v[190:193], v202 offset:43840
	s_waitcnt vmcnt(7)
; DI f32x4 mfma16(bf16x8 a, bf16x8 b, f32x4 c) { return __builtin_amdgcn_mfma_f32_16x16x32_bf16(a, b, c, 0, 0, 0); }
; template <int MI, int NJ, bool SWAP, class AP, class BP>
; DI void gemm_main(f32x4 (&acc)[MI][NJ], const AP& ap, int a_kstep, const BP& bp, int b_kstep, int nk, bf16_t* smem) {
;     ...
;   auto gload = [&](int kt) {
;     const bf16_t* ab = ap.base + (size_t)kt * a_kstep; const bf16_t* bb = bp.base + (size_t)kt * b_kstep;
; #pragma unroll
;     for (int i = 0; i < CA; ++i) ra[i] = *(const u32x4*)(ab + pa[i]);
; #pragma unroll
;     for (int i = 0; i < CB; ++i) rb[i] = *(const u32x4*)(bb + pb[i]);
;   };
;   auto sstore = [&](int buf) {
;     bf16_t* As = smem + buf * L::STAGE; bf16_t* Bs = As + L::A_ELEMS;
; #pragma unroll
;     for (int i = 0; i < CA; ++i) { const int c = tid + NTHR * i; *(u32x4*)(As + (c >> 3) * LDT + (c & 7) * 8) = oka[i] ? ra[i] : (u32x4){0u, 0u, 0u, 0u}; }
; #pragma unroll
;     for (int i = 0; i < CB; ++i) { const int c = tid + NTHR * i; *(u32x4*)(Bs + (c >> 3) * LDT + (c & 7) * 8) = rb[i]; }
;   };
;   gload(0); sstore(0); gload(nk > 1 ? 1 : 0); __syncthreads();
; #pragma unroll 1
;   for (int kt = 0; kt < nk; ++kt) {
;     const int buf = kt & 1;
;     sstore(buf ^ 1);
;     gload(kt + 2 < nk ? kt + 2 : nk - 1);
;     __builtin_amdgcn_sched_barrier(0);
;     const bf16_t* As = smem + buf * L::STAGE + (wm * 16 * MI + l15) * LDT + quad * 8;
;     const bf16_t* Bs = smem + buf * L::STAGE + L::A_ELEMS + (wn * 16 * NJ + l15) * LDT + quad * 8;
; #pragma unroll
;     for (int ks = 0; ks < 2; ++ks) {
;       if (MI * NJ >= 32 && ks == 1) asm volatile("" ::: "memory");
;       bf16x8 b[NJ];
; #pragma unroll
;       for (int j = 0; j < NJ; ++j) b[j] = *(const bf16x8*)(Bs + j * 16 * LDT + ks * 32);
; #pragma unroll
;       for (int i = 0; i < MI; ++i) {
;         const bf16x8 a = *(const bf16x8*)(As + i * 16 * LDT + ks * 32);
; #pragma unroll
;         for (int j = 0; j < NJ; ++j) acc[i][j] = SWAP ? mfma16(b[j], a, acc[i][j]) : mfma16(a, b[j], acc[i][j]);
;       }
;     }
;     __syncthreads();
;   }
	ds_write_b128 v250, v[128:131] offset:36864
	ds_read_b128 v[242:245], v177 offset:4672
	s_waitcnt lgkmcnt(5)
	v_mfma_f32_16x16x32_bf16 v[156:159], v[178:181], v[194:197], v[156:159]
	s_waitcnt lgkmcnt(4)
	v_mfma_f32_16x16x32_bf16 v[152:155], v[182:185], v[194:197], v[152:155]
	s_add_u32 s16, s12, s26
	s_addc_u32 s17, s13, 0
	v_lshl_add_u64 v[128:129], s[16:17], 0, v[162:163]
	s_nop 0
	global_load_dwordx4 v[128:131], v[128:129], off offset:256
	s_waitcnt lgkmcnt(3)
	v_mfma_f32_16x16x32_bf16 v[148:151], v[186:189], v[194:197], v[148:151]
	s_waitcnt lgkmcnt(2)
	v_mfma_f32_16x16x32_bf16 v[144:147], v[190:193], v[194:197], v[144:147]
	ds_read_b128 v[246:249], v177 offset:6976
	v_mfma_f32_16x16x32_bf16 v[108:111], v[178:181], v[198:201], v[108:111]
	v_mfma_f32_16x16x32_bf16 v[104:107], v[182:185], v[198:201], v[104:107]
	s_waitcnt vmcnt(7)
	ds_write_b128 v251, v[132:135] offset:36864
	v_mfma_f32_16x16x32_bf16 v[100:103], v[186:189], v[198:201], v[100:103]
	v_mfma_f32_16x16x32_bf16 v[96:99], v[190:193], v[198:201], v[96:99]
	v_lshl_add_u64 v[132:133], s[16:17], 0, v[164:165]
	s_nop 0
	global_load_dwordx4 v[132:135], v[132:133], off offset:256
	ds_read_b128 v[194:197], v177 offset:9280
	s_waitcnt lgkmcnt(3)
	v_mfma_f32_16x16x32_bf16 v[92:95], v[178:181], v[242:245], v[92:95]
	v_mfma_f32_16x16x32_bf16 v[88:91], v[182:185], v[242:245], v[88:91]
	v_mfma_f32_16x16x32_bf16 v[84:87], v[186:189], v[242:245], v[84:87]
	v_mfma_f32_16x16x32_bf16 v[80:83], v[190:193], v[242:245], v[80:83]
	ds_read_b128 v[198:201], v177 offset:11584
	s_waitcnt lgkmcnt(3)
	v_mfma_f32_16x16x32_bf16 v[76:79], v[178:181], v[246:249], v[76:79]
	s_waitcnt vmcnt(7)
	ds_write_b128 v252, v[136:139] offset:36864
	v_mfma_f32_16x16x32_bf16 v[72:75], v[182:185], v[246:249], v[72:75]
	v_mfma_f32_16x16x32_bf16 v[68:71], v[186:189], v[246:249], v[68:71]
	v_lshl_add_u64 v[136:137], s[16:17], 0, v[166:167]
	s_nop 0
	global_load_dwordx4 v[136:139], v[136:137], off offset:256
	v_mfma_f32_16x16x32_bf16 v[64:67], v[190:193], v[246:249], v[64:67]
	ds_read_b128 v[242:245], v177 offset:13888
	s_waitcnt lgkmcnt(3)
	v_mfma_f32_16x16x32_bf16 v[60:63], v[178:181], v[194:197], v[60:63]
	v_mfma_f32_16x16x32_bf16 v[56:59], v[182:185], v[194:197], v[56:59]
	v_mfma_f32_16x16x32_bf16 v[52:55], v[186:189], v[194:197], v[52:55]
	v_mfma_f32_16x16x32_bf16 v[48:51], v[190:193], v[194:197], v[48:51]
	s_waitcnt vmcnt(7)
	ds_write_b128 v253, v[140:143] offset:36864
	ds_read_b128 v[246:249], v177 offset:16192
	s_waitcnt lgkmcnt(4)
	v_mfma_f32_16x16x32_bf16 v[44:47], v[178:181], v[198:201], v[44:47]
	v_mfma_f32_16x16x32_bf16 v[40:43], v[182:185], v[198:201], v[40:43]
	v_lshl_add_u64 v[140:141], s[16:17], 0, v[168:169]
	s_nop 0
	global_load_dwordx4 v[140:143], v[140:141], off offset:256
	v_mfma_f32_16x16x32_bf16 v[36:39], v[186:189], v[198:201], v[36:39]
	v_mfma_f32_16x16x32_bf16 v[32:35], v[190:193], v[198:201], v[32:35]
	s_add_i32 s1, s1, 1
	s_and_b32 s98, s1, 1
	s_mul_i32 s98, s98, 0x12000
	v_add3_u32 v202, s98, v160, v173
	v_add3_u32 v177, s98, v171, v173
	s_cmp_lg_u32 s1, 16
	s_waitcnt lgkmcnt(0)
	s_barrier
	s_cbranch_scc0 .Lgm13_exit
	ds_read_b128 v[194:197], v177
	ds_read_b128 v[198:201], v177 offset:2304
	v_mfma_f32_16x16x32_bf16 v[28:31], v[178:181], v[242:245], v[28:31]
	v_mfma_f32_16x16x32_bf16 v[8:11], v[178:181], v[246:249], v[8:11]
	ds_read_b128 v[178:181], v202 offset:36864
	v_mfma_f32_16x16x32_bf16 v[24:27], v[182:185], v[242:245], v[24:27]
	v_mfma_f32_16x16x32_bf16 v[4:7], v[182:185], v[246:249], v[4:7]
	ds_read_b128 v[182:185], v202 offset:39168
	v_mfma_f32_16x16x32_bf16 v[20:23], v[186:189], v[242:245], v[20:23]
	v_mfma_f32_16x16x32_bf16 v[0:3], v[186:189], v[246:249], v[0:3]
	ds_read_b128 v[186:189], v202 offset:41472
	v_mfma_f32_16x16x32_bf16 v[16:19], v[190:193], v[242:245], v[16:19]
	v_mfma_f32_16x16x32_bf16 v[12:15], v[190:193], v[246:249], v[12:15]
	ds_read_b128 v[190:193], v202 offset:43776
	s_branch .Lgm13_main

; DI f32x4 mfma16(bf16x8 a, bf16x8 b, f32x4 c) { return __builtin_amdgcn_mfma_f32_16x16x32_bf16(a, b, c, 0, 0, 0); }
; template <int MI, int NJ, bool SWAP, class AP, class BP>
; DI void gemm_main(f32x4 (&acc)[MI][NJ], const AP& ap, int a_kstep, const BP& bp, int b_kstep, int nk, bf16_t* smem) {
;     ...
;   auto gload = [&](int kt) {
;     const bf16_t* ab = ap.base + (size_t)kt * a_kstep; const bf16_t* bb = bp.base + (size_t)kt * b_kstep;
; #pragma unroll
;     for (int i = 0; i < CA; ++i) ra[i] = *(const u32x4*)(ab + pa[i]);
; #pragma unroll
;     for (int i = 0; i < CB; ++i) rb[i] = *(const u32x4*)(bb + pb[i]);
;   };
;   auto sstore = [&](int buf) {
;     bf16_t* As = smem + buf * L::STAGE; bf16_t* Bs = As + L::A_ELEMS;
; #pragma unroll
;     for (int i = 0; i < CA; ++i) { const int c = tid + NTHR * i; *(u32x4*)(As + (c >> 3) * LDT + (c & 7) * 8) = oka[i] ? ra[i] : (u32x4){0u, 0u, 0u, 0u}; }
; #pragma unroll
;     for (int i = 0; i < CB; ++i) { const int c = tid + NTHR * i; *(u32x4*)(Bs + (c >> 3) * LDT + (c & 7) * 8) = rb[i]; }
;   };
;   gload(0); sstore(0); gload(nk > 1 ? 1 : 0); __syncthreads();
; #pragma unroll 1
;   for (int kt = 0; kt < nk; ++kt) {
;     const int buf = kt & 1;
;     sstore(buf ^ 1);
;     gload(kt + 2 < nk ? kt + 2 : nk - 1);
;     __builtin_amdgcn_sched_barrier(0);
;     const bf16_t* As = smem + buf * L::STAGE + (wm * 16 * MI + l15) * LDT + quad * 8;
;     const bf16_t* Bs = smem + buf * L::STAGE + L::A_ELEMS + (wn * 16 * NJ + l15) * LDT + quad * 8;
; #pragma unroll
;     for (int ks = 0; ks < 2; ++ks) {
;       if (MI * NJ >= 32 && ks == 1) asm volatile("" ::: "memory");
;       bf16x8 b[NJ];
; #pragma unroll
;       for (int j = 0; j < NJ; ++j) b[j] = *(const bf16x8*)(Bs + j * 16 * LDT + ks * 32);
; #pragma unroll
;       for (int i = 0; i < MI; ++i) {
;         const bf16x8 a = *(const bf16x8*)(As + i * 16 * LDT + ks * 32);
; #pragma unroll
;         for (int j = 0; j < NJ; ++j) acc[i][j] = SWAP ? mfma16(b[j], a, acc[i][j]) : mfma16(a, b[j], acc[i][j]);
;       }
;     }
;     __syncthreads();
;   }
.Lgm14_main:
	ds_read_b128 v[242:245], v181 offset:4608
	s_waitcnt lgkmcnt(4)
	v_mfma_f32_16x16x32_bf16 v[156:159], v[182:185], v[198:201], v[156:159]
	s_waitcnt lgkmcnt(3)
	v_mfma_f32_16x16x32_bf16 v[152:155], v[186:189], v[198:201], v[152:155]
	s_waitcnt lgkmcnt(2)
	v_mfma_f32_16x16x32_bf16 v[148:151], v[190:193], v[198:201], v[148:151]
	s_waitcnt lgkmcnt(1)
	v_mfma_f32_16x16x32_bf16 v[144:147], v[194:197], v[198:201], v[144:147]
	ds_read_b128 v[246:249], v181 offset:6912
	v_mfma_f32_16x16x32_bf16 v[108:111], v[182:185], v[202:205], v[108:111]
	v_mfma_f32_16x16x32_bf16 v[104:107], v[186:189], v[202:205], v[104:107]
	s_waitcnt vmcnt(7)
	v_cndmask_b32_e32 v143, 0, v143, vcc
	v_cndmask_b32_e32 v142, 0, v142, vcc
	v_cndmask_b32_e32 v141, 0, v141, vcc
	v_cndmask_b32_e32 v140, 0, v140, vcc
	s_and_b32 s46, s43, 1
	s_min_u32 s44, s43, 13
	s_xor_b32 s45, s46, 1
	s_mul_i32 s45, s45, 0x12000
	v_add3_u32 v250, s45, v172, v169
	ds_write_b128 v250, v[140:143]
	v_mfma_f32_16x16x32_bf16 v[100:103], v[190:193], v[202:205], v[100:103]
	v_mfma_f32_16x16x32_bf16 v[96:99], v[194:197], v[202:205], v[96:99]
	s_lshl_b32 s47, s44, 7
	s_add_u32 s44, s18, s47
	v_add3_u32 v251, s45, v173, v169
	v_add3_u32 v252, s45, v174, v169
	v_add3_u32 v253, s45, v175, v169
	s_addc_u32 s45, s19, 0
	s_nop 0
	global_load_dwordx4 v[140:143], v176, s[44:45] offset:256
	ds_read_b128 v[198:201], v181 offset:9216
	s_waitcnt lgkmcnt(3)
	v_mfma_f32_16x16x32_bf16 v[92:95], v[182:185], v[242:245], v[92:95]
	v_mfma_f32_16x16x32_bf16 v[88:91], v[186:189], v[242:245], v[88:91]
	v_mfma_f32_16x16x32_bf16 v[84:87], v[190:193], v[242:245], v[84:87]
	v_mfma_f32_16x16x32_bf16 v[80:83], v[194:197], v[242:245], v[80:83]
	s_waitcnt vmcnt(7)
	v_cndmask_b32_e64 v131, 0, v131, s[0:1]
	v_cndmask_b32_e64 v130, 0, v130, s[0:1]
	v_cndmask_b32_e64 v129, 0, v129, s[0:1]
	v_cndmask_b32_e64 v128, 0, v128, s[0:1]
	ds_write_b128 v251, v[128:131]
	ds_read_b128 v[202:205], v181 offset:11520
	s_waitcnt lgkmcnt(4)
	v_mfma_f32_16x16x32_bf16 v[76:79], v[182:185], v[246:249], v[76:79]
	v_mfma_f32_16x16x32_bf16 v[72:75], v[186:189], v[246:249], v[72:75]
	s_nop 0
	global_load_dwordx4 v[128:131], v177, s[44:45] offset:256
	v_mfma_f32_16x16x32_bf16 v[68:71], v[190:193], v[246:249], v[68:71]
	v_mfma_f32_16x16x32_bf16 v[64:67], v[194:197], v[246:249], v[64:67]
	ds_read_b128 v[242:245], v181 offset:13824
	s_waitcnt lgkmcnt(3)
	v_mfma_f32_16x16x32_bf16 v[60:63], v[182:185], v[198:201], v[60:63]
	v_mfma_f32_16x16x32_bf16 v[56:59], v[186:189], v[198:201], v[56:59]
	v_mfma_f32_16x16x32_bf16 v[52:55], v[190:193], v[198:201], v[52:55]
	s_waitcnt vmcnt(7)
	v_cndmask_b32_e64 v115, 0, v115, s[2:3]
	v_cndmask_b32_e64 v114, 0, v114, s[2:3]
	v_cndmask_b32_e64 v113, 0, v113, s[2:3]
	v_cndmask_b32_e64 v112, 0, v112, s[2:3]
	ds_write_b128 v252, v[112:115]
	v_mfma_f32_16x16x32_bf16 v[48:51], v[194:197], v[198:201], v[48:51]
	ds_read_b128 v[246:249], v181 offset:16128
	s_waitcnt lgkmcnt(3)
	v_mfma_f32_16x16x32_bf16 v[44:47], v[182:185], v[202:205], v[44:47]
	s_nop 0
	global_load_dwordx4 v[112:115], v178, s[44:45] offset:256
	v_mfma_f32_16x16x32_bf16 v[40:43], v[186:189], v[202:205], v[40:43]
	v_mfma_f32_16x16x32_bf16 v[36:39], v[190:193], v[202:205], v[36:39]
	v_mfma_f32_16x16x32_bf16 v[32:35], v[194:197], v[202:205], v[32:35]
	ds_read_b128 v[198:201], v181 offset:64
	s_waitcnt lgkmcnt(3)
	v_mfma_f32_16x16x32_bf16 v[28:31], v[182:185], v[242:245], v[28:31]
	s_waitcnt vmcnt(7)
	v_cndmask_b32_e64 v135, 0, v135, s[4:5]
	v_cndmask_b32_e64 v134, 0, v134, s[4:5]
	v_cndmask_b32_e64 v133, 0, v133, s[4:5]
	v_cndmask_b32_e64 v132, 0, v132, s[4:5]
	ds_write_b128 v253, v[132:135]
	v_mfma_f32_16x16x32_bf16 v[24:27], v[186:189], v[242:245], v[24:27]
	v_mfma_f32_16x16x32_bf16 v[20:23], v[190:193], v[242:245], v[20:23]
	s_nop 0
	global_load_dwordx4 v[132:135], v179, s[44:45] offset:256
	v_mfma_f32_16x16x32_bf16 v[12:15], v[194:197], v[242:245], v[12:15]
	ds_read_b128 v[202:205], v181 offset:2368
	s_waitcnt lgkmcnt(3)
; DI f32x4 mfma16(bf16x8 a, bf16x8 b, f32x4 c) { return __builtin_amdgcn_mfma_f32_16x16x32_bf16(a, b, c, 0, 0, 0); }
; template <int MI, int NJ, bool SWAP, class AP, class BP>
; DI void gemm_main(f32x4 (&acc)[MI][NJ], const AP& ap, int a_kstep, const BP& bp, int b_kstep, int nk, bf16_t* smem) {
;     ...
;   auto gload = [&](int kt) {
;     const bf16_t* ab = ap.base + (size_t)kt * a_kstep; const bf16_t* bb = bp.base + (size_t)kt * b_kstep;
; #pragma unroll
;     for (int i = 0; i < CA; ++i) ra[i] = *(const u32x4*)(ab + pa[i]);
; #pragma unroll
;     for (int i = 0; i < CB; ++i) rb[i] = *(const u32x4*)(bb + pb[i]);
;   };
;   auto sstore = [&](int buf) {
;     bf16_t* As = smem + buf * L::STAGE; bf16_t* Bs = As + L::A_ELEMS;
; #pragma unroll
;     for (int i = 0; i < CA; ++i) { const int c = tid + NTHR * i; *(u32x4*)(As + (c >> 3) * LDT + (c & 7) * 8) = oka[i] ? ra[i] : (u32x4){0u, 0u, 0u, 0u}; }
; #pragma unroll
;     for (int i = 0; i < CB; ++i) { const int c = tid + NTHR * i; *(u32x4*)(Bs + (c >> 3) * LDT + (c & 7) * 8) = rb[i]; }
;   };
;   gload(0); sstore(0); gload(nk > 1 ? 1 : 0); __syncthreads();
; #pragma unroll 1
;   for (int kt = 0; kt < nk; ++kt) {
;     const int buf = kt & 1;
;     sstore(buf ^ 1);
;     gload(kt + 2 < nk ? kt + 2 : nk - 1);
;     __builtin_amdgcn_sched_barrier(0);
;     const bf16_t* As = smem + buf * L::STAGE + (wm * 16 * MI + l15) * LDT + quad * 8;
;     const bf16_t* Bs = smem + buf * L::STAGE + L::A_ELEMS + (wn * 16 * NJ + l15) * LDT + quad * 8;
; #pragma unroll
;     for (int ks = 0; ks < 2; ++ks) {
;       if (MI * NJ >= 32 && ks == 1) asm volatile("" ::: "memory");
;       bf16x8 b[NJ];
; #pragma unroll
;       for (int j = 0; j < NJ; ++j) b[j] = *(const bf16x8*)(Bs + j * 16 * LDT + ks * 32);
; #pragma unroll
;       for (int i = 0; i < MI; ++i) {
;         const bf16x8 a = *(const bf16x8*)(As + i * 16 * LDT + ks * 32);
; #pragma unroll
;         for (int j = 0; j < NJ; ++j) acc[i][j] = SWAP ? mfma16(b[j], a, acc[i][j]) : mfma16(a, b[j], acc[i][j]);
;       }
;     }
;     __syncthreads();
;   }
	v_mfma_f32_16x16x32_bf16 v[8:11], v[182:185], v[246:249], v[8:11]
	ds_read_b128 v[182:185], v206 offset:36928
	v_mfma_f32_16x16x32_bf16 v[4:7], v[186:189], v[246:249], v[4:7]
	ds_read_b128 v[186:189], v206 offset:39232
	v_mfma_f32_16x16x32_bf16 v[0:3], v[190:193], v[246:249], v[0:3]
	ds_read_b128 v[190:193], v206 offset:41536
	v_mfma_f32_16x16x32_bf16 v[16:19], v[194:197], v[246:249], v[16:19]
	ds_read_b128 v[194:197], v206 offset:43840
	s_waitcnt vmcnt(7)
	ds_write_b128 v250, v[116:119] offset:36864
	ds_read_b128 v[242:245], v181 offset:4672
	s_waitcnt lgkmcnt(5)
	v_mfma_f32_16x16x32_bf16 v[156:159], v[182:185], v[198:201], v[156:159]
	s_waitcnt lgkmcnt(4)
	v_mfma_f32_16x16x32_bf16 v[152:155], v[186:189], v[198:201], v[152:155]
	s_add_u32 s44, s20, s47
	s_addc_u32 s45, s21, 0
	v_lshl_add_u64 v[116:117], v[160:161], 1, s[44:45]
	s_nop 0
	global_load_dwordx4 v[116:119], v[116:117], off offset:256
	s_waitcnt lgkmcnt(3)
	v_mfma_f32_16x16x32_bf16 v[148:151], v[190:193], v[198:201], v[148:151]
	s_waitcnt lgkmcnt(2)
	v_mfma_f32_16x16x32_bf16 v[144:147], v[194:197], v[198:201], v[144:147]
	ds_read_b128 v[246:249], v181 offset:6976
	v_mfma_f32_16x16x32_bf16 v[108:111], v[182:185], v[202:205], v[108:111]
	v_mfma_f32_16x16x32_bf16 v[104:107], v[186:189], v[202:205], v[104:107]
	s_waitcnt vmcnt(7)
	ds_write_b128 v251, v[120:123] offset:36864
	v_mfma_f32_16x16x32_bf16 v[100:103], v[190:193], v[202:205], v[100:103]
	v_mfma_f32_16x16x32_bf16 v[96:99], v[194:197], v[202:205], v[96:99]
	v_lshl_add_u64 v[120:121], v[162:163], 1, s[44:45]
	s_nop 0
	global_load_dwordx4 v[120:123], v[120:121], off offset:256
	ds_read_b128 v[198:201], v181 offset:9280
	s_waitcnt lgkmcnt(3)
	v_mfma_f32_16x16x32_bf16 v[92:95], v[182:185], v[242:245], v[92:95]
	v_mfma_f32_16x16x32_bf16 v[88:91], v[186:189], v[242:245], v[88:91]
	v_mfma_f32_16x16x32_bf16 v[84:87], v[190:193], v[242:245], v[84:87]
	v_mfma_f32_16x16x32_bf16 v[80:83], v[194:197], v[242:245], v[80:83]
	ds_read_b128 v[202:205], v181 offset:11584
	s_waitcnt lgkmcnt(3)
	v_mfma_f32_16x16x32_bf16 v[76:79], v[182:185], v[246:249], v[76:79]
	s_waitcnt vmcnt(7)
	ds_write_b128 v252, v[124:127] offset:36864
	v_mfma_f32_16x16x32_bf16 v[72:75], v[186:189], v[246:249], v[72:75]
	v_mfma_f32_16x16x32_bf16 v[68:71], v[190:193], v[246:249], v[68:71]
	v_lshl_add_u64 v[124:125], v[164:165], 1, s[44:45]
	s_nop 0
	global_load_dwordx4 v[124:127], v[124:125], off offset:256
	v_mfma_f32_16x16x32_bf16 v[64:67], v[194:197], v[246:249], v[64:67]
	ds_read_b128 v[242:245], v181 offset:13888
	s_waitcnt lgkmcnt(3)
	v_mfma_f32_16x16x32_bf16 v[60:63], v[182:185], v[198:201], v[60:63]
	v_mfma_f32_16x16x32_bf16 v[56:59], v[186:189], v[198:201], v[56:59]
	v_mfma_f32_16x16x32_bf16 v[52:55], v[190:193], v[198:201], v[52:55]
	v_mfma_f32_16x16x32_bf16 v[48:51], v[194:197], v[198:201], v[48:51]
	s_waitcnt vmcnt(7)
	ds_write_b128 v253, v[136:139] offset:36864
	ds_read_b128 v[246:249], v181 offset:16192
	s_waitcnt lgkmcnt(4)
	v_mfma_f32_16x16x32_bf16 v[44:47], v[182:185], v[202:205], v[44:47]
	v_mfma_f32_16x16x32_bf16 v[40:43], v[186:189], v[202:205], v[40:43]
	v_lshl_add_u64 v[136:137], v[166:167], 1, s[44:45]
	s_nop 0
	global_load_dwordx4 v[136:139], v[136:137], off offset:256
	v_mfma_f32_16x16x32_bf16 v[36:39], v[190:193], v[202:205], v[36:39]
	v_mfma_f32_16x16x32_bf16 v[32:35], v[194:197], v[202:205], v[32:35]
	s_add_i32 s43, s43, 1
	s_and_b32 s98, s43, 1
	s_mul_i32 s98, s98, 0x12000
	v_add3_u32 v206, s98, v171, v180
	v_add3_u32 v181, s98, v170, v180
	s_cmp_lg_u32 s43, 16
	s_waitcnt lgkmcnt(0)
	s_barrier
	s_cbranch_scc0 .Lgm14_exit
	ds_read_b128 v[198:201], v181
	ds_read_b128 v[202:205], v181 offset:2304
	v_mfma_f32_16x16x32_bf16 v[28:31], v[182:185], v[242:245], v[28:31]
	v_mfma_f32_16x16x32_bf16 v[8:11], v[182:185], v[246:249], v[8:11]
	ds_read_b128 v[182:185], v206 offset:36864
	v_mfma_f32_16x16x32_bf16 v[24:27], v[186:189], v[242:245], v[24:27]
	v_mfma_f32_16x16x32_bf16 v[4:7], v[186:189], v[246:249], v[4:7]
	ds_read_b128 v[186:189], v206 offset:39168
	v_mfma_f32_16x16x32_bf16 v[20:23], v[190:193], v[242:245], v[20:23]
	v_mfma_f32_16x16x32_bf16 v[0:3], v[190:193], v[246:249], v[0:3]
	ds_read_b128 v[190:193], v206 offset:41472
	v_mfma_f32_16x16x32_bf16 v[12:15], v[194:197], v[242:245], v[12:15]
	v_mfma_f32_16x16x32_bf16 v[16:19], v[194:197], v[246:249], v[16:19]
	ds_read_b128 v[194:197], v206 offset:43776
	s_branch .Lgm14_main

; DI f32x4 mfma16(bf16x8 a, bf16x8 b, f32x4 c) { return __builtin_amdgcn_mfma_f32_16x16x32_bf16(a, b, c, 0, 0, 0); }
; template <int MI, int NJ, bool SWAP, class AP, class BP>
; DI void gemm_main(f32x4 (&acc)[MI][NJ], const AP& ap, int a_kstep, const BP& bp, int b_kstep, int nk, bf16_t* smem) {
;     ...
;   auto gload = [&](int kt) {
;     const bf16_t* ab = ap.base + (size_t)kt * a_kstep; const bf16_t* bb = bp.base + (size_t)kt * b_kstep;
; #pragma unroll
;     for (int i = 0; i < CA; ++i) ra[i] = *(const u32x4*)(ab + pa[i]);
; #pragma unroll
;     for (int i = 0; i < CB; ++i) rb[i] = *(const u32x4*)(bb + pb[i]);
;   };
;   auto sstore = [&](int buf) {
;     bf16_t* As = smem + buf * L::STAGE; bf16_t* Bs = As + L::A_ELEMS;
; #pragma unroll
;     for (int i = 0; i < CA; ++i) { const int c = tid + NTHR * i; *(u32x4*)(As + (c >> 3) * LDT + (c & 7) * 8) = oka[i] ? ra[i] : (u32x4){0u, 0u, 0u, 0u}; }
; #pragma unroll
;     for (int i = 0; i < CB; ++i) { const int c = tid + NTHR * i; *(u32x4*)(Bs + (c >> 3) * LDT + (c & 7) * 8) = rb[i]; }
;   };
;   gload(0); sstore(0); gload(nk > 1 ? 1 : 0); __syncthreads();
; #pragma unroll 1
;   for (int kt = 0; kt < nk; ++kt) {
;     const int buf = kt & 1;
;     sstore(buf ^ 1);
;     gload(kt + 2 < nk ? kt + 2 : nk - 1);
;     __builtin_amdgcn_sched_barrier(0);
;     const bf16_t* As = smem + buf * L::STAGE + (wm * 16 * MI + l15) * LDT + quad * 8;
;     const bf16_t* Bs = smem + buf * L::STAGE + L::A_ELEMS + (wn * 16 * NJ + l15) * LDT + quad * 8;
; #pragma unroll
;     for (int ks = 0; ks < 2; ++ks) {
;       if (MI * NJ >= 32 && ks == 1) asm volatile("" ::: "memory");
;       bf16x8 b[NJ];
; #pragma unroll
;       for (int j = 0; j < NJ; ++j) b[j] = *(const bf16x8*)(Bs + j * 16 * LDT + ks * 32);
; #pragma unroll
;       for (int i = 0; i < MI; ++i) {
;         const bf16x8 a = *(const bf16x8*)(As + i * 16 * LDT + ks * 32);
; #pragma unroll
;         for (int j = 0; j < NJ; ++j) acc[i][j] = SWAP ? mfma16(b[j], a, acc[i][j]) : mfma16(a, b[j], acc[i][j]);
;       }
;     }
;     __syncthreads();
;   }
.Lgm15_main:
	ds_read_b128 v[242:245], v177 offset:4608
	s_waitcnt lgkmcnt(4)
	v_mfma_f32_16x16x32_bf16 v[156:159], v[178:181], v[194:197], v[156:159]
	s_waitcnt lgkmcnt(3)
	v_mfma_f32_16x16x32_bf16 v[152:155], v[182:185], v[194:197], v[152:155]
	s_waitcnt lgkmcnt(2)
	v_mfma_f32_16x16x32_bf16 v[148:151], v[186:189], v[194:197], v[148:151]
	s_waitcnt lgkmcnt(1)
	v_mfma_f32_16x16x32_bf16 v[144:147], v[190:193], v[194:197], v[144:147]
	ds_read_b128 v[246:249], v177 offset:6912
	v_mfma_f32_16x16x32_bf16 v[108:111], v[178:181], v[198:201], v[108:111]
	v_mfma_f32_16x16x32_bf16 v[104:107], v[182:185], v[198:201], v[104:107]
	s_and_b32 s17, s16, 1
	s_min_u32 s18, s16, 41
	s_xor_b32 s19, s17, 1
	s_mul_i32 s19, s19, 0x12000
	v_add3_u32 v250, s19, v172, v170
	s_waitcnt vmcnt(7)
	ds_write_b128 v250, v[112:115]
	v_mfma_f32_16x16x32_bf16 v[100:103], v[186:189], v[198:201], v[100:103]
	v_mfma_f32_16x16x32_bf16 v[96:99], v[190:193], v[198:201], v[96:99]
	s_lshl_b32 s20, s18, 7
	s_add_u32 s18, s2, s20
	v_add3_u32 v251, s19, v173, v170
	v_add3_u32 v252, s19, v174, v170
	v_add3_u32 v253, s19, v175, v170
	s_addc_u32 s19, s3, 0
	v_lshl_add_u64 v[112:113], s[18:19], 0, v[162:163]
	s_nop 0
	global_load_dwordx4 v[112:115], v[112:113], off offset:256
	ds_read_b128 v[194:197], v177 offset:9216
	s_waitcnt lgkmcnt(3)
	v_mfma_f32_16x16x32_bf16 v[92:95], v[178:181], v[242:245], v[92:95]
	v_mfma_f32_16x16x32_bf16 v[88:91], v[182:185], v[242:245], v[88:91]
	v_mfma_f32_16x16x32_bf16 v[84:87], v[186:189], v[242:245], v[84:87]
	v_mfma_f32_16x16x32_bf16 v[80:83], v[190:193], v[242:245], v[80:83]
	s_waitcnt vmcnt(7)
	ds_write_b128 v251, v[116:119]
	ds_read_b128 v[198:201], v177 offset:11520
	s_waitcnt lgkmcnt(4)
	v_mfma_f32_16x16x32_bf16 v[76:79], v[178:181], v[246:249], v[76:79]
	v_mfma_f32_16x16x32_bf16 v[72:75], v[182:185], v[246:249], v[72:75]
	v_lshl_add_u64 v[116:117], s[18:19], 0, v[164:165]
	s_nop 0
	global_load_dwordx4 v[116:119], v[116:117], off offset:256
	v_mfma_f32_16x16x32_bf16 v[68:71], v[186:189], v[246:249], v[68:71]
	v_mfma_f32_16x16x32_bf16 v[64:67], v[190:193], v[246:249], v[64:67]
	ds_read_b128 v[242:245], v177 offset:13824
	s_waitcnt lgkmcnt(3)
	v_mfma_f32_16x16x32_bf16 v[60:63], v[178:181], v[194:197], v[60:63]
	v_mfma_f32_16x16x32_bf16 v[56:59], v[182:185], v[194:197], v[56:59]
	v_mfma_f32_16x16x32_bf16 v[52:55], v[186:189], v[194:197], v[52:55]
	s_waitcnt vmcnt(7)
	ds_write_b128 v252, v[120:123]
	v_mfma_f32_16x16x32_bf16 v[48:51], v[190:193], v[194:197], v[48:51]
	ds_read_b128 v[246:249], v177 offset:16128
	s_waitcnt lgkmcnt(3)
	v_mfma_f32_16x16x32_bf16 v[44:47], v[178:181], v[198:201], v[44:47]
	v_lshl_add_u64 v[120:121], s[18:19], 0, v[166:167]
	s_nop 0
	global_load_dwordx4 v[120:123], v[120:121], off offset:256
	v_mfma_f32_16x16x32_bf16 v[40:43], v[182:185], v[198:201], v[40:43]
	v_mfma_f32_16x16x32_bf16 v[36:39], v[186:189], v[198:201], v[36:39]
	v_mfma_f32_16x16x32_bf16 v[32:35], v[190:193], v[198:201], v[32:35]
	ds_read_b128 v[194:197], v177 offset:64
	s_waitcnt lgkmcnt(3)
	v_mfma_f32_16x16x32_bf16 v[28:31], v[178:181], v[242:245], v[28:31]
	s_waitcnt vmcnt(7)
	ds_write_b128 v253, v[124:127]
	v_mfma_f32_16x16x32_bf16 v[24:27], v[182:185], v[242:245], v[24:27]
	v_mfma_f32_16x16x32_bf16 v[20:23], v[186:189], v[242:245], v[20:23]
	v_lshl_add_u64 v[124:125], s[18:19], 0, v[168:169]
	s_nop 0
	global_load_dwordx4 v[124:127], v[124:125], off offset:256
	v_mfma_f32_16x16x32_bf16 v[16:19], v[190:193], v[242:245], v[16:19]
	ds_read_b128 v[198:201], v177 offset:2368
	s_waitcnt lgkmcnt(3)
	v_mfma_f32_16x16x32_bf16 v[8:11], v[178:181], v[246:249], v[8:11]
	ds_read_b128 v[178:181], v202 offset:36928
	v_mfma_f32_16x16x32_bf16 v[4:7], v[182:185], v[246:249], v[4:7]
	ds_read_b128 v[182:185], v202 offset:39232
	v_mfma_f32_16x16x32_bf16 v[0:3], v[186:189], v[246:249], v[0:3]
	ds_read_b128 v[186:189], v202 offset:41536
	v_mfma_f32_16x16x32_bf16 v[12:15], v[190:193], v[246:249], v[12:15]
	ds_read_b128 v[190:193], v202 offset:43840
	s_waitcnt vmcnt(7)
; DI f32x4 mfma16(bf16x8 a, bf16x8 b, f32x4 c) { return __builtin_amdgcn_mfma_f32_16x16x32_bf16(a, b, c, 0, 0, 0); }
; template <int MI, int NJ, bool SWAP, class AP, class BP>
; DI void gemm_main(f32x4 (&acc)[MI][NJ], const AP& ap, int a_kstep, const BP& bp, int b_kstep, int nk, bf16_t* smem) {
;     ...
;   auto gload = [&](int kt) {
;     const bf16_t* ab = ap.base + (size_t)kt * a_kstep; const bf16_t* bb = bp.base + (size_t)kt * b_kstep;
; #pragma unroll
;     for (int i = 0; i < CA; ++i) ra[i] = *(const u32x4*)(ab + pa[i]);
; #pragma unroll
;     for (int i = 0; i < CB; ++i) rb[i] = *(const u32x4*)(bb + pb[i]);
;   };
;   auto sstore = [&](int buf) {
;     bf16_t* As = smem + buf * L::STAGE; bf16_t* Bs = As + L::A_ELEMS;
; #pragma unroll
;     for (int i = 0; i < CA; ++i) { const int c = tid + NTHR * i; *(u32x4*)(As + (c >> 3) * LDT + (c & 7) * 8) = oka[i] ? ra[i] : (u32x4){0u, 0u, 0u, 0u}; }
; #pragma unroll
;     for (int i = 0; i < CB; ++i) { const int c = tid + NTHR * i; *(u32x4*)(Bs + (c >> 3) * LDT + (c & 7) * 8) = rb[i]; }
;   };
;   gload(0); sstore(0); gload(nk > 1 ? 1 : 0); __syncthreads();
; #pragma unroll 1
;   for (int kt = 0; kt < nk; ++kt) {
;     const int buf = kt & 1;
;     sstore(buf ^ 1);
;     gload(kt + 2 < nk ? kt + 2 : nk - 1);
;     __builtin_amdgcn_sched_barrier(0);
;     const bf16_t* As = smem + buf * L::STAGE + (wm * 16 * MI + l15) * LDT + quad * 8;
;     const bf16_t* Bs = smem + buf * L::STAGE + L::A_ELEMS + (wn * 16 * NJ + l15) * LDT + quad * 8;
; #pragma unroll
;     for (int ks = 0; ks < 2; ++ks) {
;       if (MI * NJ >= 32 && ks == 1) asm volatile("" ::: "memory");
;       bf16x8 b[NJ];
; #pragma unroll
;       for (int j = 0; j < NJ; ++j) b[j] = *(const bf16x8*)(Bs + j * 16 * LDT + ks * 32);
; #pragma unroll
;       for (int i = 0; i < MI; ++i) {
;         const bf16x8 a = *(const bf16x8*)(As + i * 16 * LDT + ks * 32);
; #pragma unroll
;         for (int j = 0; j < NJ; ++j) acc[i][j] = SWAP ? mfma16(b[j], a, acc[i][j]) : mfma16(a, b[j], acc[i][j]);
;       }
;     }
;     __syncthreads();
;   }
	ds_write_b128 v250, v[128:131] offset:36864
	ds_read_b128 v[242:245], v177 offset:4672
	s_waitcnt lgkmcnt(5)
	v_mfma_f32_16x16x32_bf16 v[156:159], v[178:181], v[194:197], v[156:159]
	s_waitcnt lgkmcnt(4)
	v_mfma_f32_16x16x32_bf16 v[152:155], v[182:185], v[194:197], v[152:155]
	s_add_u32 s18, s4, s20
	s_addc_u32 s19, s5, 0
	v_lshl_add_u64 v[128:129], s[18:19], 0, v[162:163]
	s_nop 0
	global_load_dwordx4 v[128:131], v[128:129], off offset:256
	s_waitcnt lgkmcnt(3)
	v_mfma_f32_16x16x32_bf16 v[148:151], v[186:189], v[194:197], v[148:151]
	s_waitcnt lgkmcnt(2)
	v_mfma_f32_16x16x32_bf16 v[144:147], v[190:193], v[194:197], v[144:147]
	ds_read_b128 v[246:249], v177 offset:6976
	v_mfma_f32_16x16x32_bf16 v[108:111], v[178:181], v[198:201], v[108:111]
	v_mfma_f32_16x16x32_bf16 v[104:107], v[182:185], v[198:201], v[104:107]
	s_waitcnt vmcnt(7)
	ds_write_b128 v251, v[132:135] offset:36864
	v_mfma_f32_16x16x32_bf16 v[100:103], v[186:189], v[198:201], v[100:103]
	v_mfma_f32_16x16x32_bf16 v[96:99], v[190:193], v[198:201], v[96:99]
	v_lshl_add_u64 v[132:133], s[18:19], 0, v[164:165]
	s_nop 0
	global_load_dwordx4 v[132:135], v[132:133], off offset:256
	ds_read_b128 v[194:197], v177 offset:9280
	s_waitcnt lgkmcnt(3)
	v_mfma_f32_16x16x32_bf16 v[92:95], v[178:181], v[242:245], v[92:95]
	v_mfma_f32_16x16x32_bf16 v[88:91], v[182:185], v[242:245], v[88:91]
	v_mfma_f32_16x16x32_bf16 v[84:87], v[186:189], v[242:245], v[84:87]
	v_mfma_f32_16x16x32_bf16 v[80:83], v[190:193], v[242:245], v[80:83]
	ds_read_b128 v[198:201], v177 offset:11584
	s_waitcnt lgkmcnt(3)
	v_mfma_f32_16x16x32_bf16 v[76:79], v[178:181], v[246:249], v[76:79]
	s_waitcnt vmcnt(7)
	ds_write_b128 v252, v[136:139] offset:36864
	v_mfma_f32_16x16x32_bf16 v[72:75], v[182:185], v[246:249], v[72:75]
	v_mfma_f32_16x16x32_bf16 v[68:71], v[186:189], v[246:249], v[68:71]
	v_lshl_add_u64 v[136:137], s[18:19], 0, v[166:167]
	s_nop 0
	global_load_dwordx4 v[136:139], v[136:137], off offset:256
	v_mfma_f32_16x16x32_bf16 v[64:67], v[190:193], v[246:249], v[64:67]
	ds_read_b128 v[242:245], v177 offset:13888
	s_waitcnt lgkmcnt(3)
	v_mfma_f32_16x16x32_bf16 v[60:63], v[178:181], v[194:197], v[60:63]
	v_mfma_f32_16x16x32_bf16 v[56:59], v[182:185], v[194:197], v[56:59]
	v_mfma_f32_16x16x32_bf16 v[52:55], v[186:189], v[194:197], v[52:55]
	v_mfma_f32_16x16x32_bf16 v[48:51], v[190:193], v[194:197], v[48:51]
	s_waitcnt vmcnt(7)
	ds_write_b128 v253, v[140:143] offset:36864
	ds_read_b128 v[246:249], v177 offset:16192
	s_waitcnt lgkmcnt(4)
	v_mfma_f32_16x16x32_bf16 v[44:47], v[178:181], v[198:201], v[44:47]
	v_mfma_f32_16x16x32_bf16 v[40:43], v[182:185], v[198:201], v[40:43]
	v_lshl_add_u64 v[140:141], s[18:19], 0, v[168:169]
	s_nop 0
	global_load_dwordx4 v[140:143], v[140:141], off offset:256
	v_mfma_f32_16x16x32_bf16 v[36:39], v[186:189], v[198:201], v[36:39]
	v_mfma_f32_16x16x32_bf16 v[32:35], v[190:193], v[198:201], v[32:35]
	s_add_i32 s16, s16, 1
	s_and_b32 s98, s16, 1
	s_mul_i32 s98, s98, 0x12000
	v_add3_u32 v202, s98, v160, v176
	v_add3_u32 v177, s98, v171, v176
	s_cmp_lg_u32 s16, 44
	s_waitcnt lgkmcnt(0)
	s_barrier
	s_cbranch_scc0 .Lgm15_exit
	ds_read_b128 v[194:197], v177
	ds_read_b128 v[198:201], v177 offset:2304
	v_mfma_f32_16x16x32_bf16 v[28:31], v[178:181], v[242:245], v[28:31]
	v_mfma_f32_16x16x32_bf16 v[8:11], v[178:181], v[246:249], v[8:11]
	ds_read_b128 v[178:181], v202 offset:36864
	v_mfma_f32_16x16x32_bf16 v[24:27], v[182:185], v[242:245], v[24:27]
	v_mfma_f32_16x16x32_bf16 v[4:7], v[182:185], v[246:249], v[4:7]
	ds_read_b128 v[182:185], v202 offset:39168
	v_mfma_f32_16x16x32_bf16 v[20:23], v[186:189], v[242:245], v[20:23]
	v_mfma_f32_16x16x32_bf16 v[0:3], v[186:189], v[246:249], v[0:3]
	ds_read_b128 v[186:189], v202 offset:41472
	v_mfma_f32_16x16x32_bf16 v[16:19], v[190:193], v[242:245], v[16:19]
	v_mfma_f32_16x16x32_bf16 v[12:15], v[190:193], v[246:249], v[12:15]
	ds_read_b128 v[190:193], v202 offset:43776
	s_branch .Lgm15_main
